# tile-head 64-bit VGPR adds as v_add_co/v_addc pairs (full-rate) + P4 group-norm wave sums in registers (DPP/permlane) on top of the shared/double-buffered scan
# speedup vs baseline: 1.0111x; 1.0006x over previous
.LBB0_180:
	s_nop 0
	v_mov_b32_e32 v0, s19
	v_mov_b32_e32 v16, v132
	ds_read_b64 v[128:129], v0
	s_and_b64 s[4:5], exec, s[28:29]
	v_lshlrev_b32_e32 v7, 4, v16
	v_and_b32_e32 v6, 32, v16
	v_lshrrev_b32_e32 v8, 1, v16
	v_bitop3_b32 v6, v7, v6, 48 bitop3:0x6c
	s_cselect_b32 s4, 0x8000, 0
	v_bfe_u32 v17, v16, 2, 4
	v_and_b32_e32 v18, 32, v8
	v_lshrrev_b32_e32 v19, 1, v6
	v_ashrrev_i32_e32 v20, 3, v16
	s_add_i32 s4, s66, s4
	v_or_b32_e32 v10, v19, v18
	v_and_or_b32 v6, v20, s48, v17
	s_ashr_i32 s5, s4, 31
	v_and_b32_e32 v9, 0xfffffc00, v7
	v_lshl_or_b32 v134, v6, 10, v10
	v_add_u32_e32 v6, 0x2000, v7
	v_add_u32_e32 v8, 0x4000, v7
	v_add_u32_e32 v7, 0x6000, v7
	s_lshl_b64 s[4:5], s[4:5], 11
	s_ashr_i32 s27, s26, 31
	v_ashrrev_i32_e32 v21, 7, v6
	v_ashrrev_i32_e32 v22, 7, v8
	v_ashrrev_i32_e32 v23, 7, v7
	s_waitcnt lgkmcnt(0)
	v_lshl_add_u64 v[0:1], v[128:129], 0, s[4:5]
	s_lshl_b64 s[4:5], s[26:27], 19
	v_and_or_b32 v6, v21, s48, v17
	v_and_or_b32 v8, v22, s48, v17
	v_and_or_b32 v7, v23, s48, v17
	v_add_u32_e32 v150, 0, v9
	v_lshl_add_u64 v[2:3], v[0:1], 0, s[8:9]
	v_lshl_add_u64 v[4:5], v[128:129], 0, s[4:5]
	v_lshl_or_b32 v6, v6, 10, v10
	v_lshl_or_b32 v8, v8, 10, v10
	v_lshl_or_b32 v10, v7, 10, v10
	v_add_u32_e32 v7, 0x8000, v150
	v_lshlrev_b64 v[12:13], 1, v[134:135]
	v_readfirstlane_b32 s4, v150
	v_add_co_u32_e32 v14, vcc, v2, v12
	v_addc_co_u32_e32 v15, vcc, v3, v13, vcc
	s_mov_b32 m0, s4
	v_readfirstlane_b32 s4, v7
	v_mov_b32_e32 v7, v135
	v_add_u32_e32 v9, 0x2000, v150
	global_load_lds_dwordx4 v[14:15], off
	v_add_co_u32_e32 v12, vcc, v4, v12
	v_addc_co_u32_e32 v13, vcc, v5, v13, vcc
	s_mov_b32 m0, s4
	v_lshlrev_b64 v[6:7], 1, v[6:7]
	v_readfirstlane_b32 s4, v9
	v_add_u32_e32 v9, 0xa000, v150
	global_load_lds_dwordx4 v[12:13], off
	v_add_co_u32_e32 v12, vcc, v2, v6
	v_addc_co_u32_e32 v13, vcc, v3, v7, vcc
	s_mov_b32 m0, s4
	v_readfirstlane_b32 s4, v9
	global_load_lds_dwordx4 v[12:13], off
	v_add_co_u32_e32 v6, vcc, v4, v6
	v_addc_co_u32_e32 v7, vcc, v5, v7, vcc
	s_mov_b32 m0, s4
	v_mov_b32_e32 v9, v135
	v_add_u32_e32 v11, 0x4000, v150
	global_load_lds_dwordx4 v[6:7], off
	v_lshlrev_b64 v[6:7], 1, v[8:9]
	v_readfirstlane_b32 s4, v11
	v_add_co_u32_e32 v8, vcc, v2, v6
	v_addc_co_u32_e32 v9, vcc, v3, v7, vcc
	s_mov_b32 m0, s4
	v_add_co_u32_e32 v6, vcc, v4, v6
	v_addc_co_u32_e32 v7, vcc, v5, v7, vcc
	global_load_lds_dwordx4 v[8:9], off
	v_add_u32_e32 v8, 0xc000, v150
	v_mov_b32_e32 v11, v135
	v_readfirstlane_b32 s4, v8
	s_mov_b32 m0, s4
	v_add_u32_e32 v8, 0x6000, v150
	global_load_lds_dwordx4 v[6:7], off
	v_lshlrev_b64 v[6:7], 1, v[10:11]
	v_readfirstlane_b32 s4, v8
	v_add_co_u32_e32 v2, vcc, v2, v6
	v_addc_co_u32_e32 v3, vcc, v3, v7, vcc
	s_mov_b32 m0, s4
	v_and_b32_e32 v24, 15, v16
	global_load_lds_dwordx4 v[2:3], off
	v_add_co_u32_e32 v2, vcc, v4, v6
	v_addc_co_u32_e32 v3, vcc, v5, v7, vcc
	v_add_u32_e32 v6, 0xe000, v150
	v_lshlrev_b32_e32 v10, 10, v17
	v_readfirstlane_b32 s4, v6
	s_mov_b32 m0, s4
	v_lshlrev_b32_e32 v6, 2, v16
	global_load_lds_dwordx4 v[2:3], off
	v_and_b32_e32 v2, 48, v16
	v_lshlrev_b32_e32 v3, 6, v24
	v_and_b32_e32 v6, 32, v6
	v_bitop3_b32 v151, v3, v6, v2 bitop3:0x36
	v_lshlrev_b32_e32 v3, 7, v16
	v_and_b32_e32 v152, 0x6000, v3
	v_lshlrev_b32_e32 v3, 6, v16
	v_and_b32_e32 v153, 0xffffc000, v3
	v_and_b32_e32 v3, 0x3c0, v3
	v_bitop3_b32 v154, v3, v6, v2 bitop3:0x36
	v_lshlrev_b32_e32 v2, 10, v23
	v_and_or_b32 v2, v2, s49, v19
	v_lshlrev_b32_e32 v6, 10, v22
	v_or3_b32 v134, v2, v10, v18
	v_and_or_b32 v6, v6, s49, v19
	v_lshlrev_b32_e32 v8, 10, v21
	v_lshlrev_b64 v[2:3], 1, v[134:135]
	v_or3_b32 v134, v6, v10, v18
	v_and_or_b32 v8, v8, s49, v19
	v_lshlrev_b32_e32 v11, 10, v20
	v_lshlrev_b64 v[6:7], 1, v[134:135]
	v_or3_b32 v134, v8, v10, v18
	v_and_or_b32 v11, v11, s49, v19
	s_nop 0
	v_lshl_add_u64 v[4:5], v[4:5], 0, s[10:11]
	v_lshlrev_b64 v[8:9], 1, v[134:135]
	v_or3_b32 v134, v11, v10, v18
	v_lshl_add_u64 v[0:1], v[0:1], 0, s[12:13]
	v_add_co_u32_e32 v138, vcc, v4, v8
	v_addc_co_u32_e32 v139, vcc, v5, v9, vcc
	v_lshlrev_b64 v[10:11], 1, v[134:135]
	v_add_co_u32_e32 v146, vcc, v0, v8
	v_addc_co_u32_e32 v147, vcc, v1, v9, vcc
	s_mov_b32 s6, 0
	v_add_co_u32_e32 v130, vcc, v4, v2
	v_addc_co_u32_e32 v131, vcc, v5, v3, vcc
	v_add_co_u32_e32 v136, vcc, v4, v6
	v_addc_co_u32_e32 v137, vcc, v5, v7, vcc
	v_add_co_u32_e32 v140, vcc, v4, v10
	v_addc_co_u32_e32 v141, vcc, v5, v11, vcc
	v_add_co_u32_e32 v142, vcc, v0, v2
	v_addc_co_u32_e32 v143, vcc, v1, v3, vcc
	v_add_co_u32_e32 v144, vcc, v0, v6
	v_addc_co_u32_e32 v145, vcc, v1, v7, vcc
	v_add_co_u32_e32 v148, vcc, v0, v10
	v_addc_co_u32_e32 v149, vcc, v1, v11, vcc
	s_mov_b64 s[4:5], 0
	v_or_b32_e32 v134, 0x800, v153
	v_or_b32_e32 v155, 0x1000, v153
	v_or_b32_e32 v156, 0x1800, v153
	v_or_b32_e32 v157, 0x2000, v153
	v_or_b32_e32 v158, 0x2800, v153
	v_or_b32_e32 v159, 0x3000, v153
	v_or_b32_e32 v160, 0x3800, v153
	s_waitcnt vmcnt(0) lgkmcnt(0)
	s_barrier
	v_readfirstlane_b32 s100, v150
	s_and_b32 s27, s6, 0x10000
	s_xor_b32 s28, s27, 0x10000
	s_add_i32 s27, s27, 0
	v_add3_u32 v161, s27, v151, v152
	v_add3_u32 v162, s27, v151, v153
	v_add3_u32 v163, s27, v154, v134
	v_add3_u32 v200, s27, v154, v155
	v_add3_u32 v201, s27, v154, v156
	v_add3_u32 v202, s27, v154, v157
	v_add3_u32 v203, s27, v154, v158
	v_add3_u32 v204, s27, v154, v159
	v_add3_u32 v205, s27, v154, v160
	ds_read_b128 v[184:187], v161 offset:32768
	ds_read_b128 v[168:171], v162
	ds_read_b128 v[172:175], v163
	ds_read_b128 v[176:179], v200
	ds_read_b128 v[180:183], v201
	ds_read_b128 v[188:191], v161 offset:34816
	ds_read_b128 v[192:195], v161 offset:36864
	ds_read_b128 v[196:199], v161 offset:38912
	s_add_i32 s101, s100, s28
	v_readfirstlane_b32 s98, v148
	v_readfirstlane_b32 s99, v149
	v_readfirstlane_b32 vcc_lo, v140
	v_readfirstlane_b32 vcc_hi, v141
	s_sub_u32 s98, s98, 0x1000000
	s_subb_u32 s99, s99, 0
	s_sub_u32 vcc_lo, vcc_lo, 0x1000000
	s_subb_u32 vcc_hi, vcc_hi, 0
	v_subrev_u32_e32 v148, s98, v148
	v_subrev_u32_e32 v140, vcc_lo, v140
	v_subrev_u32_e32 v146, s98, v146
	v_subrev_u32_e32 v138, vcc_lo, v138
	v_subrev_u32_e32 v144, s98, v144
	v_subrev_u32_e32 v136, vcc_lo, v136
	v_subrev_u32_e32 v142, s98, v142
	v_subrev_u32_e32 v130, vcc_lo, v130
	s_mov_b32 m0, s101
	s_nop 0
	global_load_lds_dwordx4 v148, s[98:99]
	s_add_i32 m0, s101, 0x8000
	s_nop 0
	global_load_lds_dwordx4 v140, vcc
	s_add_i32 m0, s101, 0x2000
	s_nop 0
	global_load_lds_dwordx4 v146, s[98:99]
	s_add_i32 m0, s101, 0xa000
	s_nop 0
	global_load_lds_dwordx4 v138, vcc
	s_add_i32 m0, s101, 0x4000
	s_nop 0
	global_load_lds_dwordx4 v144, s[98:99]
	s_add_i32 m0, s101, 0xc000
	s_nop 0
	global_load_lds_dwordx4 v136, vcc
	s_add_i32 m0, s101, 0x6000
	s_nop 0
	global_load_lds_dwordx4 v142, s[98:99]
	s_add_i32 m0, s101, 0xe000
	s_nop 0
	global_load_lds_dwordx4 v130, vcc

.Lex_793:
	s_waitcnt lgkmcnt(0)
	v_add3_u32 v130, s46, v156, v162
	v_add3_u32 v151, s46, v156, v161
	v_add3_u32 v202, s46, v156, v160
	v_add3_u32 v198, s46, v156, v159
	v_add3_u32 v186, s46, v156, v158
	v_add3_u32 v187, s46, v156, v157
	v_add3_u32 v188, s46, v156, v155
	v_add3_u32 v189, s46, v152, v154
	v_add3_u32 v190, s47, v152, v153
	ds_read_b128 v[134:137], v130
	ds_read_b128 v[138:141], v151
	ds_read_b128 v[142:145], v202
	ds_read_b128 v[146:149], v198
	ds_read_b128 v[158:161], v186
	ds_read_b128 v[162:165], v187
	ds_read_b128 v[166:169], v188
	ds_read_b128 v[154:157], v189
	ds_read_b128 v[170:173], v190
	s_waitcnt lgkmcnt(0)
	v_mfma_f32_16x16x32_bf16 v[18:21], v[170:173], v[138:141], v[18:21]
	v_mfma_f32_16x16x32_bf16 v[174:177], v[170:173], v[134:137], v[38:41]
	s_nop 2
	ds_read_b128 v[38:41], v190 offset:2048
	s_waitcnt lgkmcnt(0)
	v_mfma_f32_16x16x32_bf16 v[10:13], v[38:41], v[138:141], v[10:13]
	v_mfma_f32_16x16x32_bf16 v[62:65], v[170:173], v[146:149], v[62:65]
	v_mfma_f32_16x16x32_bf16 v[30:33], v[38:41], v[134:137], v[30:33]
	v_mfma_f32_16x16x32_bf16 v[58:61], v[38:41], v[146:149], v[58:61]
	ds_read_b128 v[178:181], v190 offset:4096
	s_waitcnt lgkmcnt(0)
	v_mfma_f32_16x16x32_bf16 v[182:185], v[178:181], v[134:137], v[22:25]
	v_mfma_f32_16x16x32_bf16 v[54:57], v[178:181], v[146:149], v[54:57]
	s_nop 1
	ds_read_b128 v[22:25], v190 offset:6144
	s_waitcnt lgkmcnt(0)
	v_mfma_f32_16x16x32_bf16 v[134:137], v[22:25], v[134:137], v[14:17]
	v_mfma_f32_16x16x32_bf16 v[14:17], v[22:25], v[154:157], v[114:117]
	v_mfma_f32_16x16x32_bf16 v[114:117], v[22:25], v[158:161], v[66:69]
	v_mfma_f32_16x16x32_bf16 v[66:69], v[178:181], v[154:157], v[118:121]
	v_mfma_f32_16x16x32_bf16 v[118:121], v[178:181], v[158:161], v[70:73]
	v_mfma_f32_16x16x32_bf16 v[70:73], v[38:41], v[154:157], v[122:125]
	v_mfma_f32_16x16x32_bf16 v[122:125], v[38:41], v[158:161], v[74:77]
	v_mfma_f32_16x16x32_bf16 v[74:77], v[170:173], v[154:157], v[126:129]
	v_mfma_f32_16x16x32_bf16 v[126:129], v[170:173], v[158:161], v[78:81]
	v_mfma_f32_16x16x32_bf16 v[50:53], v[22:25], v[146:149], v[50:53]
	v_mfma_f32_16x16x32_bf16 v[146:149], v[170:173], v[142:145], v[46:49]
	v_mfma_f32_16x16x32_bf16 v[152:155], v[38:41], v[142:145], v[42:45]
	v_mfma_f32_16x16x32_bf16 v[156:159], v[178:181], v[142:145], v[34:37]
	v_mfma_f32_16x16x32_bf16 v[26:29], v[22:25], v[142:145], v[26:29]
	v_mfma_f32_16x16x32_bf16 v[142:145], v[178:181], v[138:141], v[6:9]
	v_mfma_f32_16x16x32_bf16 v[110:113], v[170:173], v[166:169], v[110:113]
	v_mfma_f32_16x16x32_bf16 v[94:97], v[170:173], v[162:165], v[94:97]
	v_mfma_f32_16x16x32_bf16 v[106:109], v[38:41], v[166:169], v[106:109]
	v_mfma_f32_16x16x32_bf16 v[90:93], v[38:41], v[162:165], v[90:93]
	v_mfma_f32_16x16x32_bf16 v[102:105], v[178:181], v[166:169], v[102:105]
	v_mfma_f32_16x16x32_bf16 v[86:89], v[178:181], v[162:165], v[86:89]
	v_mfma_f32_16x16x32_bf16 v[98:101], v[22:25], v[166:169], v[98:101]
	v_mfma_f32_16x16x32_bf16 v[82:85], v[22:25], v[162:165], v[82:85]
	v_mfma_f32_16x16x32_bf16 v[22:25], v[22:25], v[138:141], v[2:5]
	ds_read_b128 v[138:141], v190 offset:1024
	ds_read_b128 v[160:163], v190 offset:3072
	ds_read_b128 v[164:167], v190 offset:5120
	ds_read_b128 v[168:171], v190 offset:7168
	ds_read_b128 v[2:5], v189 offset:1024
	ds_read_b128 v[6:9], v188 offset:1024
	ds_read_b128 v[34:37], v187 offset:1024
	ds_read_b128 v[38:41], v186 offset:1024
	s_waitcnt lgkmcnt(3)
	v_mfma_f32_16x16x32_bf16 v[178:181], v[138:141], v[2:5], v[74:77]
	v_mfma_f32_16x16x32_bf16 v[186:189], v[160:163], v[2:5], v[70:73]
	v_mfma_f32_16x16x32_bf16 v[190:193], v[164:167], v[2:5], v[66:69]
	v_mfma_f32_16x16x32_bf16 v[194:197], v[168:171], v[2:5], v[14:17]
	ds_read_b128 v[2:5], v198 offset:1024
	s_waitcnt lgkmcnt(3)
	v_mfma_f32_16x16x32_bf16 v[110:113], v[138:141], v[6:9], v[110:113]
	v_mfma_f32_16x16x32_bf16 v[106:109], v[160:163], v[6:9], v[106:109]
	v_mfma_f32_16x16x32_bf16 v[102:105], v[164:167], v[6:9], v[102:105]
	v_mfma_f32_16x16x32_bf16 v[198:201], v[168:171], v[6:9], v[98:101]
	ds_read_b128 v[6:9], v202 offset:1024
	s_waitcnt lgkmcnt(3)
	v_mfma_f32_16x16x32_bf16 v[66:69], v[138:141], v[34:37], v[94:97]
	v_mfma_f32_16x16x32_bf16 v[70:73], v[160:163], v[34:37], v[90:93]
	v_mfma_f32_16x16x32_bf16 v[74:77], v[164:167], v[34:37], v[86:89]
	v_mfma_f32_16x16x32_bf16 v[78:81], v[168:171], v[34:37], v[82:85]
	ds_read_b128 v[14:17], v151 offset:1024
	s_waitcnt lgkmcnt(3)
	v_mfma_f32_16x16x32_bf16 v[82:85], v[138:141], v[38:41], v[126:129]
	v_mfma_f32_16x16x32_bf16 v[86:89], v[160:163], v[38:41], v[122:125]
	v_mfma_f32_16x16x32_bf16 v[90:93], v[164:167], v[38:41], v[118:121]
	v_mfma_f32_16x16x32_bf16 v[94:97], v[168:171], v[38:41], v[114:117]
	ds_read_b128 v[98:101], v130 offset:1024
	s_waitcnt lgkmcnt(3)
	v_mfma_f32_16x16x32_bf16 v[34:37], v[138:141], v[2:5], v[62:65]
	v_mfma_f32_16x16x32_bf16 v[38:41], v[160:163], v[2:5], v[58:61]
	v_mfma_f32_16x16x32_bf16 v[42:45], v[164:167], v[2:5], v[54:57]
	v_mfma_f32_16x16x32_bf16 v[46:49], v[168:171], v[2:5], v[50:53]
	s_waitcnt lgkmcnt(2)
	v_mfma_f32_16x16x32_bf16 v[50:53], v[138:141], v[6:9], v[146:149]
	v_mfma_f32_16x16x32_bf16 v[54:57], v[160:163], v[6:9], v[152:155]
	v_mfma_f32_16x16x32_bf16 v[58:61], v[164:167], v[6:9], v[156:159]
	v_mfma_f32_16x16x32_bf16 v[62:65], v[168:171], v[6:9], v[26:29]
	s_waitcnt lgkmcnt(1)
	v_mfma_f32_16x16x32_bf16 v[2:5], v[138:141], v[14:17], v[18:21]
	v_mfma_f32_16x16x32_bf16 v[6:9], v[160:163], v[14:17], v[10:13]
	v_mfma_f32_16x16x32_bf16 v[10:13], v[164:167], v[14:17], v[142:145]
	v_mfma_f32_16x16x32_bf16 v[14:17], v[168:171], v[14:17], v[22:25]
	s_waitcnt lgkmcnt(0)
	v_mfma_f32_16x16x32_bf16 v[18:21], v[138:141], v[98:101], v[174:177]
	v_mfma_f32_16x16x32_bf16 v[22:25], v[160:163], v[98:101], v[30:33]
	v_mfma_f32_16x16x32_bf16 v[26:29], v[164:167], v[98:101], v[182:185]
	v_mfma_f32_16x16x32_bf16 v[30:33], v[168:171], v[98:101], v[134:137]
	v_lshrrev_b32_e32 v98, 6, v150
	v_mul_lo_u32 v98, v98, s48
	v_add_u32_e32 v101, s46, v98
	v_lshlrev_b32_e32 v98, 2, v150
	v_and_b32_e32 v100, 15, v150
	v_and_b32_e32 v115, 60, v98
	v_ashrrev_i32_e32 v98, 1, v150
	v_bfe_u32 v99, v150, 4, 2
	v_and_b32_e32 v114, 48, v150
	v_and_b32_e32 v116, 0xffffff80, v98
	v_lshlrev_b32_e32 v98, 2, v115
	v_mul_u32_u24_e32 v117, 0x110, v99
	v_mul_u32_u24_e32 v100, 0x110, v100
	v_add3_u32 v98, v101, v98, v117
	v_add3_u32 v101, v101, v114, v100
	s_waitcnt vmcnt(0)
	s_barrier
	ds_write_b128 v101, v[178:181]
	ds_write_b128 v101, v[186:189] offset:64
	ds_write_b128 v101, v[190:193] offset:128
	ds_write_b128 v101, v[194:197] offset:192
	ds_write_b128 v101, v[110:113] offset:4352
	ds_write_b128 v101, v[106:109] offset:4416
	ds_write_b128 v101, v[102:105] offset:4480
	ds_write_b128 v101, v[198:201] offset:4544
	ds_read_b128 v[102:105], v98
	v_add_u32_e32 v100, s28, v116
	s_ashr_i32 s31, s30, 31
	v_and_or_b32 v106, v150, s49, v115
	s_lshl_b64 s[38:39], s[30:31], 1
	s_waitcnt lgkmcnt(0)
	v_mul_f32_e32 v102, 0xbfb8aa3b, v102
	v_mul_f32_e32 v103, 0xbfb8aa3b, v103
	v_mul_f32_e32 v104, 0xbfb8aa3b, v104
	v_mul_f32_e32 v105, 0xbfb8aa3b, v105
	v_exp_f32_e32 v102, v102
	v_exp_f32_e32 v103, v103
	v_exp_f32_e32 v104, v104
	v_exp_f32_e32 v105, v105
	v_add_f32_e32 v102, 1.0, v102
	v_add_f32_e32 v103, 1.0, v103
	v_add_f32_e32 v104, 1.0, v104
	v_add_f32_e32 v105, 1.0, v105
	v_rcp_f32_e32 v102, v102
	v_rcp_f32_e32 v103, v103
	v_rcp_f32_e32 v104, v104
	v_rcp_f32_e32 v105, v105
	v_lshl_add_u64 v[0:1], v[0:1], 0, s[38:39]
	v_cvt_pk_bf16_f32 v102, v102, v103
	v_lshlrev_b32_e32 v130, 1, v106
	v_cvt_pk_bf16_f32 v103, v104, v105
	v_or_b32_e32 v104, v100, v99
	v_ashrrev_i32_e32 v105, 31, v104
	v_lshl_add_u64 v[0:1], v[0:1], 0, v[130:131]
	v_lshlrev_b64 v[104:105], 11, v[104:105]
	v_lshl_add_u64 v[104:105], v[0:1], 0, v[104:105]
	flat_store_dwordx2 v[104:105], v[102:103]
	ds_read_b128 v[102:105], v98 offset:1088
	s_lshl_b64 s[42:43], s[28:29], 10
	s_mov_b32 s29, 0
	s_waitcnt lgkmcnt(0)
	v_mul_f32_e32 v102, 0xbfb8aa3b, v102
	v_exp_f32_e32 v102, v102
	v_mul_f32_e32 v103, 0xbfb8aa3b, v103
	v_exp_f32_e32 v103, v103
	v_add_f32_e32 v102, 1.0, v102
	v_rcp_f32_e32 v106, v102
	v_add_f32_e32 v102, 1.0, v103
	v_mul_f32_e32 v103, 0xbfb8aa3b, v104
	v_exp_f32_e32 v103, v103
	v_mul_f32_e32 v104, 0xbfb8aa3b, v105
	v_exp_f32_e32 v104, v104
	v_rcp_f32_e32 v105, v102
	v_add_f32_e32 v102, 1.0, v103
	v_rcp_f32_e32 v103, v102
	v_add_f32_e32 v102, 1.0, v104
	v_rcp_f32_e32 v107, v102
	v_or_b32_e32 v102, 4, v99
	v_cvt_pk_bf16_f32 v104, v106, v105
	v_or_b32_e32 v106, v100, v102
	v_cvt_pk_bf16_f32 v105, v103, v107
	v_ashrrev_i32_e32 v107, 31, v106
	v_lshlrev_b64 v[106:107], 11, v[106:107]
	v_lshl_add_u64 v[106:107], v[0:1], 0, v[106:107]
	flat_store_dwordx2 v[106:107], v[104:105]
	ds_read_b128 v[104:107], v98 offset:2176
	s_waitcnt lgkmcnt(0)
	v_mul_f32_e32 v103, 0xbfb8aa3b, v104
	v_exp_f32_e32 v103, v103
	v_mul_f32_e32 v104, 0xbfb8aa3b, v105
	v_exp_f32_e32 v104, v104
	v_add_f32_e32 v103, 1.0, v103
	v_rcp_f32_e32 v105, v103
	v_add_f32_e32 v103, 1.0, v104
	v_mul_f32_e32 v104, 0xbfb8aa3b, v106
	v_exp_f32_e32 v104, v104
	v_mul_f32_e32 v106, 0xbfb8aa3b, v107
	v_exp_f32_e32 v106, v106
	v_rcp_f32_e32 v107, v103
	v_add_f32_e32 v103, 1.0, v104
	v_rcp_f32_e32 v108, v103
	v_add_f32_e32 v103, 1.0, v106
	v_rcp_f32_e32 v106, v103
	v_or_b32_e32 v103, 8, v99
	v_cvt_pk_bf16_f32 v104, v105, v107
	v_cvt_pk_bf16_f32 v105, v108, v106
	v_or_b32_e32 v106, v100, v103
	v_ashrrev_i32_e32 v107, 31, v106
	v_lshlrev_b64 v[106:107], 11, v[106:107]
	v_lshl_add_u64 v[106:107], v[0:1], 0, v[106:107]
	flat_store_dwordx2 v[106:107], v[104:105]
	ds_read_b128 v[104:107], v98 offset:3264
	s_waitcnt lgkmcnt(0)
	v_mul_f32_e32 v104, 0xbfb8aa3b, v104
	v_exp_f32_e32 v104, v104
	v_mul_f32_e32 v105, 0xbfb8aa3b, v105
	v_exp_f32_e32 v105, v105
	v_add_f32_e32 v104, 1.0, v104
	v_rcp_f32_e32 v108, v104
	v_add_f32_e32 v104, 1.0, v105
	v_mul_f32_e32 v105, 0xbfb8aa3b, v106
	v_exp_f32_e32 v105, v105
	v_mul_f32_e32 v106, 0xbfb8aa3b, v107
	v_exp_f32_e32 v106, v106
	v_rcp_f32_e32 v107, v104
	v_add_f32_e32 v104, 1.0, v105
	v_rcp_f32_e32 v105, v104
	v_add_f32_e32 v104, 1.0, v106
	v_rcp_f32_e32 v109, v104
	v_or_b32_e32 v104, 12, v99
	v_cvt_pk_bf16_f32 v106, v108, v107
	v_or_b32_e32 v108, v100, v104
	v_cvt_pk_bf16_f32 v107, v105, v109
	v_ashrrev_i32_e32 v109, 31, v108
	v_lshlrev_b64 v[108:109], 11, v[108:109]
	v_lshl_add_u64 v[108:109], v[0:1], 0, v[108:109]
	flat_store_dwordx2 v[108:109], v[106:107]
	ds_read_b128 v[106:109], v98 offset:4352
	s_waitcnt lgkmcnt(0)
	v_mul_f32_e32 v105, 0xbfb8aa3b, v106
	v_exp_f32_e32 v105, v105
	v_mul_f32_e32 v106, 0xbfb8aa3b, v107
	v_exp_f32_e32 v106, v106
	v_add_f32_e32 v105, 1.0, v105
	v_rcp_f32_e32 v107, v105
	v_add_f32_e32 v105, 1.0, v106
	v_mul_f32_e32 v106, 0xbfb8aa3b, v108
	v_exp_f32_e32 v106, v106
	v_mul_f32_e32 v108, 0xbfb8aa3b, v109
	v_exp_f32_e32 v108, v108
	v_rcp_f32_e32 v109, v105
	v_add_f32_e32 v105, 1.0, v106
	v_rcp_f32_e32 v110, v105
	v_add_f32_e32 v105, 1.0, v108
	v_rcp_f32_e32 v108, v105
	v_or_b32_e32 v105, 16, v99
	v_cvt_pk_bf16_f32 v106, v107, v109
	v_cvt_pk_bf16_f32 v107, v110, v108
	v_or_b32_e32 v108, v100, v105
	v_ashrrev_i32_e32 v109, 31, v108
	v_lshlrev_b64 v[108:109], 11, v[108:109]
	v_lshl_add_u64 v[108:109], v[0:1], 0, v[108:109]
	flat_store_dwordx2 v[108:109], v[106:107]
	ds_read_b128 v[106:109], v98 offset:5440
	s_waitcnt lgkmcnt(0)
	v_mul_f32_e32 v106, 0xbfb8aa3b, v106
	v_exp_f32_e32 v106, v106
	v_mul_f32_e32 v107, 0xbfb8aa3b, v107
	v_exp_f32_e32 v107, v107
	v_add_f32_e32 v106, 1.0, v106
	v_rcp_f32_e32 v110, v106
	v_add_f32_e32 v106, 1.0, v107
	v_mul_f32_e32 v107, 0xbfb8aa3b, v108
	v_exp_f32_e32 v107, v107
	v_mul_f32_e32 v108, 0xbfb8aa3b, v109
	v_exp_f32_e32 v108, v108
	v_rcp_f32_e32 v109, v106
	v_add_f32_e32 v106, 1.0, v107
	v_rcp_f32_e32 v107, v106
	v_add_f32_e32 v106, 1.0, v108
	v_rcp_f32_e32 v111, v106
	v_or_b32_e32 v106, 20, v99
	v_cvt_pk_bf16_f32 v108, v110, v109
	v_or_b32_e32 v110, v100, v106
	v_cvt_pk_bf16_f32 v109, v107, v111
	v_ashrrev_i32_e32 v111, 31, v110
	v_lshlrev_b64 v[110:111], 11, v[110:111]
	v_lshl_add_u64 v[110:111], v[0:1], 0, v[110:111]
	flat_store_dwordx2 v[110:111], v[108:109]
	ds_read_b128 v[108:111], v98 offset:6528
	s_waitcnt lgkmcnt(0)
	v_mul_f32_e32 v107, 0xbfb8aa3b, v108
	v_exp_f32_e32 v107, v107
	v_mul_f32_e32 v108, 0xbfb8aa3b, v109
	v_exp_f32_e32 v108, v108
	v_add_f32_e32 v107, 1.0, v107
	v_rcp_f32_e32 v109, v107
	v_add_f32_e32 v107, 1.0, v108
	v_mul_f32_e32 v108, 0xbfb8aa3b, v110
	v_exp_f32_e32 v108, v108
	v_mul_f32_e32 v110, 0xbfb8aa3b, v111
	v_exp_f32_e32 v110, v110
	v_rcp_f32_e32 v111, v107
	v_add_f32_e32 v107, 1.0, v108
	v_rcp_f32_e32 v112, v107
	v_add_f32_e32 v107, 1.0, v110
	v_rcp_f32_e32 v110, v107
	v_or_b32_e32 v107, 24, v99
	v_cvt_pk_bf16_f32 v108, v109, v111
	v_cvt_pk_bf16_f32 v109, v112, v110
	v_or_b32_e32 v110, v100, v107
	v_ashrrev_i32_e32 v111, 31, v110
	v_lshlrev_b64 v[110:111], 11, v[110:111]
	v_lshl_add_u64 v[110:111], v[0:1], 0, v[110:111]
	flat_store_dwordx2 v[110:111], v[108:109]
	ds_read_b128 v[108:111], v98 offset:7616
	s_waitcnt lgkmcnt(0)
	v_mul_f32_e32 v108, 0xbfb8aa3b, v108
	v_exp_f32_e32 v108, v108
	v_mul_f32_e32 v109, 0xbfb8aa3b, v109
	v_exp_f32_e32 v109, v109
	v_add_f32_e32 v108, 1.0, v108
	v_rcp_f32_e32 v112, v108
	v_add_f32_e32 v108, 1.0, v109
	v_mul_f32_e32 v109, 0xbfb8aa3b, v110
	v_exp_f32_e32 v109, v109
	v_mul_f32_e32 v110, 0xbfb8aa3b, v111
	v_exp_f32_e32 v110, v110
	v_rcp_f32_e32 v111, v108
	v_add_f32_e32 v108, 1.0, v109
	v_rcp_f32_e32 v109, v108
	v_add_f32_e32 v108, 1.0, v110
	v_rcp_f32_e32 v113, v108
	v_or_b32_e32 v108, 28, v99
	v_cvt_pk_bf16_f32 v110, v112, v111
	v_or_b32_e32 v112, v100, v108
	v_cvt_pk_bf16_f32 v111, v109, v113
	v_ashrrev_i32_e32 v113, 31, v112
	v_lshlrev_b64 v[112:113], 11, v[112:113]
	v_lshl_add_u64 v[112:113], v[0:1], 0, v[112:113]
	flat_store_dwordx2 v[112:113], v[110:111]
	ds_write_b128 v101, v[66:69]
	ds_write_b128 v101, v[70:73] offset:64
	ds_write_b128 v101, v[74:77] offset:128
	ds_write_b128 v101, v[78:81] offset:192
	ds_write_b128 v101, v[82:85] offset:4352
	ds_write_b128 v101, v[86:89] offset:4416
	ds_write_b128 v101, v[90:93] offset:4480
	ds_write_b128 v101, v[94:97] offset:4544
	ds_read_b128 v[66:69], v98
	v_or_b32_e32 v70, 32, v100
	s_waitcnt lgkmcnt(0)
	v_mul_f32_e32 v66, 0xbfb8aa3b, v66
	v_mul_f32_e32 v67, 0xbfb8aa3b, v67
	v_mul_f32_e32 v68, 0xbfb8aa3b, v68
	v_mul_f32_e32 v69, 0xbfb8aa3b, v69
	v_exp_f32_e32 v66, v66
	v_exp_f32_e32 v67, v67
	v_exp_f32_e32 v68, v68
	v_exp_f32_e32 v69, v69
	v_add_f32_e32 v66, 1.0, v66
	v_add_f32_e32 v67, 1.0, v67
	v_add_f32_e32 v68, 1.0, v68
	v_add_f32_e32 v69, 1.0, v69
	v_rcp_f32_e32 v66, v66
	v_rcp_f32_e32 v67, v67
	v_rcp_f32_e32 v68, v68
	v_rcp_f32_e32 v69, v69
	v_cvt_pk_bf16_f32 v66, v66, v67
	v_cvt_pk_bf16_f32 v67, v68, v69
	v_or_b32_e32 v68, v70, v99
	v_ashrrev_i32_e32 v69, 31, v68
	v_lshlrev_b64 v[68:69], 11, v[68:69]
	v_lshl_add_u64 v[68:69], v[0:1], 0, v[68:69]
	flat_store_dwordx2 v[68:69], v[66:67]
	ds_read_b128 v[66:69], v98 offset:1088
	s_waitcnt lgkmcnt(0)
	v_mul_f32_e32 v66, 0xbfb8aa3b, v66
	v_mul_f32_e32 v67, 0xbfb8aa3b, v67
	v_mul_f32_e32 v68, 0xbfb8aa3b, v68
	v_mul_f32_e32 v69, 0xbfb8aa3b, v69
	v_exp_f32_e32 v66, v66
	v_exp_f32_e32 v67, v67
	v_exp_f32_e32 v68, v68
	v_exp_f32_e32 v69, v69
	v_add_f32_e32 v66, 1.0, v66
	v_add_f32_e32 v67, 1.0, v67
	v_add_f32_e32 v68, 1.0, v68
	v_add_f32_e32 v69, 1.0, v69
	v_rcp_f32_e32 v66, v66
	v_rcp_f32_e32 v67, v67
	v_rcp_f32_e32 v68, v68
	v_rcp_f32_e32 v69, v69
	v_cvt_pk_bf16_f32 v66, v66, v67
	v_cvt_pk_bf16_f32 v67, v68, v69
	v_or_b32_e32 v68, v70, v102
	v_ashrrev_i32_e32 v69, 31, v68
	v_lshlrev_b64 v[68:69], 11, v[68:69]
	v_lshl_add_u64 v[68:69], v[0:1], 0, v[68:69]
	flat_store_dwordx2 v[68:69], v[66:67]
	ds_read_b128 v[66:69], v98 offset:2176
	s_waitcnt lgkmcnt(0)
	v_mul_f32_e32 v66, 0xbfb8aa3b, v66
	v_mul_f32_e32 v67, 0xbfb8aa3b, v67
	v_mul_f32_e32 v68, 0xbfb8aa3b, v68
	v_mul_f32_e32 v69, 0xbfb8aa3b, v69
	v_exp_f32_e32 v66, v66
	v_exp_f32_e32 v67, v67
	v_exp_f32_e32 v68, v68
	v_exp_f32_e32 v69, v69
	v_add_f32_e32 v66, 1.0, v66
	v_add_f32_e32 v67, 1.0, v67
	v_add_f32_e32 v68, 1.0, v68
	v_add_f32_e32 v69, 1.0, v69
	v_rcp_f32_e32 v66, v66
	v_rcp_f32_e32 v67, v67
	v_rcp_f32_e32 v68, v68
	v_rcp_f32_e32 v69, v69
	v_cvt_pk_bf16_f32 v66, v66, v67
	v_cvt_pk_bf16_f32 v67, v68, v69
	v_or_b32_e32 v68, v70, v103
	v_ashrrev_i32_e32 v69, 31, v68
	v_lshlrev_b64 v[68:69], 11, v[68:69]
	v_lshl_add_u64 v[68:69], v[0:1], 0, v[68:69]
	flat_store_dwordx2 v[68:69], v[66:67]
	ds_read_b128 v[66:69], v98 offset:3264
	s_waitcnt lgkmcnt(0)
	v_mul_f32_e32 v66, 0xbfb8aa3b, v66
	v_mul_f32_e32 v67, 0xbfb8aa3b, v67
	v_mul_f32_e32 v68, 0xbfb8aa3b, v68
	v_mul_f32_e32 v69, 0xbfb8aa3b, v69
	v_exp_f32_e32 v66, v66
	v_exp_f32_e32 v67, v67
	v_exp_f32_e32 v68, v68
	v_exp_f32_e32 v69, v69
	v_add_f32_e32 v66, 1.0, v66
	v_add_f32_e32 v67, 1.0, v67
	v_add_f32_e32 v68, 1.0, v68
	v_add_f32_e32 v69, 1.0, v69
	v_rcp_f32_e32 v66, v66
	v_rcp_f32_e32 v67, v67
	v_rcp_f32_e32 v68, v68
	v_rcp_f32_e32 v69, v69
	v_cvt_pk_bf16_f32 v66, v66, v67
	v_cvt_pk_bf16_f32 v67, v68, v69
	v_or_b32_e32 v68, v70, v104
	v_ashrrev_i32_e32 v69, 31, v68
	v_lshlrev_b64 v[68:69], 11, v[68:69]
	v_lshl_add_u64 v[68:69], v[0:1], 0, v[68:69]
	flat_store_dwordx2 v[68:69], v[66:67]
	ds_read_b128 v[66:69], v98 offset:4352
	s_waitcnt lgkmcnt(0)
	v_mul_f32_e32 v66, 0xbfb8aa3b, v66
	v_mul_f32_e32 v67, 0xbfb8aa3b, v67
	v_mul_f32_e32 v68, 0xbfb8aa3b, v68
	v_mul_f32_e32 v69, 0xbfb8aa3b, v69
	v_exp_f32_e32 v66, v66
	v_exp_f32_e32 v67, v67
	v_exp_f32_e32 v68, v68
	v_exp_f32_e32 v69, v69
	v_add_f32_e32 v66, 1.0, v66
	v_add_f32_e32 v67, 1.0, v67
	v_add_f32_e32 v68, 1.0, v68
	v_add_f32_e32 v69, 1.0, v69
	v_rcp_f32_e32 v66, v66
	v_rcp_f32_e32 v67, v67
	v_rcp_f32_e32 v68, v68
	v_rcp_f32_e32 v69, v69
	v_cvt_pk_bf16_f32 v66, v66, v67
	v_cvt_pk_bf16_f32 v67, v68, v69
	v_or_b32_e32 v68, v70, v105
	v_ashrrev_i32_e32 v69, 31, v68
	v_lshlrev_b64 v[68:69], 11, v[68:69]
	v_lshl_add_u64 v[68:69], v[0:1], 0, v[68:69]
	flat_store_dwordx2 v[68:69], v[66:67]
	ds_read_b128 v[66:69], v98 offset:5440
	s_waitcnt lgkmcnt(0)
	v_mul_f32_e32 v66, 0xbfb8aa3b, v66
	v_mul_f32_e32 v67, 0xbfb8aa3b, v67
	v_mul_f32_e32 v68, 0xbfb8aa3b, v68
	v_mul_f32_e32 v69, 0xbfb8aa3b, v69
	v_exp_f32_e32 v66, v66
	v_exp_f32_e32 v67, v67
	v_exp_f32_e32 v68, v68
	v_exp_f32_e32 v69, v69
	v_add_f32_e32 v66, 1.0, v66
	v_add_f32_e32 v67, 1.0, v67
	v_add_f32_e32 v68, 1.0, v68
	v_add_f32_e32 v69, 1.0, v69
	v_rcp_f32_e32 v66, v66
	v_rcp_f32_e32 v67, v67
	v_rcp_f32_e32 v68, v68
	v_rcp_f32_e32 v69, v69
	v_cvt_pk_bf16_f32 v66, v66, v67
	v_cvt_pk_bf16_f32 v67, v68, v69
	v_or_b32_e32 v68, v70, v106
	v_ashrrev_i32_e32 v69, 31, v68
	v_lshlrev_b64 v[68:69], 11, v[68:69]
	v_lshl_add_u64 v[68:69], v[0:1], 0, v[68:69]
	flat_store_dwordx2 v[68:69], v[66:67]
	ds_read_b128 v[66:69], v98 offset:6528
	s_waitcnt lgkmcnt(0)
	v_mul_f32_e32 v66, 0xbfb8aa3b, v66
	v_mul_f32_e32 v67, 0xbfb8aa3b, v67
	v_mul_f32_e32 v68, 0xbfb8aa3b, v68
	v_mul_f32_e32 v69, 0xbfb8aa3b, v69
	v_exp_f32_e32 v66, v66
	v_exp_f32_e32 v67, v67
	v_exp_f32_e32 v68, v68
	v_exp_f32_e32 v69, v69
	v_add_f32_e32 v66, 1.0, v66
	v_add_f32_e32 v67, 1.0, v67
	v_add_f32_e32 v68, 1.0, v68
	v_add_f32_e32 v69, 1.0, v69
	v_rcp_f32_e32 v66, v66
	v_rcp_f32_e32 v67, v67
	v_rcp_f32_e32 v68, v68
	v_rcp_f32_e32 v69, v69
	v_cvt_pk_bf16_f32 v66, v66, v67
	v_cvt_pk_bf16_f32 v67, v68, v69
	v_or_b32_e32 v68, v70, v107
	v_ashrrev_i32_e32 v69, 31, v68
	v_lshlrev_b64 v[68:69], 11, v[68:69]
	v_lshl_add_u64 v[68:69], v[0:1], 0, v[68:69]
	flat_store_dwordx2 v[68:69], v[66:67]
	ds_read_b128 v[66:69], v98 offset:7616
	s_waitcnt lgkmcnt(0)
	v_mul_f32_e32 v66, 0xbfb8aa3b, v66
	v_mul_f32_e32 v67, 0xbfb8aa3b, v67
	v_mul_f32_e32 v68, 0xbfb8aa3b, v68
	v_mul_f32_e32 v69, 0xbfb8aa3b, v69
	v_exp_f32_e32 v66, v66
	v_exp_f32_e32 v67, v67
	v_exp_f32_e32 v68, v68
	v_exp_f32_e32 v69, v69
	v_add_f32_e32 v66, 1.0, v66
	v_add_f32_e32 v67, 1.0, v67
	v_add_f32_e32 v68, 1.0, v68
	v_add_f32_e32 v69, 1.0, v69
	v_rcp_f32_e32 v66, v66
	v_rcp_f32_e32 v67, v67
	v_rcp_f32_e32 v68, v68
	v_rcp_f32_e32 v69, v69
	v_cvt_pk_bf16_f32 v66, v66, v67
	v_cvt_pk_bf16_f32 v67, v68, v69
	v_or_b32_e32 v68, v70, v108
	v_ashrrev_i32_e32 v69, 31, v68
	v_lshlrev_b64 v[68:69], 11, v[68:69]
	v_lshl_add_u64 v[68:69], v[0:1], 0, v[68:69]
	flat_store_dwordx2 v[68:69], v[66:67]
	ds_write_b128 v101, v[34:37]
	ds_write_b128 v101, v[38:41] offset:64
	ds_write_b128 v101, v[42:45] offset:128
	ds_write_b128 v101, v[46:49] offset:192
	ds_write_b128 v101, v[50:53] offset:4352
	ds_write_b128 v101, v[54:57] offset:4416
	ds_write_b128 v101, v[58:61] offset:4480
	ds_write_b128 v101, v[62:65] offset:4544
	ds_read_b128 v[34:37], v98
	v_or_b32_e32 v38, 64, v100
	s_waitcnt lgkmcnt(0)
	v_mul_f32_e32 v34, 0xbfb8aa3b, v34
	v_mul_f32_e32 v35, 0xbfb8aa3b, v35
	v_mul_f32_e32 v36, 0xbfb8aa3b, v36
	v_mul_f32_e32 v37, 0xbfb8aa3b, v37
	v_exp_f32_e32 v34, v34
	v_exp_f32_e32 v35, v35
	v_exp_f32_e32 v36, v36
	v_exp_f32_e32 v37, v37
	v_add_f32_e32 v34, 1.0, v34
	v_add_f32_e32 v35, 1.0, v35
	v_add_f32_e32 v36, 1.0, v36
	v_add_f32_e32 v37, 1.0, v37
	v_rcp_f32_e32 v34, v34
	v_rcp_f32_e32 v35, v35
	v_rcp_f32_e32 v36, v36
	v_rcp_f32_e32 v37, v37
	v_cvt_pk_bf16_f32 v34, v34, v35
	v_cvt_pk_bf16_f32 v35, v36, v37
	v_or_b32_e32 v36, v38, v99
	v_ashrrev_i32_e32 v37, 31, v36
	v_lshlrev_b64 v[36:37], 11, v[36:37]
	v_lshl_add_u64 v[36:37], v[0:1], 0, v[36:37]
	flat_store_dwordx2 v[36:37], v[34:35]
	ds_read_b128 v[34:37], v98 offset:1088
	s_waitcnt lgkmcnt(0)
	v_mul_f32_e32 v34, 0xbfb8aa3b, v34
	v_mul_f32_e32 v35, 0xbfb8aa3b, v35
	v_mul_f32_e32 v36, 0xbfb8aa3b, v36
	v_mul_f32_e32 v37, 0xbfb8aa3b, v37
	v_exp_f32_e32 v34, v34
	v_exp_f32_e32 v35, v35
	v_exp_f32_e32 v36, v36
	v_exp_f32_e32 v37, v37
	v_add_f32_e32 v34, 1.0, v34
	v_add_f32_e32 v35, 1.0, v35
	v_add_f32_e32 v36, 1.0, v36
	v_add_f32_e32 v37, 1.0, v37
	v_rcp_f32_e32 v34, v34
	v_rcp_f32_e32 v35, v35
	v_rcp_f32_e32 v36, v36
	v_rcp_f32_e32 v37, v37
	v_cvt_pk_bf16_f32 v34, v34, v35
	v_cvt_pk_bf16_f32 v35, v36, v37
	v_or_b32_e32 v36, v38, v102
	v_ashrrev_i32_e32 v37, 31, v36
	v_lshlrev_b64 v[36:37], 11, v[36:37]
	v_lshl_add_u64 v[36:37], v[0:1], 0, v[36:37]
	flat_store_dwordx2 v[36:37], v[34:35]
	ds_read_b128 v[34:37], v98 offset:2176
	s_waitcnt lgkmcnt(0)
	v_mul_f32_e32 v34, 0xbfb8aa3b, v34
	v_mul_f32_e32 v35, 0xbfb8aa3b, v35
	v_mul_f32_e32 v36, 0xbfb8aa3b, v36
	v_mul_f32_e32 v37, 0xbfb8aa3b, v37
	v_exp_f32_e32 v34, v34
	v_exp_f32_e32 v35, v35
	v_exp_f32_e32 v36, v36
	v_exp_f32_e32 v37, v37
	v_add_f32_e32 v34, 1.0, v34
	v_add_f32_e32 v35, 1.0, v35
	v_add_f32_e32 v36, 1.0, v36
	v_add_f32_e32 v37, 1.0, v37
	v_rcp_f32_e32 v34, v34
	v_rcp_f32_e32 v35, v35
	v_rcp_f32_e32 v36, v36
	v_rcp_f32_e32 v37, v37
	v_cvt_pk_bf16_f32 v34, v34, v35
	v_cvt_pk_bf16_f32 v35, v36, v37
	v_or_b32_e32 v36, v38, v103
	v_ashrrev_i32_e32 v37, 31, v36
	v_lshlrev_b64 v[36:37], 11, v[36:37]
	v_lshl_add_u64 v[36:37], v[0:1], 0, v[36:37]
	flat_store_dwordx2 v[36:37], v[34:35]
	ds_read_b128 v[34:37], v98 offset:3264
	s_waitcnt lgkmcnt(0)
	v_mul_f32_e32 v34, 0xbfb8aa3b, v34
	v_mul_f32_e32 v35, 0xbfb8aa3b, v35
	v_mul_f32_e32 v36, 0xbfb8aa3b, v36
	v_mul_f32_e32 v37, 0xbfb8aa3b, v37
	v_exp_f32_e32 v34, v34
	v_exp_f32_e32 v35, v35
	v_exp_f32_e32 v36, v36
	v_exp_f32_e32 v37, v37
	v_add_f32_e32 v34, 1.0, v34
	v_add_f32_e32 v35, 1.0, v35
	v_add_f32_e32 v36, 1.0, v36
	v_add_f32_e32 v37, 1.0, v37
	v_rcp_f32_e32 v34, v34
	v_rcp_f32_e32 v35, v35
	v_rcp_f32_e32 v36, v36
	v_rcp_f32_e32 v37, v37
	v_cvt_pk_bf16_f32 v34, v34, v35
	v_cvt_pk_bf16_f32 v35, v36, v37
	v_or_b32_e32 v36, v38, v104
	v_ashrrev_i32_e32 v37, 31, v36
	v_lshlrev_b64 v[36:37], 11, v[36:37]
	v_lshl_add_u64 v[36:37], v[0:1], 0, v[36:37]
	flat_store_dwordx2 v[36:37], v[34:35]
	ds_read_b128 v[34:37], v98 offset:4352
	s_waitcnt lgkmcnt(0)
	v_mul_f32_e32 v34, 0xbfb8aa3b, v34
	v_mul_f32_e32 v35, 0xbfb8aa3b, v35
	v_mul_f32_e32 v36, 0xbfb8aa3b, v36
	v_mul_f32_e32 v37, 0xbfb8aa3b, v37
	v_exp_f32_e32 v34, v34
	v_exp_f32_e32 v35, v35
	v_exp_f32_e32 v36, v36
	v_exp_f32_e32 v37, v37
	v_add_f32_e32 v34, 1.0, v34
	v_add_f32_e32 v35, 1.0, v35
	v_add_f32_e32 v36, 1.0, v36
	v_add_f32_e32 v37, 1.0, v37
	v_rcp_f32_e32 v34, v34
	v_rcp_f32_e32 v35, v35
	v_rcp_f32_e32 v36, v36
	v_rcp_f32_e32 v37, v37
	v_cvt_pk_bf16_f32 v34, v34, v35
	v_cvt_pk_bf16_f32 v35, v36, v37
	v_or_b32_e32 v36, v38, v105
	v_ashrrev_i32_e32 v37, 31, v36
	v_lshlrev_b64 v[36:37], 11, v[36:37]
	v_lshl_add_u64 v[36:37], v[0:1], 0, v[36:37]
	flat_store_dwordx2 v[36:37], v[34:35]
	ds_read_b128 v[34:37], v98 offset:5440
	s_waitcnt lgkmcnt(0)
	v_mul_f32_e32 v34, 0xbfb8aa3b, v34
	v_mul_f32_e32 v35, 0xbfb8aa3b, v35
	v_mul_f32_e32 v36, 0xbfb8aa3b, v36
	v_mul_f32_e32 v37, 0xbfb8aa3b, v37
	v_exp_f32_e32 v34, v34
	v_exp_f32_e32 v35, v35
	v_exp_f32_e32 v36, v36
	v_exp_f32_e32 v37, v37
	v_add_f32_e32 v34, 1.0, v34
	v_add_f32_e32 v35, 1.0, v35
	v_add_f32_e32 v36, 1.0, v36
	v_add_f32_e32 v37, 1.0, v37
	v_rcp_f32_e32 v34, v34
	v_rcp_f32_e32 v35, v35
	v_rcp_f32_e32 v36, v36
	v_rcp_f32_e32 v37, v37
	v_cvt_pk_bf16_f32 v34, v34, v35
	v_cvt_pk_bf16_f32 v35, v36, v37
	v_or_b32_e32 v36, v38, v106
	v_ashrrev_i32_e32 v37, 31, v36
	v_lshlrev_b64 v[36:37], 11, v[36:37]
	v_lshl_add_u64 v[36:37], v[0:1], 0, v[36:37]
	flat_store_dwordx2 v[36:37], v[34:35]
	ds_read_b128 v[34:37], v98 offset:6528
	s_waitcnt lgkmcnt(0)
	v_mul_f32_e32 v34, 0xbfb8aa3b, v34
	v_mul_f32_e32 v35, 0xbfb8aa3b, v35
	v_mul_f32_e32 v36, 0xbfb8aa3b, v36
	v_mul_f32_e32 v37, 0xbfb8aa3b, v37
	v_exp_f32_e32 v34, v34
	v_exp_f32_e32 v35, v35
	v_exp_f32_e32 v36, v36
	v_exp_f32_e32 v37, v37
	v_add_f32_e32 v34, 1.0, v34
	v_add_f32_e32 v35, 1.0, v35
	v_add_f32_e32 v36, 1.0, v36
	v_add_f32_e32 v37, 1.0, v37
	v_rcp_f32_e32 v34, v34
	v_rcp_f32_e32 v35, v35
	v_rcp_f32_e32 v36, v36
	v_rcp_f32_e32 v37, v37
	v_cvt_pk_bf16_f32 v34, v34, v35
	v_cvt_pk_bf16_f32 v35, v36, v37
	v_or_b32_e32 v36, v38, v107
	v_ashrrev_i32_e32 v37, 31, v36
	v_lshlrev_b64 v[36:37], 11, v[36:37]
	v_lshl_add_u64 v[36:37], v[0:1], 0, v[36:37]
	flat_store_dwordx2 v[36:37], v[34:35]
	ds_read_b128 v[34:37], v98 offset:7616
	s_waitcnt lgkmcnt(0)
	v_mul_f32_e32 v34, 0xbfb8aa3b, v34
	v_mul_f32_e32 v35, 0xbfb8aa3b, v35
	v_mul_f32_e32 v36, 0xbfb8aa3b, v36
	v_mul_f32_e32 v37, 0xbfb8aa3b, v37
	v_exp_f32_e32 v34, v34
	v_exp_f32_e32 v35, v35
	v_exp_f32_e32 v36, v36
	v_exp_f32_e32 v37, v37
	v_add_f32_e32 v34, 1.0, v34
	v_add_f32_e32 v35, 1.0, v35
	v_add_f32_e32 v36, 1.0, v36
	v_add_f32_e32 v37, 1.0, v37
	v_rcp_f32_e32 v34, v34
	v_rcp_f32_e32 v35, v35
	v_rcp_f32_e32 v36, v36
	v_rcp_f32_e32 v37, v37
	v_cvt_pk_bf16_f32 v34, v34, v35
	v_cvt_pk_bf16_f32 v35, v36, v37
	v_or_b32_e32 v36, v38, v108
	v_ashrrev_i32_e32 v37, 31, v36
	v_lshlrev_b64 v[36:37], 11, v[36:37]
	v_lshl_add_u64 v[36:37], v[0:1], 0, v[36:37]
	flat_store_dwordx2 v[36:37], v[34:35]
	ds_write_b128 v101, v[2:5]
	ds_write_b128 v101, v[6:9] offset:64
	ds_write_b128 v101, v[10:13] offset:128
	ds_write_b128 v101, v[14:17] offset:192
	ds_write_b128 v101, v[18:21] offset:4352
	ds_write_b128 v101, v[22:25] offset:4416
	ds_write_b128 v101, v[26:29] offset:4480
	ds_write_b128 v101, v[30:33] offset:4544
	ds_read_b128 v[2:5], v98
	v_or_b32_e32 v6, 0x60, v100
	v_mov_b32_e32 v20, v132
	v_mov_b32_e32 v7, v131
	v_mov_b32_e32 v11, v131
	s_waitcnt lgkmcnt(0)
	v_mul_f32_e32 v2, 0xbfb8aa3b, v2
	v_mul_f32_e32 v3, 0xbfb8aa3b, v3
	v_mul_f32_e32 v4, 0xbfb8aa3b, v4
	v_mul_f32_e32 v5, 0xbfb8aa3b, v5
	v_exp_f32_e32 v2, v2
	v_exp_f32_e32 v3, v3
	v_exp_f32_e32 v4, v4
	v_exp_f32_e32 v5, v5
	v_add_f32_e32 v2, 1.0, v2
	v_add_f32_e32 v3, 1.0, v3
	v_add_f32_e32 v4, 1.0, v4
	v_add_f32_e32 v5, 1.0, v5
	v_rcp_f32_e32 v2, v2
	v_rcp_f32_e32 v3, v3
	v_rcp_f32_e32 v4, v4
	v_rcp_f32_e32 v5, v5
	v_mov_b32_e32 v19, v131
	v_cvt_pk_bf16_f32 v2, v2, v3
	v_cvt_pk_bf16_f32 v3, v4, v5
	v_or_b32_e32 v4, v6, v99
	v_ashrrev_i32_e32 v5, 31, v4
	v_lshlrev_b64 v[4:5], 11, v[4:5]
	v_lshl_add_u64 v[4:5], v[0:1], 0, v[4:5]
	flat_store_dwordx2 v[4:5], v[2:3]
	ds_read_b128 v[2:5], v98 offset:1088
	s_waitcnt lgkmcnt(0)
	v_mul_f32_e32 v2, 0xbfb8aa3b, v2
	v_mul_f32_e32 v3, 0xbfb8aa3b, v3
	v_mul_f32_e32 v4, 0xbfb8aa3b, v4
	v_mul_f32_e32 v5, 0xbfb8aa3b, v5
	v_exp_f32_e32 v2, v2
	v_exp_f32_e32 v3, v3
	v_exp_f32_e32 v4, v4
	v_exp_f32_e32 v5, v5
	v_add_f32_e32 v2, 1.0, v2
	v_add_f32_e32 v3, 1.0, v3
	v_add_f32_e32 v4, 1.0, v4
	v_add_f32_e32 v5, 1.0, v5
	v_rcp_f32_e32 v2, v2
	v_rcp_f32_e32 v3, v3
	v_rcp_f32_e32 v4, v4
	v_rcp_f32_e32 v5, v5
	v_cvt_pk_bf16_f32 v2, v2, v3
	v_cvt_pk_bf16_f32 v3, v4, v5
	v_or_b32_e32 v4, v6, v102
	v_ashrrev_i32_e32 v5, 31, v4
	v_lshlrev_b64 v[4:5], 11, v[4:5]
	v_lshl_add_u64 v[4:5], v[0:1], 0, v[4:5]
	flat_store_dwordx2 v[4:5], v[2:3]
	ds_read_b128 v[2:5], v98 offset:2176
	s_waitcnt lgkmcnt(0)
	v_mul_f32_e32 v2, 0xbfb8aa3b, v2
	v_mul_f32_e32 v3, 0xbfb8aa3b, v3
	v_mul_f32_e32 v4, 0xbfb8aa3b, v4
	v_mul_f32_e32 v5, 0xbfb8aa3b, v5
	v_exp_f32_e32 v2, v2
	v_exp_f32_e32 v3, v3
	v_exp_f32_e32 v4, v4
	v_exp_f32_e32 v5, v5
	v_add_f32_e32 v2, 1.0, v2
	v_add_f32_e32 v3, 1.0, v3
	v_add_f32_e32 v4, 1.0, v4
	v_add_f32_e32 v5, 1.0, v5
	v_rcp_f32_e32 v2, v2
	v_rcp_f32_e32 v3, v3
	v_rcp_f32_e32 v4, v4
	v_rcp_f32_e32 v5, v5
	v_cvt_pk_bf16_f32 v2, v2, v3
	v_cvt_pk_bf16_f32 v3, v4, v5
	v_or_b32_e32 v4, v6, v103
	v_ashrrev_i32_e32 v5, 31, v4
	v_lshlrev_b64 v[4:5], 11, v[4:5]
	v_lshl_add_u64 v[4:5], v[0:1], 0, v[4:5]
	flat_store_dwordx2 v[4:5], v[2:3]
	ds_read_b128 v[2:5], v98 offset:3264
	s_waitcnt lgkmcnt(0)
	v_mul_f32_e32 v2, 0xbfb8aa3b, v2
	v_mul_f32_e32 v3, 0xbfb8aa3b, v3
	v_mul_f32_e32 v4, 0xbfb8aa3b, v4
	v_mul_f32_e32 v5, 0xbfb8aa3b, v5
	v_exp_f32_e32 v2, v2
	v_exp_f32_e32 v3, v3
	v_exp_f32_e32 v4, v4
	v_exp_f32_e32 v5, v5
	v_add_f32_e32 v2, 1.0, v2
	v_add_f32_e32 v3, 1.0, v3
	v_add_f32_e32 v4, 1.0, v4
	v_add_f32_e32 v5, 1.0, v5
	v_rcp_f32_e32 v2, v2
	v_rcp_f32_e32 v3, v3
	v_rcp_f32_e32 v4, v4
	v_rcp_f32_e32 v5, v5
	v_cvt_pk_bf16_f32 v2, v2, v3
	v_cvt_pk_bf16_f32 v3, v4, v5
	v_or_b32_e32 v4, v6, v104
	v_ashrrev_i32_e32 v5, 31, v4
	v_lshlrev_b64 v[4:5], 11, v[4:5]
	v_lshl_add_u64 v[4:5], v[0:1], 0, v[4:5]
	flat_store_dwordx2 v[4:5], v[2:3]
	ds_read_b128 v[2:5], v98 offset:4352
	s_waitcnt lgkmcnt(0)
	v_mul_f32_e32 v2, 0xbfb8aa3b, v2
	v_mul_f32_e32 v3, 0xbfb8aa3b, v3
	v_mul_f32_e32 v4, 0xbfb8aa3b, v4
	v_mul_f32_e32 v5, 0xbfb8aa3b, v5
	v_exp_f32_e32 v2, v2
	v_exp_f32_e32 v3, v3
	v_exp_f32_e32 v4, v4
	v_exp_f32_e32 v5, v5
	v_add_f32_e32 v2, 1.0, v2
	v_add_f32_e32 v3, 1.0, v3
	v_add_f32_e32 v4, 1.0, v4
	v_add_f32_e32 v5, 1.0, v5
	v_rcp_f32_e32 v2, v2
	v_rcp_f32_e32 v3, v3
	v_rcp_f32_e32 v4, v4
	v_rcp_f32_e32 v5, v5
	v_cvt_pk_bf16_f32 v2, v2, v3
	v_cvt_pk_bf16_f32 v3, v4, v5
	v_or_b32_e32 v4, v6, v105
	v_ashrrev_i32_e32 v5, 31, v4
	v_lshlrev_b64 v[4:5], 11, v[4:5]
	v_lshl_add_u64 v[4:5], v[0:1], 0, v[4:5]
	flat_store_dwordx2 v[4:5], v[2:3]
	ds_read_b128 v[2:5], v98 offset:5440
	s_waitcnt lgkmcnt(0)
	v_mul_f32_e32 v2, 0xbfb8aa3b, v2
	v_mul_f32_e32 v3, 0xbfb8aa3b, v3
	v_mul_f32_e32 v4, 0xbfb8aa3b, v4
	v_mul_f32_e32 v5, 0xbfb8aa3b, v5
	v_exp_f32_e32 v2, v2
	v_exp_f32_e32 v3, v3
	v_exp_f32_e32 v4, v4
	v_exp_f32_e32 v5, v5
	v_add_f32_e32 v2, 1.0, v2
	v_add_f32_e32 v3, 1.0, v3
	v_add_f32_e32 v4, 1.0, v4
	v_add_f32_e32 v5, 1.0, v5
	v_rcp_f32_e32 v2, v2
	v_rcp_f32_e32 v3, v3
	v_rcp_f32_e32 v4, v4
	v_rcp_f32_e32 v5, v5
	v_cvt_pk_bf16_f32 v2, v2, v3
	v_cvt_pk_bf16_f32 v3, v4, v5
	v_or_b32_e32 v4, v6, v106
	v_ashrrev_i32_e32 v5, 31, v4
	v_lshlrev_b64 v[4:5], 11, v[4:5]
	v_lshl_add_u64 v[4:5], v[0:1], 0, v[4:5]
	flat_store_dwordx2 v[4:5], v[2:3]
	ds_read_b128 v[2:5], v98 offset:6528
	s_waitcnt lgkmcnt(0)
	v_mul_f32_e32 v2, 0xbfb8aa3b, v2
	v_mul_f32_e32 v3, 0xbfb8aa3b, v3
	v_mul_f32_e32 v4, 0xbfb8aa3b, v4
	v_mul_f32_e32 v5, 0xbfb8aa3b, v5
	v_exp_f32_e32 v2, v2
	v_exp_f32_e32 v3, v3
	v_exp_f32_e32 v4, v4
	v_exp_f32_e32 v5, v5
	v_add_f32_e32 v2, 1.0, v2
	v_add_f32_e32 v3, 1.0, v3
	v_add_f32_e32 v4, 1.0, v4
	v_add_f32_e32 v5, 1.0, v5
	v_rcp_f32_e32 v2, v2
	v_rcp_f32_e32 v3, v3
	v_rcp_f32_e32 v4, v4
	v_rcp_f32_e32 v5, v5
	v_cvt_pk_bf16_f32 v2, v2, v3
	v_cvt_pk_bf16_f32 v3, v4, v5
	v_or_b32_e32 v4, v6, v107
	v_ashrrev_i32_e32 v5, 31, v4
	v_lshlrev_b64 v[4:5], 11, v[4:5]
	v_lshl_add_u64 v[4:5], v[0:1], 0, v[4:5]
	flat_store_dwordx2 v[4:5], v[2:3]
	ds_read_b128 v[2:5], v98 offset:7616
	v_mov_b32_e32 v98, v132
	s_waitcnt lgkmcnt(0)
	v_mul_f32_e32 v2, 0xbfb8aa3b, v2
	v_mul_f32_e32 v3, 0xbfb8aa3b, v3
	v_mul_f32_e32 v4, 0xbfb8aa3b, v4
	v_mul_f32_e32 v5, 0xbfb8aa3b, v5
	v_exp_f32_e32 v2, v2
	v_exp_f32_e32 v3, v3
	v_exp_f32_e32 v4, v4
	v_exp_f32_e32 v5, v5
	v_add_f32_e32 v2, 1.0, v2
	v_add_f32_e32 v3, 1.0, v3
	v_add_f32_e32 v4, 1.0, v4
	v_add_f32_e32 v5, 1.0, v5
	v_rcp_f32_e32 v2, v2
	v_rcp_f32_e32 v3, v3
	v_rcp_f32_e32 v4, v4
	v_rcp_f32_e32 v5, v5
	v_cvt_pk_bf16_f32 v2, v2, v3
	v_cvt_pk_bf16_f32 v3, v4, v5
	v_or_b32_e32 v4, v6, v108
	v_ashrrev_i32_e32 v5, 31, v4
	v_lshlrev_b64 v[4:5], 11, v[4:5]
	v_lshl_add_u64 v[0:1], v[0:1], 0, v[4:5]
	flat_store_dwordx2 v[0:1], v[2:3]
	v_mov_b32_e32 v0, s3
	ds_read_b128 v[0:3], v0
	s_waitcnt lgkmcnt(0)
	v_lshl_add_u64 v[4:5], v[2:3], 0, s[42:43]
	s_lshl_b64 s[42:43], s[30:31], 10
	v_lshl_add_u64 v[2:3], v[2:3], 0, s[42:43]
	v_lshl_add_u64 v[16:17], v[2:3], 0, s[12:13]
	v_lshlrev_b32_e32 v2, 4, v20
	v_and_b32_e32 v3, 32, v20
	v_bitop3_b32 v3, v2, v3, 48 bitop3:0x6c
	v_lshl_add_u64 v[14:15], v[4:5], 0, s[10:11]
	v_lshrrev_b32_e32 v5, 1, v20
	v_lshrrev_b32_e32 v3, 1, v3
	v_bfe_u32 v4, v20, 2, 4
	v_and_or_b32 v3, v5, 32, v3
	v_lshrrev_b32_e32 v5, 3, v20
	v_and_or_b32 v5, v5, s50, v4
	v_lshl_or_b32 v130, v5, 9, v3
	v_add_u32_e32 v5, 0x2000, v2
	v_lshrrev_b32_e32 v5, 7, v5
	v_and_or_b32 v5, v5, s50, v4
	v_lshl_or_b32 v6, v5, 9, v3
	v_add_u32_e32 v5, 0x4000, v2
	v_and_b32_e32 v21, 0xfffffc00, v2
	v_lshrrev_b32_e32 v5, 7, v5
	v_add_u32_e32 v2, 0x6000, v2
	v_and_or_b32 v5, v5, s50, v4
	v_lshrrev_b32_e32 v2, 7, v2
	v_add_u32_e32 v45, 0, v21
	v_lshl_or_b32 v10, v5, 9, v3
	v_and_or_b32 v2, v2, s50, v4
	v_add_u32_e32 v44, 0x8000, v45
	v_lshlrev_b64 v[4:5], 1, v[130:131]
	v_readfirstlane_b32 s60, v45
	v_lshl_or_b32 v18, v2, 9, v3
	v_lshl_add_u64 v[2:3], v[14:15], 0, v[4:5]
	s_mov_b32 m0, s60
	v_readfirstlane_b32 s58, v44
	v_add_u32_e32 v46, 0x2000, v45
	global_load_lds_dwordx4 v[2:3], off
	v_lshl_add_u64 v[4:5], v[16:17], 0, v[4:5]
	s_mov_b32 m0, s58
	v_lshlrev_b64 v[8:9], 1, v[6:7]
	v_readfirstlane_b32 s59, v46
	v_add_u32_e32 v47, 0xa000, v45
	global_load_lds_dwordx4 v[4:5], off
	v_lshl_add_u64 v[6:7], v[14:15], 0, v[8:9]
	s_mov_b32 m0, s59
	v_readfirstlane_b32 s61, v47
	v_add_u32_e32 v48, 0x4000, v45
	global_load_lds_dwordx4 v[6:7], off
	v_lshl_add_u64 v[8:9], v[16:17], 0, v[8:9]
	s_mov_b32 m0, s61
	v_lshlrev_b64 v[12:13], 1, v[10:11]
	v_readfirstlane_b32 s62, v48
	v_add_u32_e32 v49, 0xc000, v45
	v_lshlrev_b64 v[18:19], 1, v[18:19]
	v_and_b32_e32 v22, 15, v20
	global_load_lds_dwordx4 v[8:9], off
	v_lshl_add_u64 v[10:11], v[14:15], 0, v[12:13]
	s_mov_b32 m0, s62
	v_lshl_add_u64 v[12:13], v[16:17], 0, v[12:13]
	v_readfirstlane_b32 s63, v49
	v_lshl_add_u64 v[14:15], v[14:15], 0, v[18:19]
	v_add_u32_e32 v50, 0x6000, v45
	v_lshl_add_u64 v[16:17], v[16:17], 0, v[18:19]
	v_lshlrev_b32_e32 v19, 2, v20
	global_load_lds_dwordx4 v[10:11], off
	s_mov_b32 m0, s63
	v_readfirstlane_b32 s64, v50
	v_add_u32_e32 v51, 0xe000, v45
	v_and_b32_e32 v23, 48, v20
	v_lshlrev_b32_e32 v18, 6, v22
	v_and_b32_e32 v22, 32, v19
	global_load_lds_dwordx4 v[12:13], off
	s_mov_b32 m0, s64
	v_readfirstlane_b32 s65, v51
	v_bitop3_b32 v96, v18, v22, v23 bitop3:0x36
	v_lshlrev_b32_e32 v18, 7, v20
	v_add_u32_e32 v37, s46, v21
	global_load_lds_dwordx4 v[14:15], off
	s_mov_b32 m0, s65
	v_and_b32_e32 v97, 0x6000, v18
	v_lshlrev_b32_e32 v18, 6, v20
	v_add_u32_e32 v36, s47, v21
	v_readfirstlane_b32 s53, v37
	global_load_lds_dwordx4 v[16:17], off
	v_and_b32_e32 v99, 0xffffc000, v18
	v_and_b32_e32 v20, 0x3c0, v18
	v_lshl_add_u64 v[18:19], v[2:3], 0, s[6:7]
	s_mov_b32 m0, s53
	v_readfirstlane_b32 s0, v36
	v_add_u32_e32 v38, 0x2000, v37
	s_waitcnt vmcnt(0)
	s_waitcnt vmcnt(0) lgkmcnt(0)
	s_barrier
	global_load_lds_dwordx4 v[18:19], off
	v_lshl_add_u64 v[18:19], v[4:5], 0, s[6:7]
	s_mov_b32 m0, s0
	v_readfirstlane_b32 s42, v38
	v_add_u32_e32 v39, 0x2000, v36
	global_load_lds_dwordx4 v[18:19], off
	v_lshl_add_u64 v[18:19], v[6:7], 0, s[6:7]
	s_mov_b32 m0, s42
	v_readfirstlane_b32 s43, v39
	v_add_u32_e32 v40, 0x4000, v37
	global_load_lds_dwordx4 v[18:19], off
	v_lshl_add_u64 v[18:19], v[8:9], 0, s[6:7]
	s_mov_b32 m0, s43
	v_readfirstlane_b32 s54, v40
	v_add_u32_e32 v41, 0x4000, v36
	global_load_lds_dwordx4 v[18:19], off
	v_lshl_add_u64 v[18:19], v[10:11], 0, s[6:7]
	s_mov_b32 m0, s54
	v_readfirstlane_b32 s55, v41
	v_add_u32_e32 v42, 0x6000, v37
	global_load_lds_dwordx4 v[18:19], off
	v_lshl_add_u64 v[18:19], v[12:13], 0, s[6:7]
	s_mov_b32 m0, s55
	v_readfirstlane_b32 s56, v42
	v_add_u32_e32 v43, 0x6000, v36
	global_load_lds_dwordx4 v[18:19], off
	v_lshl_add_u64 v[18:19], v[14:15], 0, s[6:7]
	s_mov_b32 m0, s56
	v_readfirstlane_b32 s57, v43
	global_load_lds_dwordx4 v[18:19], off
	v_lshl_add_u64 v[18:19], v[16:17], 0, s[6:7]
	s_mov_b32 m0, s57
	v_add_u32_e32 v129, 0, v96
	global_load_lds_dwordx4 v[18:19], off
	v_add_u32_e32 v18, v129, v97
	ds_read_b128 v[24:27], v18 offset:32768
	ds_read_b128 v[56:59], v18 offset:34816
	ds_read_b128 v[64:67], v18 offset:36864
	ds_read_b128 v[72:75], v18 offset:38912
	v_bitop3_b32 v130, v20, v22, v23 bitop3:0x36
	v_add_u32_e32 v23, 0, v130
	v_or_b32_e32 v222, 0x3000, v99
	v_add_u32_e32 v20, v23, v222
	ds_read_b128 v[32:35], v20
	v_or_b32_e32 v223, 0x2800, v99
	v_add_u32_e32 v21, v23, v223
	s_waitcnt lgkmcnt(0)
	v_mfma_f32_16x16x32_bf16 v[76:79], v[24:27], v[32:35], 0
	v_or_b32_e32 v128, 0x3800, v99
	v_or_b32_e32 v218, 0x2000, v99
	v_or_b32_e32 v219, 0x1000, v99
	v_mfma_f32_16x16x32_bf16 v[80:83], v[56:59], v[32:35], 0
	v_or_b32_e32 v220, 0x1800, v99
	v_add_u32_e32 v19, v23, v128
	v_add_u32_e32 v22, v23, v218
	v_mfma_f32_16x16x32_bf16 v[84:87], v[64:67], v[32:35], 0
	ds_read_b128 v[28:31], v19
	ds_read_b128 v[112:115], v22
	v_mfma_f32_16x16x32_bf16 v[88:91], v[72:75], v[32:35], 0
	ds_read_b128 v[32:35], v21
	s_waitcnt lgkmcnt(0)
	v_mfma_f32_16x16x32_bf16 v[92:95], v[24:27], v[32:35], 0
	v_mfma_f32_16x16x32_bf16 v[100:103], v[56:59], v[32:35], 0
	v_mfma_f32_16x16x32_bf16 v[104:107], v[64:67], v[32:35], 0
	v_mfma_f32_16x16x32_bf16 v[108:111], v[72:75], v[32:35], 0
	v_add_u32_e32 v32, v129, v99
	v_or_b32_e32 v129, 0x800, v99
	v_add_u32_e32 v33, v23, v129
	v_add_u32_e32 v34, v23, v219
	v_add_u32_e32 v35, v23, v220
	ds_read_b128 v[134:137], v32
	ds_read_b128 v[150:153], v33
	ds_read_b128 v[166:169], v34
	ds_read_b128 v[182:185], v35
	s_waitcnt lgkmcnt(0)
	v_mfma_f32_16x16x32_bf16 v[178:181], v[64:67], v[166:169], 0
	v_mfma_f32_16x16x32_bf16 v[162:165], v[64:67], v[150:153], 0
	v_mfma_f32_16x16x32_bf16 v[146:149], v[64:67], v[134:137], 0
	v_mfma_f32_16x16x32_bf16 v[68:71], v[64:67], v[28:31], 0
	v_mfma_f32_16x16x32_bf16 v[124:127], v[64:67], v[112:115], 0
	v_mfma_f32_16x16x32_bf16 v[64:67], v[64:67], v[182:185], 0
	v_mfma_f32_16x16x32_bf16 v[174:177], v[56:59], v[166:169], 0
	v_mfma_f32_16x16x32_bf16 v[158:161], v[56:59], v[150:153], 0
	v_mfma_f32_16x16x32_bf16 v[142:145], v[56:59], v[134:137], 0
	v_mfma_f32_16x16x32_bf16 v[60:63], v[56:59], v[28:31], 0
	v_mfma_f32_16x16x32_bf16 v[120:123], v[56:59], v[112:115], 0
	v_mfma_f32_16x16x32_bf16 v[56:59], v[56:59], v[182:185], 0
	v_mfma_f32_16x16x32_bf16 v[170:173], v[24:27], v[166:169], 0
	v_mfma_f32_16x16x32_bf16 v[154:157], v[24:27], v[150:153], 0
	v_mfma_f32_16x16x32_bf16 v[138:141], v[24:27], v[134:137], 0
	v_mfma_f32_16x16x32_bf16 v[52:55], v[24:27], v[28:31], 0
	v_mfma_f32_16x16x32_bf16 v[116:119], v[24:27], v[112:115], 0
	v_mfma_f32_16x16x32_bf16 v[24:27], v[24:27], v[182:185], 0
	v_mfma_f32_16x16x32_bf16 v[166:169], v[72:75], v[166:169], 0
	v_mfma_f32_16x16x32_bf16 v[150:153], v[72:75], v[150:153], 0
	v_mfma_f32_16x16x32_bf16 v[134:137], v[72:75], v[134:137], 0
	v_mfma_f32_16x16x32_bf16 v[28:31], v[72:75], v[28:31], 0
	v_mfma_f32_16x16x32_bf16 v[112:115], v[72:75], v[112:115], 0
	v_mfma_f32_16x16x32_bf16 v[72:75], v[72:75], v[182:185], 0
	ds_read_b128 v[182:185], v18 offset:33792
	ds_read_b128 v[186:189], v18 offset:35840
	ds_read_b128 v[190:193], v18 offset:37888
	ds_read_b128 v[198:201], v18 offset:39936
	ds_read_b128 v[194:197], v32 offset:1024
	ds_read_b128 v[202:205], v33 offset:1024
	ds_read_b128 v[206:209], v34 offset:1024
	ds_read_b128 v[210:213], v35 offset:1024
	s_waitcnt lgkmcnt(0)
	v_mfma_f32_16x16x32_bf16 v[138:141], v[182:185], v[194:197], v[138:141]
	v_mfma_f32_16x16x32_bf16 v[142:145], v[186:189], v[194:197], v[142:145]
	v_mfma_f32_16x16x32_bf16 v[146:149], v[190:193], v[194:197], v[146:149]
	v_mfma_f32_16x16x32_bf16 v[134:137], v[198:201], v[194:197], v[134:137]
	ds_read_b128 v[194:197], v22 offset:1024
	v_mfma_f32_16x16x32_bf16 v[154:157], v[182:185], v[202:205], v[154:157]
	v_mfma_f32_16x16x32_bf16 v[158:161], v[186:189], v[202:205], v[158:161]
	v_mfma_f32_16x16x32_bf16 v[162:165], v[190:193], v[202:205], v[162:165]
	v_mfma_f32_16x16x32_bf16 v[150:153], v[198:201], v[202:205], v[150:153]
	ds_read_b128 v[202:205], v21 offset:1024
	v_mfma_f32_16x16x32_bf16 v[170:173], v[182:185], v[206:209], v[170:173]
	v_mfma_f32_16x16x32_bf16 v[174:177], v[186:189], v[206:209], v[174:177]
	v_mfma_f32_16x16x32_bf16 v[178:181], v[190:193], v[206:209], v[178:181]
	v_mfma_f32_16x16x32_bf16 v[166:169], v[198:201], v[206:209], v[166:169]
	ds_read_b128 v[206:209], v20 offset:1024
	v_mfma_f32_16x16x32_bf16 v[214:217], v[182:185], v[210:213], v[24:27]
	v_mfma_f32_16x16x32_bf16 v[56:59], v[186:189], v[210:213], v[56:59]
	v_mfma_f32_16x16x32_bf16 v[64:67], v[190:193], v[210:213], v[64:67]
	v_mfma_f32_16x16x32_bf16 v[72:75], v[198:201], v[210:213], v[72:75]
	ds_read_b128 v[24:27], v19 offset:1024
	s_waitcnt lgkmcnt(0)
	v_mfma_f32_16x16x32_bf16 v[116:119], v[182:185], v[194:197], v[116:119]
	v_mfma_f32_16x16x32_bf16 v[120:123], v[186:189], v[194:197], v[120:123]
	v_mfma_f32_16x16x32_bf16 v[124:127], v[190:193], v[194:197], v[124:127]
	v_mfma_f32_16x16x32_bf16 v[112:115], v[198:201], v[194:197], v[112:115]
	v_mfma_f32_16x16x32_bf16 v[92:95], v[182:185], v[202:205], v[92:95]
	v_mfma_f32_16x16x32_bf16 v[100:103], v[186:189], v[202:205], v[100:103]
	v_mfma_f32_16x16x32_bf16 v[104:107], v[190:193], v[202:205], v[104:107]
	v_mfma_f32_16x16x32_bf16 v[108:111], v[198:201], v[202:205], v[108:111]
	v_mfma_f32_16x16x32_bf16 v[76:79], v[182:185], v[206:209], v[76:79]
	v_mfma_f32_16x16x32_bf16 v[80:83], v[186:189], v[206:209], v[80:83]
	v_mfma_f32_16x16x32_bf16 v[84:87], v[190:193], v[206:209], v[84:87]
	v_mfma_f32_16x16x32_bf16 v[88:91], v[198:201], v[206:209], v[88:91]
	v_mfma_f32_16x16x32_bf16 v[52:55], v[182:185], v[24:27], v[52:55]
	v_mfma_f32_16x16x32_bf16 v[60:63], v[186:189], v[24:27], v[60:63]
	v_mfma_f32_16x16x32_bf16 v[68:71], v[190:193], v[24:27], v[68:71]
	v_mfma_f32_16x16x32_bf16 v[182:185], v[198:201], v[24:27], v[28:31]
	s_mov_b32 m0, s60
	v_lshl_add_u64 v[24:25], v[2:3], 0, s[14:15]
	s_waitcnt vmcnt(0)
	s_waitcnt vmcnt(0)
	s_barrier
	global_load_lds_dwordx4 v[24:25], off
	v_lshl_add_u64 v[24:25], v[4:5], 0, s[14:15]
	s_mov_b32 m0, s58
	v_add3_u32 v23, s47, v96, v97
	global_load_lds_dwordx4 v[24:25], off
	v_lshl_add_u64 v[24:25], v[6:7], 0, s[14:15]
	s_mov_b32 m0, s59
	s_nop 0
	global_load_lds_dwordx4 v[24:25], off
	v_lshl_add_u64 v[24:25], v[8:9], 0, s[14:15]
	s_mov_b32 m0, s61
	s_nop 0
	global_load_lds_dwordx4 v[24:25], off
	v_lshl_add_u64 v[24:25], v[10:11], 0, s[14:15]
	s_mov_b32 m0, s62
	s_nop 0
	global_load_lds_dwordx4 v[24:25], off
	v_lshl_add_u64 v[24:25], v[12:13], 0, s[14:15]
	s_mov_b32 m0, s63
	s_nop 0
	global_load_lds_dwordx4 v[24:25], off
	v_lshl_add_u64 v[24:25], v[14:15], 0, s[14:15]
	s_mov_b32 m0, s64
	s_nop 0
	global_load_lds_dwordx4 v[24:25], off
	v_lshl_add_u64 v[24:25], v[16:17], 0, s[14:15]
	s_mov_b32 m0, s65
	s_nop 0
	global_load_lds_dwordx4 v[24:25], off
	ds_read_b128 v[186:189], v23
	ds_read_b128 v[190:193], v23 offset:2048
	ds_read_b128 v[194:197], v23 offset:4096
	ds_read_b128 v[198:201], v23 offset:6144
	v_add3_u32 v24, s46, v96, v99
	v_add_u32_e32 v96, s46, v130
	ds_read_b128 v[28:31], v24
	v_add_u32_e32 v25, v96, v129
	v_add_u32_e32 v26, v96, v219
	v_add_u32_e32 v27, v96, v220
	ds_read_b128 v[202:205], v25
	ds_read_b128 v[206:209], v26
	ds_read_b128 v[210:213], v27
	s_waitcnt lgkmcnt(0)
	v_mfma_f32_16x16x32_bf16 v[138:141], v[186:189], v[28:31], v[138:141]
	v_mfma_f32_16x16x32_bf16 v[142:145], v[190:193], v[28:31], v[142:145]
	v_mfma_f32_16x16x32_bf16 v[146:149], v[194:197], v[28:31], v[146:149]
	v_mfma_f32_16x16x32_bf16 v[134:137], v[198:201], v[28:31], v[134:137]
	v_add_u32_e32 v28, v96, v218
	v_add_u32_e32 v29, v96, v223
	v_add_u32_e32 v30, v96, v222
	v_add_u32_e32 v31, v96, v128
	ds_read_b128 v[218:221], v28
	v_mfma_f32_16x16x32_bf16 v[154:157], v[186:189], v[202:205], v[154:157]
	v_mfma_f32_16x16x32_bf16 v[158:161], v[190:193], v[202:205], v[158:161]
	v_mfma_f32_16x16x32_bf16 v[162:165], v[194:197], v[202:205], v[162:165]
	v_mfma_f32_16x16x32_bf16 v[150:153], v[198:201], v[202:205], v[150:153]
	ds_read_b128 v[202:205], v29
	v_mfma_f32_16x16x32_bf16 v[170:173], v[186:189], v[206:209], v[170:173]
	v_mfma_f32_16x16x32_bf16 v[174:177], v[190:193], v[206:209], v[174:177]
	v_mfma_f32_16x16x32_bf16 v[178:181], v[194:197], v[206:209], v[178:181]
	v_mfma_f32_16x16x32_bf16 v[166:169], v[198:201], v[206:209], v[166:169]
	ds_read_b128 v[206:209], v30
	v_mfma_f32_16x16x32_bf16 v[214:217], v[186:189], v[210:213], v[214:217]
	v_mfma_f32_16x16x32_bf16 v[56:59], v[190:193], v[210:213], v[56:59]
	v_mfma_f32_16x16x32_bf16 v[64:67], v[194:197], v[210:213], v[64:67]
	v_mfma_f32_16x16x32_bf16 v[72:75], v[198:201], v[210:213], v[72:75]
	ds_read_b128 v[210:213], v31
	s_waitcnt lgkmcnt(0)
	v_mfma_f32_16x16x32_bf16 v[116:119], v[186:189], v[218:221], v[116:119]
	v_mfma_f32_16x16x32_bf16 v[120:123], v[190:193], v[218:221], v[120:123]
	v_mfma_f32_16x16x32_bf16 v[124:127], v[194:197], v[218:221], v[124:127]
	v_mfma_f32_16x16x32_bf16 v[112:115], v[198:201], v[218:221], v[112:115]
	v_mfma_f32_16x16x32_bf16 v[92:95], v[186:189], v[202:205], v[92:95]
	v_mfma_f32_16x16x32_bf16 v[100:103], v[190:193], v[202:205], v[100:103]
	v_mfma_f32_16x16x32_bf16 v[104:107], v[194:197], v[202:205], v[104:107]
	v_mfma_f32_16x16x32_bf16 v[108:111], v[198:201], v[202:205], v[108:111]
	v_mfma_f32_16x16x32_bf16 v[76:79], v[186:189], v[206:209], v[76:79]
	v_mfma_f32_16x16x32_bf16 v[80:83], v[190:193], v[206:209], v[80:83]
	v_mfma_f32_16x16x32_bf16 v[84:87], v[194:197], v[206:209], v[84:87]
	v_mfma_f32_16x16x32_bf16 v[88:91], v[198:201], v[206:209], v[88:91]
	v_mfma_f32_16x16x32_bf16 v[52:55], v[186:189], v[210:213], v[52:55]
	v_mfma_f32_16x16x32_bf16 v[60:63], v[190:193], v[210:213], v[60:63]
	v_mfma_f32_16x16x32_bf16 v[68:71], v[194:197], v[210:213], v[68:71]
	v_mfma_f32_16x16x32_bf16 v[182:185], v[198:201], v[210:213], v[182:185]
	ds_read_b128 v[186:189], v23 offset:1024
	ds_read_b128 v[190:193], v23 offset:3072
	ds_read_b128 v[194:197], v23 offset:5120
	ds_read_b128 v[202:205], v23 offset:7168
	ds_read_b128 v[198:201], v24 offset:1024
	ds_read_b128 v[206:209], v25 offset:1024
	ds_read_b128 v[210:213], v26 offset:1024
	ds_read_b128 v[218:221], v27 offset:1024
	s_waitcnt lgkmcnt(0)
	v_mfma_f32_16x16x32_bf16 v[138:141], v[186:189], v[198:201], v[138:141]
	v_mfma_f32_16x16x32_bf16 v[142:145], v[190:193], v[198:201], v[142:145]
	v_mfma_f32_16x16x32_bf16 v[146:149], v[194:197], v[198:201], v[146:149]
	v_mfma_f32_16x16x32_bf16 v[134:137], v[202:205], v[198:201], v[134:137]
	ds_read_b128 v[198:201], v28 offset:1024
	v_mfma_f32_16x16x32_bf16 v[154:157], v[186:189], v[206:209], v[154:157]
	v_mfma_f32_16x16x32_bf16 v[158:161], v[190:193], v[206:209], v[158:161]
	v_mfma_f32_16x16x32_bf16 v[162:165], v[194:197], v[206:209], v[162:165]
	v_mfma_f32_16x16x32_bf16 v[150:153], v[202:205], v[206:209], v[150:153]
	ds_read_b128 v[206:209], v29 offset:1024
	v_mfma_f32_16x16x32_bf16 v[170:173], v[186:189], v[210:213], v[170:173]
	v_mfma_f32_16x16x32_bf16 v[174:177], v[190:193], v[210:213], v[174:177]
	v_mfma_f32_16x16x32_bf16 v[178:181], v[194:197], v[210:213], v[178:181]
	v_mfma_f32_16x16x32_bf16 v[166:169], v[202:205], v[210:213], v[166:169]
	ds_read_b128 v[210:213], v30 offset:1024
	v_mfma_f32_16x16x32_bf16 v[214:217], v[186:189], v[218:221], v[214:217]
	v_mfma_f32_16x16x32_bf16 v[56:59], v[190:193], v[218:221], v[56:59]
	v_mfma_f32_16x16x32_bf16 v[64:67], v[194:197], v[218:221], v[64:67]
	v_mfma_f32_16x16x32_bf16 v[72:75], v[202:205], v[218:221], v[72:75]
	ds_read_b128 v[218:221], v31 offset:1024
	s_waitcnt lgkmcnt(0)
	v_mfma_f32_16x16x32_bf16 v[116:119], v[186:189], v[198:201], v[116:119]
	v_mfma_f32_16x16x32_bf16 v[120:123], v[190:193], v[198:201], v[120:123]
	v_mfma_f32_16x16x32_bf16 v[124:127], v[194:197], v[198:201], v[124:127]
	v_mfma_f32_16x16x32_bf16 v[112:115], v[202:205], v[198:201], v[112:115]
	v_mfma_f32_16x16x32_bf16 v[92:95], v[186:189], v[206:209], v[92:95]
	v_mfma_f32_16x16x32_bf16 v[100:103], v[190:193], v[206:209], v[100:103]
	v_mfma_f32_16x16x32_bf16 v[104:107], v[194:197], v[206:209], v[104:107]
	v_mfma_f32_16x16x32_bf16 v[108:111], v[202:205], v[206:209], v[108:111]
	v_mfma_f32_16x16x32_bf16 v[76:79], v[186:189], v[210:213], v[76:79]
	v_mfma_f32_16x16x32_bf16 v[80:83], v[190:193], v[210:213], v[80:83]
	v_mfma_f32_16x16x32_bf16 v[84:87], v[194:197], v[210:213], v[84:87]
	v_mfma_f32_16x16x32_bf16 v[88:91], v[202:205], v[210:213], v[88:91]
	v_mfma_f32_16x16x32_bf16 v[52:55], v[186:189], v[218:221], v[52:55]
	v_mfma_f32_16x16x32_bf16 v[60:63], v[190:193], v[218:221], v[60:63]
	v_mfma_f32_16x16x32_bf16 v[68:71], v[194:197], v[218:221], v[68:71]
	v_mfma_f32_16x16x32_bf16 v[182:185], v[202:205], v[218:221], v[182:185]
	s_mov_b32 m0, s53
	v_lshl_add_u64 v[96:97], v[2:3], 0, s[16:17]
	s_waitcnt vmcnt(0)
	s_waitcnt vmcnt(0)
	s_barrier
	global_load_lds_dwordx4 v[96:97], off
	v_lshl_add_u64 v[96:97], v[4:5], 0, s[16:17]
	s_mov_b32 m0, s0
	s_nop 0
	global_load_lds_dwordx4 v[96:97], off
	v_lshl_add_u64 v[96:97], v[6:7], 0, s[16:17]
	s_mov_b32 m0, s42
	s_nop 0
	global_load_lds_dwordx4 v[96:97], off
	v_lshl_add_u64 v[96:97], v[8:9], 0, s[16:17]
	s_mov_b32 m0, s43
	s_nop 0
	global_load_lds_dwordx4 v[96:97], off
	v_lshl_add_u64 v[96:97], v[10:11], 0, s[16:17]
	s_mov_b32 m0, s54
	s_nop 0
	global_load_lds_dwordx4 v[96:97], off
	v_lshl_add_u64 v[96:97], v[12:13], 0, s[16:17]
	s_mov_b32 m0, s55
	s_nop 0
	global_load_lds_dwordx4 v[96:97], off
	v_lshl_add_u64 v[96:97], v[14:15], 0, s[16:17]
	s_mov_b32 m0, s56
	s_nop 0
	global_load_lds_dwordx4 v[96:97], off
	v_lshl_add_u64 v[96:97], v[16:17], 0, s[16:17]
	s_mov_b32 m0, s57
	s_nop 0
	global_load_lds_dwordx4 v[96:97], off
	ds_read_b128 v[186:189], v18 offset:32768
	ds_read_b128 v[190:193], v18 offset:34816
	ds_read_b128 v[194:197], v18 offset:36864
	ds_read_b128 v[202:205], v18 offset:38912
	ds_read_b128 v[198:201], v32
	ds_read_b128 v[206:209], v33
	ds_read_b128 v[210:213], v34
	ds_read_b128 v[218:221], v35
	s_waitcnt lgkmcnt(0)
	v_mfma_f32_16x16x32_bf16 v[138:141], v[186:189], v[198:201], v[138:141]
	v_mfma_f32_16x16x32_bf16 v[142:145], v[190:193], v[198:201], v[142:145]
	v_mfma_f32_16x16x32_bf16 v[146:149], v[194:197], v[198:201], v[146:149]
	v_mfma_f32_16x16x32_bf16 v[134:137], v[202:205], v[198:201], v[134:137]
	ds_read_b128 v[198:201], v22
	v_mfma_f32_16x16x32_bf16 v[154:157], v[186:189], v[206:209], v[154:157]
	v_mfma_f32_16x16x32_bf16 v[158:161], v[190:193], v[206:209], v[158:161]
	v_mfma_f32_16x16x32_bf16 v[162:165], v[194:197], v[206:209], v[162:165]
	v_mfma_f32_16x16x32_bf16 v[150:153], v[202:205], v[206:209], v[150:153]
	ds_read_b128 v[206:209], v21
	v_mfma_f32_16x16x32_bf16 v[170:173], v[186:189], v[210:213], v[170:173]
	v_mfma_f32_16x16x32_bf16 v[174:177], v[190:193], v[210:213], v[174:177]
	v_mfma_f32_16x16x32_bf16 v[178:181], v[194:197], v[210:213], v[178:181]
	v_mfma_f32_16x16x32_bf16 v[166:169], v[202:205], v[210:213], v[166:169]
	ds_read_b128 v[210:213], v20
	v_mfma_f32_16x16x32_bf16 v[214:217], v[186:189], v[218:221], v[214:217]
	v_mfma_f32_16x16x32_bf16 v[56:59], v[190:193], v[218:221], v[56:59]
	v_mfma_f32_16x16x32_bf16 v[64:67], v[194:197], v[218:221], v[64:67]
	v_mfma_f32_16x16x32_bf16 v[72:75], v[202:205], v[218:221], v[72:75]
	ds_read_b128 v[218:221], v19
	s_waitcnt lgkmcnt(0)
	v_mfma_f32_16x16x32_bf16 v[116:119], v[186:189], v[198:201], v[116:119]
	v_mfma_f32_16x16x32_bf16 v[120:123], v[190:193], v[198:201], v[120:123]
	v_mfma_f32_16x16x32_bf16 v[124:127], v[194:197], v[198:201], v[124:127]
	v_mfma_f32_16x16x32_bf16 v[112:115], v[202:205], v[198:201], v[112:115]
	v_mfma_f32_16x16x32_bf16 v[92:95], v[186:189], v[206:209], v[92:95]
	v_mfma_f32_16x16x32_bf16 v[100:103], v[190:193], v[206:209], v[100:103]
	v_mfma_f32_16x16x32_bf16 v[104:107], v[194:197], v[206:209], v[104:107]
	v_mfma_f32_16x16x32_bf16 v[108:111], v[202:205], v[206:209], v[108:111]
	v_mfma_f32_16x16x32_bf16 v[76:79], v[186:189], v[210:213], v[76:79]
	v_mfma_f32_16x16x32_bf16 v[80:83], v[190:193], v[210:213], v[80:83]
	v_mfma_f32_16x16x32_bf16 v[84:87], v[194:197], v[210:213], v[84:87]
	v_mfma_f32_16x16x32_bf16 v[88:91], v[202:205], v[210:213], v[88:91]
	v_mfma_f32_16x16x32_bf16 v[52:55], v[186:189], v[218:221], v[52:55]
	v_mfma_f32_16x16x32_bf16 v[60:63], v[190:193], v[218:221], v[60:63]
	v_mfma_f32_16x16x32_bf16 v[68:71], v[194:197], v[218:221], v[68:71]
	v_mfma_f32_16x16x32_bf16 v[182:185], v[202:205], v[218:221], v[182:185]
	ds_read_b128 v[186:189], v18 offset:33792
	ds_read_b128 v[190:193], v18 offset:35840
	ds_read_b128 v[194:197], v18 offset:37888
	ds_read_b128 v[202:205], v18 offset:39936
	ds_read_b128 v[198:201], v32 offset:1024
	ds_read_b128 v[206:209], v33 offset:1024
	ds_read_b128 v[210:213], v34 offset:1024
	ds_read_b128 v[218:221], v35 offset:1024
	s_waitcnt lgkmcnt(0)
	v_mfma_f32_16x16x32_bf16 v[138:141], v[186:189], v[198:201], v[138:141]
	v_mfma_f32_16x16x32_bf16 v[142:145], v[190:193], v[198:201], v[142:145]
	v_mfma_f32_16x16x32_bf16 v[146:149], v[194:197], v[198:201], v[146:149]
	v_mfma_f32_16x16x32_bf16 v[134:137], v[202:205], v[198:201], v[134:137]
	ds_read_b128 v[198:201], v22 offset:1024
	v_mfma_f32_16x16x32_bf16 v[154:157], v[186:189], v[206:209], v[154:157]
	v_mfma_f32_16x16x32_bf16 v[158:161], v[190:193], v[206:209], v[158:161]
	v_mfma_f32_16x16x32_bf16 v[162:165], v[194:197], v[206:209], v[162:165]
	v_mfma_f32_16x16x32_bf16 v[150:153], v[202:205], v[206:209], v[150:153]
	ds_read_b128 v[206:209], v21 offset:1024
	v_mfma_f32_16x16x32_bf16 v[170:173], v[186:189], v[210:213], v[170:173]
	v_mfma_f32_16x16x32_bf16 v[174:177], v[190:193], v[210:213], v[174:177]
	v_mfma_f32_16x16x32_bf16 v[178:181], v[194:197], v[210:213], v[178:181]
	v_mfma_f32_16x16x32_bf16 v[166:169], v[202:205], v[210:213], v[166:169]
	ds_read_b128 v[210:213], v20 offset:1024
	v_mfma_f32_16x16x32_bf16 v[214:217], v[186:189], v[218:221], v[214:217]
	v_mfma_f32_16x16x32_bf16 v[56:59], v[190:193], v[218:221], v[56:59]
	v_mfma_f32_16x16x32_bf16 v[64:67], v[194:197], v[218:221], v[64:67]
	v_mfma_f32_16x16x32_bf16 v[72:75], v[202:205], v[218:221], v[72:75]
	ds_read_b128 v[218:221], v19 offset:1024
	s_waitcnt lgkmcnt(0)
	v_mfma_f32_16x16x32_bf16 v[116:119], v[186:189], v[198:201], v[116:119]
	v_mfma_f32_16x16x32_bf16 v[120:123], v[190:193], v[198:201], v[120:123]
	v_mfma_f32_16x16x32_bf16 v[124:127], v[194:197], v[198:201], v[124:127]
	v_mfma_f32_16x16x32_bf16 v[112:115], v[202:205], v[198:201], v[112:115]
	v_mfma_f32_16x16x32_bf16 v[92:95], v[186:189], v[206:209], v[92:95]
	v_mfma_f32_16x16x32_bf16 v[100:103], v[190:193], v[206:209], v[100:103]
	v_mfma_f32_16x16x32_bf16 v[104:107], v[194:197], v[206:209], v[104:107]
	v_mfma_f32_16x16x32_bf16 v[108:111], v[202:205], v[206:209], v[108:111]
	v_mfma_f32_16x16x32_bf16 v[76:79], v[186:189], v[210:213], v[76:79]
	v_mfma_f32_16x16x32_bf16 v[80:83], v[190:193], v[210:213], v[80:83]
	v_mfma_f32_16x16x32_bf16 v[84:87], v[194:197], v[210:213], v[84:87]
	v_mfma_f32_16x16x32_bf16 v[88:91], v[202:205], v[210:213], v[88:91]
	v_mfma_f32_16x16x32_bf16 v[52:55], v[186:189], v[218:221], v[52:55]
	v_mfma_f32_16x16x32_bf16 v[60:63], v[190:193], v[218:221], v[60:63]
	v_mfma_f32_16x16x32_bf16 v[68:71], v[194:197], v[218:221], v[68:71]
	v_mfma_f32_16x16x32_bf16 v[182:185], v[202:205], v[218:221], v[182:185]
	v_readfirstlane_b32 s56, v45
	v_lshl_add_u64 v[96:97], v[2:3], 0, s[18:19]
	s_mov_b32 m0, s56
	v_readfirstlane_b32 s0, v44
	s_waitcnt vmcnt(0)
	s_waitcnt vmcnt(0)
	s_barrier
	global_load_lds_dwordx4 v[96:97], off
	v_lshl_add_u64 v[96:97], v[4:5], 0, s[18:19]
	s_mov_b32 m0, s0
	v_readfirstlane_b32 s42, v46
	global_load_lds_dwordx4 v[96:97], off
	v_lshl_add_u64 v[44:45], v[6:7], 0, s[18:19]
	s_mov_b32 m0, s42
	v_readfirstlane_b32 s43, v47
	global_load_lds_dwordx4 v[44:45], off
	v_lshl_add_u64 v[44:45], v[8:9], 0, s[18:19]
	s_mov_b32 m0, s43
	v_readfirstlane_b32 s53, v48
	global_load_lds_dwordx4 v[44:45], off
	v_lshl_add_u64 v[44:45], v[10:11], 0, s[18:19]
	s_mov_b32 m0, s53
	v_readfirstlane_b32 s54, v49
	global_load_lds_dwordx4 v[44:45], off
	v_lshl_add_u64 v[44:45], v[12:13], 0, s[18:19]
	s_mov_b32 m0, s54
	v_readfirstlane_b32 s55, v50
	global_load_lds_dwordx4 v[44:45], off
	v_lshl_add_u64 v[44:45], v[14:15], 0, s[18:19]
	s_mov_b32 m0, s55
	v_readfirstlane_b32 s57, v51
	global_load_lds_dwordx4 v[44:45], off
	v_lshl_add_u64 v[44:45], v[16:17], 0, s[18:19]
	s_mov_b32 m0, s57
	s_nop 0
	global_load_lds_dwordx4 v[44:45], off
	ds_read_b128 v[44:47], v23
	ds_read_b128 v[48:51], v23 offset:2048
	ds_read_b128 v[186:189], v23 offset:4096
	ds_read_b128 v[194:197], v23 offset:6144
	ds_read_b128 v[190:193], v24
	ds_read_b128 v[198:201], v25
	ds_read_b128 v[202:205], v26
	ds_read_b128 v[206:209], v27
	s_waitcnt lgkmcnt(0)
	v_mfma_f32_16x16x32_bf16 v[138:141], v[44:47], v[190:193], v[138:141]
	v_mfma_f32_16x16x32_bf16 v[142:145], v[48:51], v[190:193], v[142:145]
	v_mfma_f32_16x16x32_bf16 v[146:149], v[186:189], v[190:193], v[146:149]
	v_mfma_f32_16x16x32_bf16 v[134:137], v[194:197], v[190:193], v[134:137]
	ds_read_b128 v[190:193], v28
	v_mfma_f32_16x16x32_bf16 v[154:157], v[44:47], v[198:201], v[154:157]
	v_mfma_f32_16x16x32_bf16 v[158:161], v[48:51], v[198:201], v[158:161]
	v_mfma_f32_16x16x32_bf16 v[162:165], v[186:189], v[198:201], v[162:165]
	v_mfma_f32_16x16x32_bf16 v[150:153], v[194:197], v[198:201], v[150:153]
	ds_read_b128 v[198:201], v29
	v_mfma_f32_16x16x32_bf16 v[170:173], v[44:47], v[202:205], v[170:173]
	v_mfma_f32_16x16x32_bf16 v[174:177], v[48:51], v[202:205], v[174:177]
	v_mfma_f32_16x16x32_bf16 v[178:181], v[186:189], v[202:205], v[178:181]
	v_mfma_f32_16x16x32_bf16 v[166:169], v[194:197], v[202:205], v[166:169]
	ds_read_b128 v[202:205], v30
	v_mfma_f32_16x16x32_bf16 v[210:213], v[44:47], v[206:209], v[214:217]
	v_mfma_f32_16x16x32_bf16 v[56:59], v[48:51], v[206:209], v[56:59]
	v_mfma_f32_16x16x32_bf16 v[64:67], v[186:189], v[206:209], v[64:67]
	v_mfma_f32_16x16x32_bf16 v[72:75], v[194:197], v[206:209], v[72:75]
	ds_read_b128 v[206:209], v31
	s_waitcnt lgkmcnt(0)
	v_mfma_f32_16x16x32_bf16 v[116:119], v[44:47], v[190:193], v[116:119]
	v_mfma_f32_16x16x32_bf16 v[120:123], v[48:51], v[190:193], v[120:123]
	v_mfma_f32_16x16x32_bf16 v[124:127], v[186:189], v[190:193], v[124:127]
	v_mfma_f32_16x16x32_bf16 v[112:115], v[194:197], v[190:193], v[112:115]
	v_mfma_f32_16x16x32_bf16 v[92:95], v[44:47], v[198:201], v[92:95]
	v_mfma_f32_16x16x32_bf16 v[100:103], v[48:51], v[198:201], v[100:103]
	v_mfma_f32_16x16x32_bf16 v[104:107], v[186:189], v[198:201], v[104:107]
	v_mfma_f32_16x16x32_bf16 v[108:111], v[194:197], v[198:201], v[108:111]
	v_mfma_f32_16x16x32_bf16 v[76:79], v[44:47], v[202:205], v[76:79]
	v_mfma_f32_16x16x32_bf16 v[80:83], v[48:51], v[202:205], v[80:83]
	v_mfma_f32_16x16x32_bf16 v[84:87], v[186:189], v[202:205], v[84:87]
	v_mfma_f32_16x16x32_bf16 v[88:91], v[194:197], v[202:205], v[88:91]
	v_mfma_f32_16x16x32_bf16 v[44:47], v[44:47], v[206:209], v[52:55]
	v_mfma_f32_16x16x32_bf16 v[48:51], v[48:51], v[206:209], v[60:63]
	v_mfma_f32_16x16x32_bf16 v[52:55], v[186:189], v[206:209], v[68:71]
	v_mfma_f32_16x16x32_bf16 v[60:63], v[194:197], v[206:209], v[182:185]
	s_nop 1
	ds_read_b128 v[68:71], v23 offset:1024
	ds_read_b128 v[182:185], v23 offset:3072
	ds_read_b128 v[186:189], v23 offset:5120
	ds_read_b128 v[194:197], v23 offset:7168
	ds_read_b128 v[190:193], v24 offset:1024
	ds_read_b128 v[198:201], v25 offset:1024
	ds_read_b128 v[202:205], v26 offset:1024
	ds_read_b128 v[206:209], v27 offset:1024
	s_waitcnt lgkmcnt(0)
	v_mfma_f32_16x16x32_bf16 v[138:141], v[68:71], v[190:193], v[138:141]
	v_mfma_f32_16x16x32_bf16 v[142:145], v[182:185], v[190:193], v[142:145]
	v_mfma_f32_16x16x32_bf16 v[146:149], v[186:189], v[190:193], v[146:149]
	v_mfma_f32_16x16x32_bf16 v[134:137], v[194:197], v[190:193], v[134:137]
	ds_read_b128 v[190:193], v28 offset:1024
	v_mfma_f32_16x16x32_bf16 v[154:157], v[68:71], v[198:201], v[154:157]
	v_mfma_f32_16x16x32_bf16 v[158:161], v[182:185], v[198:201], v[158:161]
	v_mfma_f32_16x16x32_bf16 v[162:165], v[186:189], v[198:201], v[162:165]
	v_mfma_f32_16x16x32_bf16 v[150:153], v[194:197], v[198:201], v[150:153]
	ds_read_b128 v[198:201], v29 offset:1024
	v_mfma_f32_16x16x32_bf16 v[170:173], v[68:71], v[202:205], v[170:173]
	v_mfma_f32_16x16x32_bf16 v[174:177], v[182:185], v[202:205], v[174:177]
	v_mfma_f32_16x16x32_bf16 v[178:181], v[186:189], v[202:205], v[178:181]
	v_mfma_f32_16x16x32_bf16 v[166:169], v[194:197], v[202:205], v[166:169]
	ds_read_b128 v[202:205], v30 offset:1024
	v_mfma_f32_16x16x32_bf16 v[210:213], v[68:71], v[206:209], v[210:213]
	v_mfma_f32_16x16x32_bf16 v[56:59], v[182:185], v[206:209], v[56:59]
	v_mfma_f32_16x16x32_bf16 v[64:67], v[186:189], v[206:209], v[64:67]
	v_mfma_f32_16x16x32_bf16 v[72:75], v[194:197], v[206:209], v[72:75]
	ds_read_b128 v[206:209], v31 offset:1024
	s_waitcnt lgkmcnt(0)
	v_mfma_f32_16x16x32_bf16 v[116:119], v[68:71], v[190:193], v[116:119]
	v_mfma_f32_16x16x32_bf16 v[120:123], v[182:185], v[190:193], v[120:123]
	v_mfma_f32_16x16x32_bf16 v[124:127], v[186:189], v[190:193], v[124:127]
	v_mfma_f32_16x16x32_bf16 v[112:115], v[194:197], v[190:193], v[112:115]
	v_mfma_f32_16x16x32_bf16 v[92:95], v[68:71], v[198:201], v[92:95]
	v_mfma_f32_16x16x32_bf16 v[100:103], v[182:185], v[198:201], v[100:103]
	v_mfma_f32_16x16x32_bf16 v[104:107], v[186:189], v[198:201], v[104:107]
	v_mfma_f32_16x16x32_bf16 v[108:111], v[194:197], v[198:201], v[108:111]
	v_mfma_f32_16x16x32_bf16 v[76:79], v[68:71], v[202:205], v[76:79]
	v_mfma_f32_16x16x32_bf16 v[80:83], v[182:185], v[202:205], v[80:83]
	v_mfma_f32_16x16x32_bf16 v[84:87], v[186:189], v[202:205], v[84:87]
	v_mfma_f32_16x16x32_bf16 v[88:91], v[194:197], v[202:205], v[88:91]
	v_mfma_f32_16x16x32_bf16 v[44:47], v[68:71], v[206:209], v[44:47]
	v_mfma_f32_16x16x32_bf16 v[48:51], v[182:185], v[206:209], v[48:51]
	v_mfma_f32_16x16x32_bf16 v[52:55], v[186:189], v[206:209], v[52:55]
	v_mfma_f32_16x16x32_bf16 v[60:63], v[194:197], v[206:209], v[60:63]
	v_readfirstlane_b32 s64, v37
	v_lshl_add_u64 v[68:69], v[2:3], 0, s[20:21]
	s_mov_b32 m0, s64
	v_readfirstlane_b32 s58, v36
	s_waitcnt vmcnt(0)
	s_waitcnt vmcnt(0)
	s_barrier
	global_load_lds_dwordx4 v[68:69], off
	v_lshl_add_u64 v[68:69], v[4:5], 0, s[20:21]
	s_mov_b32 m0, s58
	v_readfirstlane_b32 s59, v38
	global_load_lds_dwordx4 v[68:69], off
	v_lshl_add_u64 v[36:37], v[6:7], 0, s[20:21]
	s_mov_b32 m0, s59
	v_readfirstlane_b32 s60, v39
	global_load_lds_dwordx4 v[36:37], off
	v_lshl_add_u64 v[36:37], v[8:9], 0, s[20:21]
	s_mov_b32 m0, s60
	v_readfirstlane_b32 s61, v40
	global_load_lds_dwordx4 v[36:37], off
	v_lshl_add_u64 v[36:37], v[10:11], 0, s[20:21]
	s_mov_b32 m0, s61
	v_readfirstlane_b32 s62, v41
	global_load_lds_dwordx4 v[36:37], off
	v_lshl_add_u64 v[36:37], v[12:13], 0, s[20:21]
	s_mov_b32 m0, s62
	v_readfirstlane_b32 s63, v42
	global_load_lds_dwordx4 v[36:37], off
	v_lshl_add_u64 v[36:37], v[14:15], 0, s[20:21]
	s_mov_b32 m0, s63
	v_readfirstlane_b32 s65, v43
	global_load_lds_dwordx4 v[36:37], off
	v_lshl_add_u64 v[36:37], v[16:17], 0, s[20:21]
	s_mov_b32 m0, s65
	s_nop 0
	global_load_lds_dwordx4 v[36:37], off
	ds_read_b128 v[36:39], v18 offset:32768
	ds_read_b128 v[40:43], v18 offset:34816
	ds_read_b128 v[68:71], v18 offset:36864
	ds_read_b128 v[186:189], v18 offset:38912
	ds_read_b128 v[182:185], v32
	ds_read_b128 v[190:193], v33
	ds_read_b128 v[194:197], v34
	ds_read_b128 v[198:201], v35
	s_waitcnt lgkmcnt(0)
	v_mfma_f32_16x16x32_bf16 v[138:141], v[36:39], v[182:185], v[138:141]
	v_mfma_f32_16x16x32_bf16 v[142:145], v[40:43], v[182:185], v[142:145]
	v_mfma_f32_16x16x32_bf16 v[146:149], v[68:71], v[182:185], v[146:149]
	v_mfma_f32_16x16x32_bf16 v[134:137], v[186:189], v[182:185], v[134:137]
	ds_read_b128 v[182:185], v22
	v_mfma_f32_16x16x32_bf16 v[154:157], v[36:39], v[190:193], v[154:157]
	v_mfma_f32_16x16x32_bf16 v[158:161], v[40:43], v[190:193], v[158:161]
	v_mfma_f32_16x16x32_bf16 v[162:165], v[68:71], v[190:193], v[162:165]
	v_mfma_f32_16x16x32_bf16 v[150:153], v[186:189], v[190:193], v[150:153]
	ds_read_b128 v[190:193], v21
	v_mfma_f32_16x16x32_bf16 v[170:173], v[36:39], v[194:197], v[170:173]
	v_mfma_f32_16x16x32_bf16 v[174:177], v[40:43], v[194:197], v[174:177]
	v_mfma_f32_16x16x32_bf16 v[178:181], v[68:71], v[194:197], v[178:181]
	v_mfma_f32_16x16x32_bf16 v[166:169], v[186:189], v[194:197], v[166:169]
	ds_read_b128 v[194:197], v20
	v_mfma_f32_16x16x32_bf16 v[202:205], v[36:39], v[198:201], v[210:213]
	v_mfma_f32_16x16x32_bf16 v[56:59], v[40:43], v[198:201], v[56:59]
	v_mfma_f32_16x16x32_bf16 v[64:67], v[68:71], v[198:201], v[64:67]
	v_mfma_f32_16x16x32_bf16 v[72:75], v[186:189], v[198:201], v[72:75]
	ds_read_b128 v[198:201], v19
	s_waitcnt lgkmcnt(0)
	v_mfma_f32_16x16x32_bf16 v[116:119], v[36:39], v[182:185], v[116:119]
	v_mfma_f32_16x16x32_bf16 v[120:123], v[40:43], v[182:185], v[120:123]
	v_mfma_f32_16x16x32_bf16 v[124:127], v[68:71], v[182:185], v[124:127]
	v_mfma_f32_16x16x32_bf16 v[112:115], v[186:189], v[182:185], v[112:115]
	v_mfma_f32_16x16x32_bf16 v[92:95], v[36:39], v[190:193], v[92:95]
	v_mfma_f32_16x16x32_bf16 v[100:103], v[40:43], v[190:193], v[100:103]
	v_mfma_f32_16x16x32_bf16 v[104:107], v[68:71], v[190:193], v[104:107]
	v_mfma_f32_16x16x32_bf16 v[108:111], v[186:189], v[190:193], v[108:111]
	v_mfma_f32_16x16x32_bf16 v[76:79], v[36:39], v[194:197], v[76:79]
	v_mfma_f32_16x16x32_bf16 v[80:83], v[40:43], v[194:197], v[80:83]
	v_mfma_f32_16x16x32_bf16 v[84:87], v[68:71], v[194:197], v[84:87]
	v_mfma_f32_16x16x32_bf16 v[88:91], v[186:189], v[194:197], v[88:91]
	v_mfma_f32_16x16x32_bf16 v[36:39], v[36:39], v[198:201], v[44:47]
	v_mfma_f32_16x16x32_bf16 v[40:43], v[40:43], v[198:201], v[48:51]
	v_mfma_f32_16x16x32_bf16 v[44:47], v[68:71], v[198:201], v[52:55]
	v_mfma_f32_16x16x32_bf16 v[48:51], v[186:189], v[198:201], v[60:63]
	s_nop 1
	ds_read_b128 v[52:55], v18 offset:33792
	ds_read_b128 v[60:63], v18 offset:35840
	ds_read_b128 v[68:71], v18 offset:37888
	ds_read_b128 v[186:189], v18 offset:39936
	ds_read_b128 v[182:185], v32 offset:1024
	ds_read_b128 v[190:193], v33 offset:1024
	ds_read_b128 v[194:197], v34 offset:1024
	ds_read_b128 v[198:201], v35 offset:1024
	s_waitcnt lgkmcnt(0)
	v_mfma_f32_16x16x32_bf16 v[138:141], v[52:55], v[182:185], v[138:141]
	v_mfma_f32_16x16x32_bf16 v[142:145], v[60:63], v[182:185], v[142:145]
	v_mfma_f32_16x16x32_bf16 v[146:149], v[68:71], v[182:185], v[146:149]
	v_mfma_f32_16x16x32_bf16 v[134:137], v[186:189], v[182:185], v[134:137]
	ds_read_b128 v[182:185], v22 offset:1024
	v_mfma_f32_16x16x32_bf16 v[154:157], v[52:55], v[190:193], v[154:157]
	v_mfma_f32_16x16x32_bf16 v[158:161], v[60:63], v[190:193], v[158:161]
	v_mfma_f32_16x16x32_bf16 v[162:165], v[68:71], v[190:193], v[162:165]
	v_mfma_f32_16x16x32_bf16 v[150:153], v[186:189], v[190:193], v[150:153]
	ds_read_b128 v[190:193], v21 offset:1024
	v_mfma_f32_16x16x32_bf16 v[170:173], v[52:55], v[194:197], v[170:173]
	v_mfma_f32_16x16x32_bf16 v[174:177], v[60:63], v[194:197], v[174:177]
	v_mfma_f32_16x16x32_bf16 v[178:181], v[68:71], v[194:197], v[178:181]
	v_mfma_f32_16x16x32_bf16 v[166:169], v[186:189], v[194:197], v[166:169]
	ds_read_b128 v[194:197], v20 offset:1024
	v_mfma_f32_16x16x32_bf16 v[202:205], v[52:55], v[198:201], v[202:205]
	v_mfma_f32_16x16x32_bf16 v[56:59], v[60:63], v[198:201], v[56:59]
	v_mfma_f32_16x16x32_bf16 v[64:67], v[68:71], v[198:201], v[64:67]
	v_mfma_f32_16x16x32_bf16 v[72:75], v[186:189], v[198:201], v[72:75]
	ds_read_b128 v[198:201], v19 offset:1024
	s_waitcnt lgkmcnt(0)
	v_mfma_f32_16x16x32_bf16 v[116:119], v[52:55], v[182:185], v[116:119]
	v_mfma_f32_16x16x32_bf16 v[120:123], v[60:63], v[182:185], v[120:123]
	v_mfma_f32_16x16x32_bf16 v[124:127], v[68:71], v[182:185], v[124:127]
	v_mfma_f32_16x16x32_bf16 v[112:115], v[186:189], v[182:185], v[112:115]
	v_mfma_f32_16x16x32_bf16 v[92:95], v[52:55], v[190:193], v[92:95]
	v_mfma_f32_16x16x32_bf16 v[100:103], v[60:63], v[190:193], v[100:103]
	v_mfma_f32_16x16x32_bf16 v[104:107], v[68:71], v[190:193], v[104:107]
	v_mfma_f32_16x16x32_bf16 v[108:111], v[186:189], v[190:193], v[108:111]
	v_mfma_f32_16x16x32_bf16 v[76:79], v[52:55], v[194:197], v[76:79]
	v_mfma_f32_16x16x32_bf16 v[80:83], v[60:63], v[194:197], v[80:83]
	v_mfma_f32_16x16x32_bf16 v[84:87], v[68:71], v[194:197], v[84:87]
	v_mfma_f32_16x16x32_bf16 v[88:91], v[186:189], v[194:197], v[88:91]
	v_mfma_f32_16x16x32_bf16 v[36:39], v[52:55], v[198:201], v[36:39]
	v_mfma_f32_16x16x32_bf16 v[40:43], v[60:63], v[198:201], v[40:43]
	v_mfma_f32_16x16x32_bf16 v[44:47], v[68:71], v[198:201], v[44:47]
	v_mfma_f32_16x16x32_bf16 v[48:51], v[186:189], v[198:201], v[48:51]
	s_mov_b32 m0, s56
	v_lshl_add_u64 v[52:53], v[2:3], 0, s[22:23]
	s_waitcnt vmcnt(0)
	s_waitcnt vmcnt(0)
	s_barrier
	global_load_lds_dwordx4 v[52:53], off
	v_lshl_add_u64 v[52:53], v[4:5], 0, s[22:23]
	s_mov_b32 m0, s0
	s_nop 0
	global_load_lds_dwordx4 v[52:53], off
	v_lshl_add_u64 v[52:53], v[6:7], 0, s[22:23]
	s_mov_b32 m0, s42
	s_nop 0
	global_load_lds_dwordx4 v[52:53], off
	v_lshl_add_u64 v[52:53], v[8:9], 0, s[22:23]
	s_mov_b32 m0, s43
	s_nop 0
	global_load_lds_dwordx4 v[52:53], off
	v_lshl_add_u64 v[52:53], v[10:11], 0, s[22:23]
	s_mov_b32 m0, s53
	s_nop 0
	global_load_lds_dwordx4 v[52:53], off
	v_lshl_add_u64 v[52:53], v[12:13], 0, s[22:23]
	s_mov_b32 m0, s54
	s_nop 0
	global_load_lds_dwordx4 v[52:53], off
	v_lshl_add_u64 v[52:53], v[14:15], 0, s[22:23]
	s_mov_b32 m0, s55
	s_nop 0
	global_load_lds_dwordx4 v[52:53], off
	v_lshl_add_u64 v[52:53], v[16:17], 0, s[22:23]
	s_mov_b32 m0, s57
	s_nop 0
	global_load_lds_dwordx4 v[52:53], off
	ds_read_b128 v[52:55], v23
	ds_read_b128 v[60:63], v23 offset:2048
	ds_read_b128 v[68:71], v23 offset:4096
	ds_read_b128 v[186:189], v23 offset:6144
	ds_read_b128 v[182:185], v24
	ds_read_b128 v[190:193], v25
	ds_read_b128 v[194:197], v26
	ds_read_b128 v[198:201], v27
	s_waitcnt lgkmcnt(0)
	v_mfma_f32_16x16x32_bf16 v[138:141], v[52:55], v[182:185], v[138:141]
	v_mfma_f32_16x16x32_bf16 v[142:145], v[60:63], v[182:185], v[142:145]
	v_mfma_f32_16x16x32_bf16 v[146:149], v[68:71], v[182:185], v[146:149]
	v_mfma_f32_16x16x32_bf16 v[134:137], v[186:189], v[182:185], v[134:137]
	ds_read_b128 v[182:185], v28
	v_mfma_f32_16x16x32_bf16 v[154:157], v[52:55], v[190:193], v[154:157]
	v_mfma_f32_16x16x32_bf16 v[158:161], v[60:63], v[190:193], v[158:161]
	v_mfma_f32_16x16x32_bf16 v[162:165], v[68:71], v[190:193], v[162:165]
	v_mfma_f32_16x16x32_bf16 v[150:153], v[186:189], v[190:193], v[150:153]
	ds_read_b128 v[190:193], v29
	v_mfma_f32_16x16x32_bf16 v[170:173], v[52:55], v[194:197], v[170:173]
	v_mfma_f32_16x16x32_bf16 v[174:177], v[60:63], v[194:197], v[174:177]
	v_mfma_f32_16x16x32_bf16 v[178:181], v[68:71], v[194:197], v[178:181]
	v_mfma_f32_16x16x32_bf16 v[166:169], v[186:189], v[194:197], v[166:169]
	ds_read_b128 v[194:197], v30
	v_mfma_f32_16x16x32_bf16 v[202:205], v[52:55], v[198:201], v[202:205]
	v_mfma_f32_16x16x32_bf16 v[56:59], v[60:63], v[198:201], v[56:59]
	v_mfma_f32_16x16x32_bf16 v[64:67], v[68:71], v[198:201], v[64:67]
	v_mfma_f32_16x16x32_bf16 v[72:75], v[186:189], v[198:201], v[72:75]
	ds_read_b128 v[198:201], v31
	s_waitcnt lgkmcnt(0)
	v_mfma_f32_16x16x32_bf16 v[116:119], v[52:55], v[182:185], v[116:119]
	v_mfma_f32_16x16x32_bf16 v[120:123], v[60:63], v[182:185], v[120:123]
	v_mfma_f32_16x16x32_bf16 v[124:127], v[68:71], v[182:185], v[124:127]
	v_mfma_f32_16x16x32_bf16 v[112:115], v[186:189], v[182:185], v[112:115]
	v_mfma_f32_16x16x32_bf16 v[92:95], v[52:55], v[190:193], v[92:95]
	v_mfma_f32_16x16x32_bf16 v[100:103], v[60:63], v[190:193], v[100:103]
	v_mfma_f32_16x16x32_bf16 v[104:107], v[68:71], v[190:193], v[104:107]
	v_mfma_f32_16x16x32_bf16 v[108:111], v[186:189], v[190:193], v[108:111]
	v_mfma_f32_16x16x32_bf16 v[76:79], v[52:55], v[194:197], v[76:79]
	v_mfma_f32_16x16x32_bf16 v[80:83], v[60:63], v[194:197], v[80:83]
	v_mfma_f32_16x16x32_bf16 v[84:87], v[68:71], v[194:197], v[84:87]
	v_mfma_f32_16x16x32_bf16 v[88:91], v[186:189], v[194:197], v[88:91]
	v_mfma_f32_16x16x32_bf16 v[36:39], v[52:55], v[198:201], v[36:39]
	v_mfma_f32_16x16x32_bf16 v[40:43], v[60:63], v[198:201], v[40:43]
	v_mfma_f32_16x16x32_bf16 v[44:47], v[68:71], v[198:201], v[44:47]
	v_mfma_f32_16x16x32_bf16 v[48:51], v[186:189], v[198:201], v[48:51]
	ds_read_b128 v[52:55], v23 offset:1024
	ds_read_b128 v[60:63], v23 offset:3072
	ds_read_b128 v[68:71], v23 offset:5120
	ds_read_b128 v[186:189], v23 offset:7168
	ds_read_b128 v[182:185], v24 offset:1024
	ds_read_b128 v[190:193], v25 offset:1024
	ds_read_b128 v[194:197], v26 offset:1024
	ds_read_b128 v[198:201], v27 offset:1024
	s_waitcnt lgkmcnt(0)
	v_mfma_f32_16x16x32_bf16 v[138:141], v[52:55], v[182:185], v[138:141]
	v_mfma_f32_16x16x32_bf16 v[142:145], v[60:63], v[182:185], v[142:145]
	v_mfma_f32_16x16x32_bf16 v[146:149], v[68:71], v[182:185], v[146:149]
	v_mfma_f32_16x16x32_bf16 v[134:137], v[186:189], v[182:185], v[134:137]
	ds_read_b128 v[182:185], v28 offset:1024
	v_mfma_f32_16x16x32_bf16 v[154:157], v[52:55], v[190:193], v[154:157]
	v_mfma_f32_16x16x32_bf16 v[158:161], v[60:63], v[190:193], v[158:161]
	v_mfma_f32_16x16x32_bf16 v[162:165], v[68:71], v[190:193], v[162:165]
	v_mfma_f32_16x16x32_bf16 v[150:153], v[186:189], v[190:193], v[150:153]
	ds_read_b128 v[190:193], v29 offset:1024
	v_mfma_f32_16x16x32_bf16 v[170:173], v[52:55], v[194:197], v[170:173]
	v_mfma_f32_16x16x32_bf16 v[174:177], v[60:63], v[194:197], v[174:177]
	v_mfma_f32_16x16x32_bf16 v[178:181], v[68:71], v[194:197], v[178:181]
	v_mfma_f32_16x16x32_bf16 v[166:169], v[186:189], v[194:197], v[166:169]
	ds_read_b128 v[194:197], v30 offset:1024
	v_mfma_f32_16x16x32_bf16 v[202:205], v[52:55], v[198:201], v[202:205]
	v_mfma_f32_16x16x32_bf16 v[56:59], v[60:63], v[198:201], v[56:59]
	v_mfma_f32_16x16x32_bf16 v[64:67], v[68:71], v[198:201], v[64:67]
	v_mfma_f32_16x16x32_bf16 v[72:75], v[186:189], v[198:201], v[72:75]
	ds_read_b128 v[198:201], v31 offset:1024
	s_waitcnt lgkmcnt(0)
	v_mfma_f32_16x16x32_bf16 v[116:119], v[52:55], v[182:185], v[116:119]
	v_mfma_f32_16x16x32_bf16 v[120:123], v[60:63], v[182:185], v[120:123]
	v_mfma_f32_16x16x32_bf16 v[124:127], v[68:71], v[182:185], v[124:127]
	v_mfma_f32_16x16x32_bf16 v[112:115], v[186:189], v[182:185], v[112:115]
	v_mfma_f32_16x16x32_bf16 v[92:95], v[52:55], v[190:193], v[92:95]
	v_mfma_f32_16x16x32_bf16 v[100:103], v[60:63], v[190:193], v[100:103]
	v_mfma_f32_16x16x32_bf16 v[104:107], v[68:71], v[190:193], v[104:107]
	v_mfma_f32_16x16x32_bf16 v[108:111], v[186:189], v[190:193], v[108:111]
	v_mfma_f32_16x16x32_bf16 v[76:79], v[52:55], v[194:197], v[76:79]
	v_mfma_f32_16x16x32_bf16 v[80:83], v[60:63], v[194:197], v[80:83]
	v_mfma_f32_16x16x32_bf16 v[84:87], v[68:71], v[194:197], v[84:87]
	v_mfma_f32_16x16x32_bf16 v[88:91], v[186:189], v[194:197], v[88:91]
	v_mfma_f32_16x16x32_bf16 v[36:39], v[52:55], v[198:201], v[36:39]
	v_mfma_f32_16x16x32_bf16 v[40:43], v[60:63], v[198:201], v[40:43]
	v_mfma_f32_16x16x32_bf16 v[44:47], v[68:71], v[198:201], v[44:47]
	v_mfma_f32_16x16x32_bf16 v[48:51], v[186:189], v[198:201], v[48:51]
	s_mov_b32 m0, s64
	v_lshl_add_u64 v[2:3], v[2:3], 0, s[24:25]
	s_waitcnt vmcnt(0)
	s_waitcnt vmcnt(0)
	s_barrier
	global_load_lds_dwordx4 v[2:3], off
	v_lshl_add_u64 v[2:3], v[4:5], 0, s[24:25]
	s_mov_b32 m0, s58
	s_nop 0
	global_load_lds_dwordx4 v[2:3], off
	v_lshl_add_u64 v[2:3], v[6:7], 0, s[24:25]
	s_mov_b32 m0, s59
	s_nop 0
	global_load_lds_dwordx4 v[2:3], off
	v_lshl_add_u64 v[2:3], v[8:9], 0, s[24:25]
	s_mov_b32 m0, s60
	s_nop 0
	global_load_lds_dwordx4 v[2:3], off
	v_lshl_add_u64 v[2:3], v[10:11], 0, s[24:25]
	s_mov_b32 m0, s61
	s_nop 0
	global_load_lds_dwordx4 v[2:3], off
	v_lshl_add_u64 v[2:3], v[12:13], 0, s[24:25]
	s_mov_b32 m0, s62
	s_nop 0
	global_load_lds_dwordx4 v[2:3], off
	v_lshl_add_u64 v[2:3], v[14:15], 0, s[24:25]
	s_mov_b32 m0, s63
	s_nop 0
	global_load_lds_dwordx4 v[2:3], off
	v_lshl_add_u64 v[2:3], v[16:17], 0, s[24:25]
	s_mov_b32 m0, s65
	s_nop 0
	global_load_lds_dwordx4 v[2:3], off
	ds_read_b128 v[2:5], v18 offset:32768
	ds_read_b128 v[6:9], v18 offset:34816
	ds_read_b128 v[10:13], v18 offset:36864
	ds_read_b128 v[52:55], v18 offset:38912
	ds_read_b128 v[14:17], v32
	ds_read_b128 v[60:63], v33
	ds_read_b128 v[68:71], v34
	ds_read_b128 v[182:185], v35
	s_waitcnt lgkmcnt(0)
	v_mfma_f32_16x16x32_bf16 v[138:141], v[2:5], v[14:17], v[138:141]
	v_mfma_f32_16x16x32_bf16 v[142:145], v[6:9], v[14:17], v[142:145]
	v_mfma_f32_16x16x32_bf16 v[146:149], v[10:13], v[14:17], v[146:149]
	v_mfma_f32_16x16x32_bf16 v[14:17], v[52:55], v[14:17], v[134:137]
	s_nop 2
	ds_read_b128 v[134:137], v22
	v_mfma_f32_16x16x32_bf16 v[154:157], v[2:5], v[60:63], v[154:157]
	v_mfma_f32_16x16x32_bf16 v[158:161], v[6:9], v[60:63], v[158:161]
	v_mfma_f32_16x16x32_bf16 v[162:165], v[10:13], v[60:63], v[162:165]
	v_mfma_f32_16x16x32_bf16 v[60:63], v[52:55], v[60:63], v[150:153]
	s_nop 2
	ds_read_b128 v[150:153], v21
	v_mfma_f32_16x16x32_bf16 v[170:173], v[2:5], v[68:71], v[170:173]
	v_mfma_f32_16x16x32_bf16 v[174:177], v[6:9], v[68:71], v[174:177]
	v_mfma_f32_16x16x32_bf16 v[178:181], v[10:13], v[68:71], v[178:181]
	v_mfma_f32_16x16x32_bf16 v[68:71], v[52:55], v[68:71], v[166:169]
	s_nop 2
	ds_read_b128 v[166:169], v20
	v_mfma_f32_16x16x32_bf16 v[186:189], v[2:5], v[182:185], v[202:205]
	v_mfma_f32_16x16x32_bf16 v[56:59], v[6:9], v[182:185], v[56:59]
	v_mfma_f32_16x16x32_bf16 v[64:67], v[10:13], v[182:185], v[64:67]
	v_mfma_f32_16x16x32_bf16 v[72:75], v[52:55], v[182:185], v[72:75]
	ds_read_b128 v[182:185], v19
	s_waitcnt lgkmcnt(0)
	v_mfma_f32_16x16x32_bf16 v[116:119], v[2:5], v[134:137], v[116:119]
	v_mfma_f32_16x16x32_bf16 v[120:123], v[6:9], v[134:137], v[120:123]
	v_mfma_f32_16x16x32_bf16 v[124:127], v[10:13], v[134:137], v[124:127]
	v_mfma_f32_16x16x32_bf16 v[112:115], v[52:55], v[134:137], v[112:115]
	v_mfma_f32_16x16x32_bf16 v[92:95], v[2:5], v[150:153], v[92:95]
	v_mfma_f32_16x16x32_bf16 v[100:103], v[6:9], v[150:153], v[100:103]
	v_mfma_f32_16x16x32_bf16 v[104:107], v[10:13], v[150:153], v[104:107]
	v_mfma_f32_16x16x32_bf16 v[108:111], v[52:55], v[150:153], v[108:111]
	v_mfma_f32_16x16x32_bf16 v[76:79], v[2:5], v[166:169], v[76:79]
	v_mfma_f32_16x16x32_bf16 v[80:83], v[6:9], v[166:169], v[80:83]
	v_mfma_f32_16x16x32_bf16 v[84:87], v[10:13], v[166:169], v[84:87]
	v_mfma_f32_16x16x32_bf16 v[88:91], v[52:55], v[166:169], v[88:91]
	v_mfma_f32_16x16x32_bf16 v[2:5], v[2:5], v[182:185], v[36:39]
	v_mfma_f32_16x16x32_bf16 v[6:9], v[6:9], v[182:185], v[40:43]
	v_mfma_f32_16x16x32_bf16 v[10:13], v[10:13], v[182:185], v[44:47]
	v_mfma_f32_16x16x32_bf16 v[36:39], v[52:55], v[182:185], v[48:51]
	s_nop 0
	ds_read_b128 v[40:43], v18 offset:33792
	ds_read_b128 v[44:47], v18 offset:35840
	ds_read_b128 v[48:51], v18 offset:37888
	ds_read_b128 v[134:137], v18 offset:39936
	ds_read_b128 v[52:55], v32 offset:1024
	ds_read_b128 v[150:153], v33 offset:1024
	ds_read_b128 v[166:169], v34 offset:1024
	ds_read_b128 v[32:35], v35 offset:1024
	s_waitcnt lgkmcnt(0)
	v_mfma_f32_16x16x32_bf16 v[138:141], v[40:43], v[52:55], v[138:141]
	v_mfma_f32_16x16x32_bf16 v[142:145], v[44:47], v[52:55], v[142:145]
	v_mfma_f32_16x16x32_bf16 v[146:149], v[48:51], v[52:55], v[146:149]
	v_mfma_f32_16x16x32_bf16 v[14:17], v[134:137], v[52:55], v[14:17]
	ds_read_b128 v[52:55], v22 offset:1024
	v_mfma_f32_16x16x32_bf16 v[154:157], v[40:43], v[150:153], v[154:157]
	v_mfma_f32_16x16x32_bf16 v[158:161], v[44:47], v[150:153], v[158:161]
	v_mfma_f32_16x16x32_bf16 v[162:165], v[48:51], v[150:153], v[162:165]
	v_mfma_f32_16x16x32_bf16 v[60:63], v[134:137], v[150:153], v[60:63]
	ds_read_b128 v[150:153], v21 offset:1024
	v_mfma_f32_16x16x32_bf16 v[170:173], v[40:43], v[166:169], v[170:173]
	v_mfma_f32_16x16x32_bf16 v[174:177], v[44:47], v[166:169], v[174:177]
	v_mfma_f32_16x16x32_bf16 v[178:181], v[48:51], v[166:169], v[178:181]
	v_mfma_f32_16x16x32_bf16 v[68:71], v[134:137], v[166:169], v[68:71]
	ds_read_b128 v[166:169], v20 offset:1024
	v_mfma_f32_16x16x32_bf16 v[182:185], v[40:43], v[32:35], v[186:189]
	v_mfma_f32_16x16x32_bf16 v[56:59], v[44:47], v[32:35], v[56:59]
	v_mfma_f32_16x16x32_bf16 v[64:67], v[48:51], v[32:35], v[64:67]
	v_mfma_f32_16x16x32_bf16 v[32:35], v[134:137], v[32:35], v[72:75]
	ds_read_b128 v[18:21], v19 offset:1024
	s_waitcnt lgkmcnt(0)
	v_mfma_f32_16x16x32_bf16 v[72:75], v[40:43], v[52:55], v[116:119]
	v_mfma_f32_16x16x32_bf16 v[116:119], v[44:47], v[52:55], v[120:123]
	v_mfma_f32_16x16x32_bf16 v[120:123], v[48:51], v[52:55], v[124:127]
	v_mfma_f32_16x16x32_bf16 v[52:55], v[134:137], v[52:55], v[112:115]
	v_mfma_f32_16x16x32_bf16 v[92:95], v[40:43], v[150:153], v[92:95]
	v_mfma_f32_16x16x32_bf16 v[100:103], v[44:47], v[150:153], v[100:103]
	v_mfma_f32_16x16x32_bf16 v[104:107], v[48:51], v[150:153], v[104:107]
	v_mfma_f32_16x16x32_bf16 v[108:111], v[134:137], v[150:153], v[108:111]
	v_mfma_f32_16x16x32_bf16 v[76:79], v[40:43], v[166:169], v[76:79]
	v_mfma_f32_16x16x32_bf16 v[80:83], v[44:47], v[166:169], v[80:83]
	v_mfma_f32_16x16x32_bf16 v[84:87], v[48:51], v[166:169], v[84:87]
	v_mfma_f32_16x16x32_bf16 v[88:91], v[134:137], v[166:169], v[88:91]
	v_mfma_f32_16x16x32_bf16 v[2:5], v[40:43], v[18:21], v[2:5]
	v_mfma_f32_16x16x32_bf16 v[6:9], v[44:47], v[18:21], v[6:9]
	v_mfma_f32_16x16x32_bf16 v[10:13], v[48:51], v[18:21], v[10:13]
	v_mfma_f32_16x16x32_bf16 v[18:21], v[134:137], v[18:21], v[36:39]
	s_waitcnt vmcnt(0)
	s_waitcnt vmcnt(0)
	s_barrier
	s_nop 0
	ds_read_b128 v[36:39], v31
	ds_read_b128 v[40:43], v30
	ds_read_b128 v[44:47], v29
	ds_read_b128 v[48:51], v28
	ds_read_b128 v[112:115], v27
	ds_read_b128 v[124:127], v26
	ds_read_b128 v[134:137], v25
	ds_read_b128 v[150:153], v24
	ds_read_b128 v[166:169], v23
	s_waitcnt lgkmcnt(0)
	v_mfma_f32_16x16x32_bf16 v[186:189], v[166:169], v[36:39], v[2:5]
	s_nop 2
	ds_read_b128 v[2:5], v23 offset:2048
	s_waitcnt lgkmcnt(0)
	v_mfma_f32_16x16x32_bf16 v[190:193], v[2:5], v[36:39], v[6:9]
	s_nop 2
	ds_read_b128 v[6:9], v23 offset:4096
	s_waitcnt lgkmcnt(0)
	v_mfma_f32_16x16x32_bf16 v[194:197], v[6:9], v[36:39], v[10:13]
	s_nop 2
	ds_read_b128 v[10:13], v23 offset:6144
	s_waitcnt lgkmcnt(0)
	v_mfma_f32_16x16x32_bf16 v[198:201], v[10:13], v[36:39], v[18:21]
	v_mfma_f32_16x16x32_bf16 v[18:21], v[10:13], v[134:137], v[60:63]
	v_mfma_f32_16x16x32_bf16 v[36:39], v[10:13], v[124:127], v[68:71]
	v_mfma_f32_16x16x32_bf16 v[68:71], v[6:9], v[134:137], v[162:165]
	v_mfma_f32_16x16x32_bf16 v[162:165], v[6:9], v[112:115], v[64:67]
	v_mfma_f32_16x16x32_bf16 v[64:67], v[2:5], v[150:153], v[142:145]
	v_mfma_f32_16x16x32_bf16 v[142:145], v[2:5], v[134:137], v[158:161]
	v_mfma_f32_16x16x32_bf16 v[134:137], v[166:169], v[134:137], v[154:157]
	v_mfma_f32_16x16x32_bf16 v[154:157], v[166:169], v[40:43], v[76:79]
	v_mfma_f32_16x16x32_bf16 v[60:63], v[6:9], v[150:153], v[146:149]
	v_mfma_f32_16x16x32_bf16 v[146:149], v[6:9], v[124:127], v[178:181]
	v_mfma_f32_16x16x32_bf16 v[158:161], v[2:5], v[124:127], v[174:177]
	v_mfma_f32_16x16x32_bf16 v[124:127], v[166:169], v[124:127], v[170:173]
	v_mfma_f32_16x16x32_bf16 v[170:173], v[6:9], v[40:43], v[84:87]
	v_mfma_f32_16x16x32_bf16 v[138:141], v[166:169], v[150:153], v[138:141]
	v_mfma_f32_16x16x32_bf16 v[56:59], v[2:5], v[112:115], v[56:59]
	v_mfma_f32_16x16x32_bf16 v[116:119], v[2:5], v[48:51], v[116:119]
	v_mfma_f32_16x16x32_bf16 v[120:123], v[6:9], v[48:51], v[120:123]
	v_mfma_f32_16x16x32_bf16 v[14:17], v[10:13], v[150:153], v[14:17]
	v_mfma_f32_16x16x32_bf16 v[150:153], v[166:169], v[48:51], v[72:75]
	v_mfma_f32_16x16x32_bf16 v[48:51], v[10:13], v[48:51], v[52:55]
	v_mfma_f32_16x16x32_bf16 v[52:55], v[166:169], v[44:47], v[92:95]
	v_mfma_f32_16x16x32_bf16 v[32:35], v[10:13], v[112:115], v[32:35]
	v_mfma_f32_16x16x32_bf16 v[112:115], v[166:169], v[112:115], v[182:185]
	v_mfma_f32_16x16x32_bf16 v[166:169], v[2:5], v[40:43], v[80:83]
	v_mfma_f32_16x16x32_bf16 v[104:107], v[6:9], v[44:47], v[104:107]
	v_mfma_f32_16x16x32_bf16 v[108:111], v[10:13], v[44:47], v[108:111]
	v_mfma_f32_16x16x32_bf16 v[100:103], v[2:5], v[44:47], v[100:103]
	v_mfma_f32_16x16x32_bf16 v[174:177], v[10:13], v[40:43], v[88:91]
	ds_read_b128 v[178:181], v23 offset:1024
	ds_read_b128 v[182:185], v23 offset:3072
	ds_read_b128 v[202:205], v23 offset:5120
	ds_read_b128 v[206:209], v23 offset:7168
	ds_read_b128 v[2:5], v24 offset:1024
	ds_read_b128 v[6:9], v25 offset:1024
	ds_read_b128 v[10:13], v26 offset:1024
	ds_read_b128 v[22:25], v27 offset:1024
	s_waitcnt lgkmcnt(3)
	v_mfma_f32_16x16x32_bf16 v[138:141], v[178:181], v[2:5], v[138:141]
	v_mfma_f32_16x16x32_bf16 v[210:213], v[182:185], v[2:5], v[64:67]
	v_mfma_f32_16x16x32_bf16 v[214:217], v[202:205], v[2:5], v[60:63]
	v_mfma_f32_16x16x32_bf16 v[218:221], v[206:209], v[2:5], v[14:17]
	ds_read_b128 v[2:5], v28 offset:1024
	s_waitcnt lgkmcnt(3)
	v_mfma_f32_16x16x32_bf16 v[134:137], v[178:181], v[6:9], v[134:137]
	v_mfma_f32_16x16x32_bf16 v[142:145], v[182:185], v[6:9], v[142:145]
	v_mfma_f32_16x16x32_bf16 v[222:225], v[202:205], v[6:9], v[68:71]
	v_mfma_f32_16x16x32_bf16 v[226:229], v[206:209], v[6:9], v[18:21]
	ds_read_b128 v[6:9], v29 offset:1024
	s_waitcnt lgkmcnt(3)
	v_mfma_f32_16x16x32_bf16 v[66:69], v[178:181], v[10:13], v[124:127]
	v_mfma_f32_16x16x32_bf16 v[70:73], v[182:185], v[10:13], v[158:161]
	v_mfma_f32_16x16x32_bf16 v[74:77], v[202:205], v[10:13], v[146:149]
	v_mfma_f32_16x16x32_bf16 v[78:81], v[206:209], v[10:13], v[36:39]
	ds_read_b128 v[14:17], v30 offset:1024
	s_waitcnt lgkmcnt(3)
	v_mfma_f32_16x16x32_bf16 v[82:85], v[178:181], v[22:25], v[112:115]
	v_mfma_f32_16x16x32_bf16 v[86:89], v[182:185], v[22:25], v[56:59]
	v_mfma_f32_16x16x32_bf16 v[90:93], v[202:205], v[22:25], v[162:165]
	v_mfma_f32_16x16x32_bf16 v[94:97], v[206:209], v[22:25], v[32:35]
	s_nop 2
	ds_read_b128 v[30:33], v31 offset:1024
	s_waitcnt lgkmcnt(3)
	v_mfma_f32_16x16x32_bf16 v[34:37], v[178:181], v[2:5], v[150:153]
	v_mfma_f32_16x16x32_bf16 v[38:41], v[182:185], v[2:5], v[116:119]
	v_mfma_f32_16x16x32_bf16 v[42:45], v[202:205], v[2:5], v[120:123]
	v_mfma_f32_16x16x32_bf16 v[46:49], v[206:209], v[2:5], v[48:51]
	s_waitcnt lgkmcnt(2)
	v_mfma_f32_16x16x32_bf16 v[50:53], v[178:181], v[6:9], v[52:55]
	v_mfma_f32_16x16x32_bf16 v[54:57], v[182:185], v[6:9], v[100:103]
	v_mfma_f32_16x16x32_bf16 v[58:61], v[202:205], v[6:9], v[104:107]
	v_mfma_f32_16x16x32_bf16 v[62:65], v[206:209], v[6:9], v[108:111]
	s_waitcnt lgkmcnt(1)
	v_mfma_f32_16x16x32_bf16 v[2:5], v[178:181], v[14:17], v[154:157]
	v_mfma_f32_16x16x32_bf16 v[6:9], v[182:185], v[14:17], v[166:169]
	v_mfma_f32_16x16x32_bf16 v[10:13], v[202:205], v[14:17], v[170:173]
	v_mfma_f32_16x16x32_bf16 v[14:17], v[206:209], v[14:17], v[174:177]
	s_waitcnt lgkmcnt(0)
	v_mfma_f32_16x16x32_bf16 v[18:21], v[178:181], v[30:33], v[186:189]
	v_mfma_f32_16x16x32_bf16 v[22:25], v[182:185], v[30:33], v[190:193]
	v_mfma_f32_16x16x32_bf16 v[26:29], v[202:205], v[30:33], v[194:197]
	v_mfma_f32_16x16x32_bf16 v[30:33], v[206:209], v[30:33], v[198:201]
	v_lshlrev_b32_e32 v101, 2, v98
	v_and_b32_e32 v112, 60, v101
	v_ashrrev_i32_e32 v101, 1, v98
	v_lshrrev_b32_e32 v99, 6, v98
	v_and_b32_e32 v101, 0xffffff80, v101
	v_and_b32_e32 v100, 15, v98
	v_mul_lo_u32 v99, v99, s48
	v_add_u32_e32 v107, s28, v101
	v_bfe_u32 v108, v98, 4, 2
	v_add_u32_e32 v109, s46, v99
	v_and_b32_e32 v99, 48, v98
	v_and_or_b32 v102, v98, s49, v112
	v_mul_u32_u24_e32 v98, 0x110, v100
	v_or_b32_e32 v100, v107, v108
	v_lshl_add_u64 v[0:1], v[0:1], 0, s[38:39]
	v_lshlrev_b32_e32 v130, 1, v102
	v_ashrrev_i32_e32 v101, 31, v100
	v_lshl_add_u64 v[0:1], v[0:1], 0, v[130:131]
	v_add3_u32 v99, v109, v99, v98
	v_lshlrev_b64 v[100:101], 11, v[100:101]
	s_waitcnt vmcnt(0)
	s_barrier
	ds_write_b128 v99, v[138:141]
	ds_write_b128 v99, v[210:213] offset:64
	ds_write_b128 v99, v[214:217] offset:128
	ds_write_b128 v99, v[218:221] offset:192
	ds_write_b128 v99, v[134:137] offset:4352
	ds_write_b128 v99, v[142:145] offset:4416
	ds_write_b128 v99, v[222:225] offset:4480
	ds_write_b128 v99, v[226:229] offset:4544
	v_lshl_add_u64 v[114:115], v[0:1], 0, v[100:101]
	flat_load_dwordx2 v[116:117], v[114:115]
	v_or_b32_e32 v100, 4, v108
	v_or_b32_e32 v102, v107, v100
	v_ashrrev_i32_e32 v103, 31, v102
	v_lshlrev_b64 v[102:103], 11, v[102:103]
	v_lshl_add_u64 v[118:119], v[0:1], 0, v[102:103]
	flat_load_dwordx2 v[120:121], v[118:119]
	v_or_b32_e32 v101, 8, v108
	v_or_b32_e32 v102, v107, v101
	v_ashrrev_i32_e32 v103, 31, v102
	v_lshlrev_b64 v[102:103], 11, v[102:103]
	v_lshl_add_u64 v[122:123], v[0:1], 0, v[102:103]
	flat_load_dwordx2 v[124:125], v[122:123]
	v_or_b32_e32 v102, 12, v108
	v_or_b32_e32 v104, v107, v102
	v_ashrrev_i32_e32 v105, 31, v104
	v_lshlrev_b64 v[104:105], 11, v[104:105]
	v_lshl_add_u64 v[126:127], v[0:1], 0, v[104:105]
	flat_load_dwordx2 v[128:129], v[126:127]
	v_or_b32_e32 v103, 16, v108
	v_or_b32_e32 v104, v107, v103
	v_ashrrev_i32_e32 v105, 31, v104
	v_lshlrev_b64 v[104:105], 11, v[104:105]
	v_lshl_add_u64 v[134:135], v[0:1], 0, v[104:105]
	flat_load_dwordx2 v[136:137], v[134:135]
	v_or_b32_e32 v104, 20, v108
	v_or_b32_e32 v110, v107, v104
	v_ashrrev_i32_e32 v111, 31, v110
	v_lshlrev_b64 v[110:111], 11, v[110:111]
	v_lshl_add_u64 v[138:139], v[0:1], 0, v[110:111]
	flat_load_dwordx2 v[140:141], v[138:139]
	v_or_b32_e32 v105, 24, v108
	v_or_b32_e32 v110, v107, v105
	v_ashrrev_i32_e32 v111, 31, v110
	v_lshlrev_b64 v[110:111], 11, v[110:111]
	v_lshl_add_u64 v[142:143], v[0:1], 0, v[110:111]
	flat_load_dwordx2 v[144:145], v[142:143]
	v_or_b32_e32 v106, 28, v108
	v_or_b32_e32 v146, v107, v106
	v_ashrrev_i32_e32 v147, 31, v146
	v_lshlrev_b64 v[146:147], 11, v[146:147]
	v_lshl_add_u64 v[146:147], v[0:1], 0, v[146:147]
	flat_load_dwordx2 v[148:149], v[146:147]
	v_mul_u32_u24_e32 v98, 0x110, v108
	v_lshlrev_b32_e32 v110, 2, v112
	v_add3_u32 v98, v109, v110, v98
	ds_read_b128 v[110:113], v98
	s_add_i32 s0, s30, 0x1600
	s_lshl_b64 s[42:43], s[0:1], 11
	s_waitcnt vmcnt(0) lgkmcnt(0)
	v_and_b32_e32 v151, 0xffff0000, v116
	v_lshlrev_b32_e32 v150, 16, v116
	v_and_b32_e32 v153, 0xffff0000, v117
	v_lshlrev_b32_e32 v152, 16, v117
	v_pk_mul_f32 v[110:111], v[110:111], v[150:151]
	v_pk_mul_f32 v[112:113], v[112:113], v[152:153]
	v_cvt_pk_bf16_f32 v110, v110, v111
	v_cvt_pk_bf16_f32 v111, v112, v113
	flat_store_dwordx2 v[114:115], v[110:111]
	ds_read_b128 v[110:113], v98 offset:1088
	v_and_b32_e32 v115, 0xffff0000, v120
	v_lshlrev_b32_e32 v114, 16, v120
	v_and_b32_e32 v117, 0xffff0000, v121
	v_lshlrev_b32_e32 v116, 16, v121
	s_waitcnt lgkmcnt(0)
	v_pk_mul_f32 v[110:111], v[110:111], v[114:115]
	v_pk_mul_f32 v[112:113], v[112:113], v[116:117]
	v_cvt_pk_bf16_f32 v110, v110, v111
	v_cvt_pk_bf16_f32 v111, v112, v113
	flat_store_dwordx2 v[118:119], v[110:111]
	ds_read_b128 v[110:113], v98 offset:2176
	v_and_b32_e32 v115, 0xffff0000, v124
	v_lshlrev_b32_e32 v114, 16, v124
	v_and_b32_e32 v117, 0xffff0000, v125
	v_lshlrev_b32_e32 v116, 16, v125
	s_waitcnt lgkmcnt(0)
	v_pk_mul_f32 v[110:111], v[110:111], v[114:115]
	v_pk_mul_f32 v[112:113], v[112:113], v[116:117]
	v_cvt_pk_bf16_f32 v110, v110, v111
	v_cvt_pk_bf16_f32 v111, v112, v113
	flat_store_dwordx2 v[122:123], v[110:111]
	ds_read_b128 v[110:113], v98 offset:3264
	v_and_b32_e32 v115, 0xffff0000, v128
	v_lshlrev_b32_e32 v114, 16, v128
	v_mov_b32_e32 v150, v132
	s_waitcnt lgkmcnt(0)
	v_pk_mul_f32 v[110:111], v[110:111], v[114:115]
	v_and_b32_e32 v115, 0xffff0000, v129
	v_lshlrev_b32_e32 v114, 16, v129
	v_pk_mul_f32 v[112:113], v[112:113], v[114:115]
	v_cvt_pk_bf16_f32 v110, v110, v111
	v_cvt_pk_bf16_f32 v111, v112, v113
	flat_store_dwordx2 v[126:127], v[110:111]
	ds_read_b128 v[110:113], v98 offset:4352
	v_and_b32_e32 v115, 0xffff0000, v136
	v_lshlrev_b32_e32 v114, 16, v136
	s_waitcnt lgkmcnt(0)
	v_pk_mul_f32 v[110:111], v[110:111], v[114:115]
	v_and_b32_e32 v115, 0xffff0000, v137
	v_lshlrev_b32_e32 v114, 16, v137
	v_pk_mul_f32 v[112:113], v[112:113], v[114:115]
	v_cvt_pk_bf16_f32 v110, v110, v111
	v_cvt_pk_bf16_f32 v111, v112, v113
	flat_store_dwordx2 v[134:135], v[110:111]
	ds_read_b128 v[110:113], v98 offset:5440
	v_and_b32_e32 v115, 0xffff0000, v140
	v_lshlrev_b32_e32 v114, 16, v140
	s_waitcnt lgkmcnt(0)
	v_pk_mul_f32 v[110:111], v[110:111], v[114:115]
	v_and_b32_e32 v115, 0xffff0000, v141
	v_lshlrev_b32_e32 v114, 16, v141
	v_pk_mul_f32 v[112:113], v[112:113], v[114:115]
	v_cvt_pk_bf16_f32 v110, v110, v111
	v_cvt_pk_bf16_f32 v111, v112, v113
	flat_store_dwordx2 v[138:139], v[110:111]
	ds_read_b128 v[110:113], v98 offset:6528
	v_and_b32_e32 v115, 0xffff0000, v144
	v_lshlrev_b32_e32 v114, 16, v144
	s_waitcnt lgkmcnt(0)
	v_pk_mul_f32 v[110:111], v[110:111], v[114:115]
	v_and_b32_e32 v115, 0xffff0000, v145
	v_lshlrev_b32_e32 v114, 16, v145
	v_pk_mul_f32 v[112:113], v[112:113], v[114:115]
	v_cvt_pk_bf16_f32 v110, v110, v111
	v_cvt_pk_bf16_f32 v111, v112, v113
	flat_store_dwordx2 v[142:143], v[110:111]
	ds_read_b128 v[110:113], v98 offset:7616
	v_and_b32_e32 v115, 0xffff0000, v148
	v_lshlrev_b32_e32 v114, 16, v148
	s_waitcnt lgkmcnt(0)
	v_pk_mul_f32 v[110:111], v[110:111], v[114:115]
	v_and_b32_e32 v115, 0xffff0000, v149
	v_lshlrev_b32_e32 v114, 16, v149
	v_pk_mul_f32 v[112:113], v[112:113], v[114:115]
	v_cvt_pk_bf16_f32 v110, v110, v111
	v_cvt_pk_bf16_f32 v111, v112, v113
	flat_store_dwordx2 v[146:147], v[110:111]
	ds_write_b128 v99, v[66:69]
	v_or_b32_e32 v68, 32, v107
	v_or_b32_e32 v66, v68, v108
	v_ashrrev_i32_e32 v67, 31, v66
	v_lshlrev_b64 v[66:67], 11, v[66:67]
	ds_write_b128 v99, v[70:73] offset:64
	ds_write_b128 v99, v[74:77] offset:128
	ds_write_b128 v99, v[78:81] offset:192
	ds_write_b128 v99, v[82:85] offset:4352
	ds_write_b128 v99, v[86:89] offset:4416
	ds_write_b128 v99, v[90:93] offset:4480
	ds_write_b128 v99, v[94:97] offset:4544
	v_lshl_add_u64 v[70:71], v[0:1], 0, v[66:67]
	flat_load_dwordx2 v[72:73], v[70:71]
	v_or_b32_e32 v66, v68, v100
	v_ashrrev_i32_e32 v67, 31, v66
	v_lshlrev_b64 v[66:67], 11, v[66:67]
	v_lshl_add_u64 v[74:75], v[0:1], 0, v[66:67]
	flat_load_dwordx2 v[76:77], v[74:75]
	v_or_b32_e32 v66, v68, v101
	v_ashrrev_i32_e32 v67, 31, v66
	v_lshlrev_b64 v[66:67], 11, v[66:67]
	v_lshl_add_u64 v[78:79], v[0:1], 0, v[66:67]
	flat_load_dwordx2 v[80:81], v[78:79]
	v_or_b32_e32 v66, v68, v102
	v_ashrrev_i32_e32 v67, 31, v66
	v_lshlrev_b64 v[66:67], 11, v[66:67]
	v_lshl_add_u64 v[82:83], v[0:1], 0, v[66:67]
	flat_load_dwordx2 v[84:85], v[82:83]
	v_or_b32_e32 v66, v68, v103
	v_ashrrev_i32_e32 v67, 31, v66
	v_lshlrev_b64 v[66:67], 11, v[66:67]
	v_lshl_add_u64 v[86:87], v[0:1], 0, v[66:67]
	flat_load_dwordx2 v[88:89], v[86:87]
	v_or_b32_e32 v66, v68, v104
	v_ashrrev_i32_e32 v67, 31, v66
	v_lshlrev_b64 v[66:67], 11, v[66:67]
	v_lshl_add_u64 v[90:91], v[0:1], 0, v[66:67]
	flat_load_dwordx2 v[92:93], v[90:91]
	v_or_b32_e32 v66, v68, v105
	v_ashrrev_i32_e32 v67, 31, v66
	v_lshlrev_b64 v[66:67], 11, v[66:67]
	v_lshl_add_u64 v[94:95], v[0:1], 0, v[66:67]
	flat_load_dwordx2 v[96:97], v[94:95]
	v_or_b32_e32 v66, v68, v106
	v_ashrrev_i32_e32 v67, 31, v66
	v_lshlrev_b64 v[66:67], 11, v[66:67]
	v_lshl_add_u64 v[110:111], v[0:1], 0, v[66:67]
	flat_load_dwordx2 v[112:113], v[110:111]
	ds_read_b128 v[66:69], v98
	s_waitcnt vmcnt(0) lgkmcnt(0)
	v_and_b32_e32 v115, 0xffff0000, v72
	v_lshlrev_b32_e32 v114, 16, v72
	v_and_b32_e32 v117, 0xffff0000, v73
	v_lshlrev_b32_e32 v116, 16, v73
	v_pk_mul_f32 v[66:67], v[66:67], v[114:115]
	v_pk_mul_f32 v[68:69], v[68:69], v[116:117]
	v_cvt_pk_bf16_f32 v66, v66, v67
	v_cvt_pk_bf16_f32 v67, v68, v69
	flat_store_dwordx2 v[70:71], v[66:67]
	ds_read_b128 v[66:69], v98 offset:1088
	v_and_b32_e32 v71, 0xffff0000, v76
	v_lshlrev_b32_e32 v70, 16, v76
	v_and_b32_e32 v73, 0xffff0000, v77
	v_lshlrev_b32_e32 v72, 16, v77
	s_waitcnt lgkmcnt(0)
	v_pk_mul_f32 v[66:67], v[66:67], v[70:71]
	v_pk_mul_f32 v[68:69], v[68:69], v[72:73]
	v_cvt_pk_bf16_f32 v66, v66, v67
	v_cvt_pk_bf16_f32 v67, v68, v69
	flat_store_dwordx2 v[74:75], v[66:67]
	ds_read_b128 v[66:69], v98 offset:2176
	v_and_b32_e32 v71, 0xffff0000, v80
	v_lshlrev_b32_e32 v70, 16, v80
	v_and_b32_e32 v73, 0xffff0000, v81
	v_lshlrev_b32_e32 v72, 16, v81
	s_waitcnt lgkmcnt(0)
	v_pk_mul_f32 v[66:67], v[66:67], v[70:71]
	v_pk_mul_f32 v[68:69], v[68:69], v[72:73]
	v_cvt_pk_bf16_f32 v66, v66, v67
	v_cvt_pk_bf16_f32 v67, v68, v69
	flat_store_dwordx2 v[78:79], v[66:67]
	ds_read_b128 v[66:69], v98 offset:3264
	v_and_b32_e32 v71, 0xffff0000, v84
	v_lshlrev_b32_e32 v70, 16, v84
	v_and_b32_e32 v73, 0xffff0000, v85
	v_lshlrev_b32_e32 v72, 16, v85
	s_waitcnt lgkmcnt(0)
	v_pk_mul_f32 v[66:67], v[66:67], v[70:71]
	v_pk_mul_f32 v[68:69], v[68:69], v[72:73]
	v_cvt_pk_bf16_f32 v66, v66, v67
	v_cvt_pk_bf16_f32 v67, v68, v69
	flat_store_dwordx2 v[82:83], v[66:67]
	ds_read_b128 v[66:69], v98 offset:4352
	v_and_b32_e32 v71, 0xffff0000, v88
	v_lshlrev_b32_e32 v70, 16, v88
	v_and_b32_e32 v73, 0xffff0000, v89
	v_lshlrev_b32_e32 v72, 16, v89
	s_waitcnt lgkmcnt(0)
	v_pk_mul_f32 v[66:67], v[66:67], v[70:71]
	v_pk_mul_f32 v[68:69], v[68:69], v[72:73]
	v_cvt_pk_bf16_f32 v66, v66, v67
	v_cvt_pk_bf16_f32 v67, v68, v69
	flat_store_dwordx2 v[86:87], v[66:67]
	ds_read_b128 v[66:69], v98 offset:5440
	v_and_b32_e32 v71, 0xffff0000, v92
	v_lshlrev_b32_e32 v70, 16, v92
	v_and_b32_e32 v73, 0xffff0000, v93
	v_lshlrev_b32_e32 v72, 16, v93
	s_waitcnt lgkmcnt(0)
	v_pk_mul_f32 v[66:67], v[66:67], v[70:71]
	v_pk_mul_f32 v[68:69], v[68:69], v[72:73]
	v_cvt_pk_bf16_f32 v66, v66, v67
	v_cvt_pk_bf16_f32 v67, v68, v69
	flat_store_dwordx2 v[90:91], v[66:67]
	ds_read_b128 v[66:69], v98 offset:6528
	v_and_b32_e32 v71, 0xffff0000, v96
	v_lshlrev_b32_e32 v70, 16, v96
	v_and_b32_e32 v73, 0xffff0000, v97
	v_lshlrev_b32_e32 v72, 16, v97
	s_waitcnt lgkmcnt(0)
	v_pk_mul_f32 v[66:67], v[66:67], v[70:71]
	v_pk_mul_f32 v[68:69], v[68:69], v[72:73]
	v_cvt_pk_bf16_f32 v66, v66, v67
	v_cvt_pk_bf16_f32 v67, v68, v69
	flat_store_dwordx2 v[94:95], v[66:67]
	ds_read_b128 v[66:69], v98 offset:7616
	v_and_b32_e32 v71, 0xffff0000, v112
	v_lshlrev_b32_e32 v70, 16, v112
	v_and_b32_e32 v73, 0xffff0000, v113
	v_lshlrev_b32_e32 v72, 16, v113
	s_waitcnt lgkmcnt(0)
	v_pk_mul_f32 v[66:67], v[66:67], v[70:71]
	v_pk_mul_f32 v[68:69], v[68:69], v[72:73]
	v_cvt_pk_bf16_f32 v66, v66, v67
	v_cvt_pk_bf16_f32 v67, v68, v69
	flat_store_dwordx2 v[110:111], v[66:67]
	ds_write_b128 v99, v[34:37]
	v_or_b32_e32 v36, 64, v107
	v_or_b32_e32 v34, v36, v108
	v_ashrrev_i32_e32 v35, 31, v34
	v_lshlrev_b64 v[34:35], 11, v[34:35]
	ds_write_b128 v99, v[38:41] offset:64
	ds_write_b128 v99, v[42:45] offset:128
	ds_write_b128 v99, v[46:49] offset:192
	ds_write_b128 v99, v[50:53] offset:4352
	ds_write_b128 v99, v[54:57] offset:4416
	ds_write_b128 v99, v[58:61] offset:4480
	ds_write_b128 v99, v[62:65] offset:4544
	v_lshl_add_u64 v[38:39], v[0:1], 0, v[34:35]
	flat_load_dwordx2 v[40:41], v[38:39]
	v_or_b32_e32 v34, v36, v100
	v_ashrrev_i32_e32 v35, 31, v34
	v_lshlrev_b64 v[34:35], 11, v[34:35]
	v_lshl_add_u64 v[42:43], v[0:1], 0, v[34:35]
	flat_load_dwordx2 v[44:45], v[42:43]
	v_or_b32_e32 v34, v36, v101
	v_ashrrev_i32_e32 v35, 31, v34
	v_lshlrev_b64 v[34:35], 11, v[34:35]
	v_lshl_add_u64 v[46:47], v[0:1], 0, v[34:35]
	flat_load_dwordx2 v[48:49], v[46:47]
	v_or_b32_e32 v34, v36, v102
	v_ashrrev_i32_e32 v35, 31, v34
	v_lshlrev_b64 v[34:35], 11, v[34:35]
	v_lshl_add_u64 v[50:51], v[0:1], 0, v[34:35]
	flat_load_dwordx2 v[52:53], v[50:51]
	v_or_b32_e32 v34, v36, v103
	v_ashrrev_i32_e32 v35, 31, v34
	v_lshlrev_b64 v[34:35], 11, v[34:35]
	v_lshl_add_u64 v[54:55], v[0:1], 0, v[34:35]
	flat_load_dwordx2 v[56:57], v[54:55]
	v_or_b32_e32 v34, v36, v104
	v_ashrrev_i32_e32 v35, 31, v34
	v_lshlrev_b64 v[34:35], 11, v[34:35]
	v_lshl_add_u64 v[58:59], v[0:1], 0, v[34:35]
	flat_load_dwordx2 v[60:61], v[58:59]
	v_or_b32_e32 v34, v36, v105
	v_ashrrev_i32_e32 v35, 31, v34
	v_lshlrev_b64 v[34:35], 11, v[34:35]
	v_lshl_add_u64 v[62:63], v[0:1], 0, v[34:35]
	flat_load_dwordx2 v[64:65], v[62:63]
	v_or_b32_e32 v34, v36, v106
	v_ashrrev_i32_e32 v35, 31, v34
	v_lshlrev_b64 v[34:35], 11, v[34:35]
	v_lshl_add_u64 v[66:67], v[0:1], 0, v[34:35]
	flat_load_dwordx2 v[68:69], v[66:67]
	ds_read_b128 v[34:37], v98
	v_or_b32_e32 v76, 0x60, v107
	v_or_b32_e32 v70, v76, v108
	v_ashrrev_i32_e32 v71, 31, v70
	s_waitcnt vmcnt(0) lgkmcnt(0)
	v_and_b32_e32 v73, 0xffff0000, v40
	v_lshlrev_b32_e32 v72, 16, v40
	v_and_b32_e32 v75, 0xffff0000, v41
	v_lshlrev_b32_e32 v74, 16, v41
	v_pk_mul_f32 v[34:35], v[34:35], v[72:73]
	v_pk_mul_f32 v[36:37], v[36:37], v[74:75]
	v_cvt_pk_bf16_f32 v34, v34, v35
	v_cvt_pk_bf16_f32 v35, v36, v37
	flat_store_dwordx2 v[38:39], v[34:35]
	ds_read_b128 v[34:37], v98 offset:1088
	v_and_b32_e32 v39, 0xffff0000, v44
	v_lshlrev_b32_e32 v38, 16, v44
	v_and_b32_e32 v41, 0xffff0000, v45
	v_lshlrev_b32_e32 v40, 16, v45
	s_waitcnt lgkmcnt(0)
	v_pk_mul_f32 v[34:35], v[34:35], v[38:39]
	v_pk_mul_f32 v[36:37], v[36:37], v[40:41]
	v_cvt_pk_bf16_f32 v34, v34, v35
	v_cvt_pk_bf16_f32 v35, v36, v37
	flat_store_dwordx2 v[42:43], v[34:35]
	ds_read_b128 v[34:37], v98 offset:2176
	v_and_b32_e32 v39, 0xffff0000, v48
	v_lshlrev_b32_e32 v38, 16, v48
	v_and_b32_e32 v41, 0xffff0000, v49
	v_lshlrev_b32_e32 v40, 16, v49
	s_waitcnt lgkmcnt(0)
	v_pk_mul_f32 v[34:35], v[34:35], v[38:39]
	v_pk_mul_f32 v[36:37], v[36:37], v[40:41]
	v_cvt_pk_bf16_f32 v34, v34, v35
	v_cvt_pk_bf16_f32 v35, v36, v37
	flat_store_dwordx2 v[46:47], v[34:35]
	ds_read_b128 v[34:37], v98 offset:3264
	v_and_b32_e32 v39, 0xffff0000, v52
	v_lshlrev_b32_e32 v38, 16, v52
	v_and_b32_e32 v41, 0xffff0000, v53
	v_lshlrev_b32_e32 v40, 16, v53
	s_waitcnt lgkmcnt(0)
	v_pk_mul_f32 v[34:35], v[34:35], v[38:39]
	v_pk_mul_f32 v[36:37], v[36:37], v[40:41]
	v_cvt_pk_bf16_f32 v34, v34, v35
	v_cvt_pk_bf16_f32 v35, v36, v37
	flat_store_dwordx2 v[50:51], v[34:35]
	ds_read_b128 v[34:37], v98 offset:4352
	v_and_b32_e32 v39, 0xffff0000, v56
	v_lshlrev_b32_e32 v38, 16, v56
	v_and_b32_e32 v41, 0xffff0000, v57
	v_lshlrev_b32_e32 v40, 16, v57
	s_waitcnt lgkmcnt(0)
	v_pk_mul_f32 v[34:35], v[34:35], v[38:39]
	v_pk_mul_f32 v[36:37], v[36:37], v[40:41]
	v_cvt_pk_bf16_f32 v34, v34, v35
	v_cvt_pk_bf16_f32 v35, v36, v37
	flat_store_dwordx2 v[54:55], v[34:35]
	ds_read_b128 v[34:37], v98 offset:5440
	v_and_b32_e32 v39, 0xffff0000, v60
	v_lshlrev_b32_e32 v38, 16, v60
	v_and_b32_e32 v41, 0xffff0000, v61
	v_lshlrev_b32_e32 v40, 16, v61
	s_waitcnt lgkmcnt(0)
	v_pk_mul_f32 v[34:35], v[34:35], v[38:39]
	v_pk_mul_f32 v[36:37], v[36:37], v[40:41]
	v_cvt_pk_bf16_f32 v34, v34, v35
	v_cvt_pk_bf16_f32 v35, v36, v37
	flat_store_dwordx2 v[58:59], v[34:35]
	ds_read_b128 v[34:37], v98 offset:6528
	v_and_b32_e32 v39, 0xffff0000, v64
	v_lshlrev_b32_e32 v38, 16, v64
	v_and_b32_e32 v41, 0xffff0000, v65
	v_lshlrev_b32_e32 v40, 16, v65
	s_waitcnt lgkmcnt(0)
	v_pk_mul_f32 v[34:35], v[34:35], v[38:39]
	v_pk_mul_f32 v[36:37], v[36:37], v[40:41]
	v_cvt_pk_bf16_f32 v34, v34, v35
	v_cvt_pk_bf16_f32 v35, v36, v37
	flat_store_dwordx2 v[62:63], v[34:35]
	ds_read_b128 v[34:37], v98 offset:7616
	v_and_b32_e32 v39, 0xffff0000, v68
	v_lshlrev_b32_e32 v38, 16, v68
	v_and_b32_e32 v41, 0xffff0000, v69
	v_lshlrev_b32_e32 v40, 16, v69
	s_waitcnt lgkmcnt(0)
	v_pk_mul_f32 v[34:35], v[34:35], v[38:39]
	v_pk_mul_f32 v[36:37], v[36:37], v[40:41]
	v_cvt_pk_bf16_f32 v34, v34, v35
	v_cvt_pk_bf16_f32 v35, v36, v37
	flat_store_dwordx2 v[66:67], v[34:35]
	ds_write_b128 v99, v[2:5]
	v_lshlrev_b64 v[2:3], 11, v[70:71]
	ds_write_b128 v99, v[6:9] offset:64
	ds_write_b128 v99, v[10:13] offset:128
	ds_write_b128 v99, v[14:17] offset:192
	ds_write_b128 v99, v[18:21] offset:4352
	ds_write_b128 v99, v[22:25] offset:4416
	ds_write_b128 v99, v[26:29] offset:4480
	ds_write_b128 v99, v[30:33] offset:4544
	v_lshl_add_u64 v[4:5], v[0:1], 0, v[2:3]
	flat_load_dwordx2 v[6:7], v[4:5]
	v_or_b32_e32 v2, v76, v100
	v_ashrrev_i32_e32 v3, 31, v2
	v_lshlrev_b64 v[2:3], 11, v[2:3]
	v_lshl_add_u64 v[8:9], v[0:1], 0, v[2:3]
	flat_load_dwordx2 v[10:11], v[8:9]
	v_or_b32_e32 v2, v76, v101
	v_ashrrev_i32_e32 v3, 31, v2
	v_lshlrev_b64 v[2:3], 11, v[2:3]
	v_lshl_add_u64 v[12:13], v[0:1], 0, v[2:3]
	flat_load_dwordx2 v[14:15], v[12:13]
	v_or_b32_e32 v2, v76, v102
	v_ashrrev_i32_e32 v3, 31, v2
	v_lshlrev_b64 v[2:3], 11, v[2:3]
	v_lshl_add_u64 v[16:17], v[0:1], 0, v[2:3]
	flat_load_dwordx2 v[18:19], v[16:17]
	v_or_b32_e32 v2, v76, v103
	v_ashrrev_i32_e32 v3, 31, v2
	v_lshlrev_b64 v[2:3], 11, v[2:3]
	v_lshl_add_u64 v[20:21], v[0:1], 0, v[2:3]
	flat_load_dwordx2 v[22:23], v[20:21]
	v_or_b32_e32 v2, v76, v104
	v_ashrrev_i32_e32 v3, 31, v2
	v_lshlrev_b64 v[2:3], 11, v[2:3]
	v_lshl_add_u64 v[24:25], v[0:1], 0, v[2:3]
	flat_load_dwordx2 v[26:27], v[24:25]
	v_or_b32_e32 v2, v76, v105
	v_ashrrev_i32_e32 v3, 31, v2
	v_lshlrev_b64 v[2:3], 11, v[2:3]
	v_lshl_add_u64 v[28:29], v[0:1], 0, v[2:3]
	flat_load_dwordx2 v[30:31], v[28:29]
	v_or_b32_e32 v2, v76, v106
	v_ashrrev_i32_e32 v3, 31, v2
	v_lshlrev_b64 v[2:3], 11, v[2:3]
	v_lshl_add_u64 v[32:33], v[0:1], 0, v[2:3]
	flat_load_dwordx2 v[34:35], v[32:33]
	ds_read_b128 v[0:3], v98
	v_mov_b32_e32 v40, s51
	v_mov_b32_e32 v41, v132
	s_waitcnt vmcnt(0) lgkmcnt(0)
	v_and_b32_e32 v37, 0xffff0000, v6
	v_lshlrev_b32_e32 v36, 16, v6
	v_and_b32_e32 v39, 0xffff0000, v7
	v_lshlrev_b32_e32 v38, 16, v7
	v_pk_mul_f32 v[0:1], v[0:1], v[36:37]
	v_pk_mul_f32 v[2:3], v[2:3], v[38:39]
	v_cvt_pk_bf16_f32 v0, v0, v1
	v_cvt_pk_bf16_f32 v1, v2, v3
	flat_store_dwordx2 v[4:5], v[0:1]
	ds_read_b128 v[0:3], v98 offset:1088
	v_and_b32_e32 v5, 0xffff0000, v10
	v_lshlrev_b32_e32 v4, 16, v10
	v_and_b32_e32 v7, 0xffff0000, v11
	v_lshlrev_b32_e32 v6, 16, v11
	s_waitcnt lgkmcnt(0)
	v_pk_mul_f32 v[0:1], v[0:1], v[4:5]
	v_pk_mul_f32 v[2:3], v[2:3], v[6:7]
	v_cvt_pk_bf16_f32 v0, v0, v1
	v_cvt_pk_bf16_f32 v1, v2, v3
	flat_store_dwordx2 v[8:9], v[0:1]
	ds_read_b128 v[0:3], v98 offset:2176
	v_and_b32_e32 v5, 0xffff0000, v14
	v_lshlrev_b32_e32 v4, 16, v14
	v_and_b32_e32 v7, 0xffff0000, v15
	v_lshlrev_b32_e32 v6, 16, v15
	s_waitcnt lgkmcnt(0)
	v_pk_mul_f32 v[0:1], v[0:1], v[4:5]
	v_pk_mul_f32 v[2:3], v[2:3], v[6:7]
	v_cvt_pk_bf16_f32 v0, v0, v1
	v_cvt_pk_bf16_f32 v1, v2, v3
	flat_store_dwordx2 v[12:13], v[0:1]
	ds_read_b128 v[0:3], v98 offset:3264
	v_and_b32_e32 v5, 0xffff0000, v18
	v_lshlrev_b32_e32 v4, 16, v18
	v_and_b32_e32 v7, 0xffff0000, v19
	v_lshlrev_b32_e32 v6, 16, v19
	s_waitcnt lgkmcnt(0)
	v_pk_mul_f32 v[0:1], v[0:1], v[4:5]
	v_pk_mul_f32 v[2:3], v[2:3], v[6:7]
	v_cvt_pk_bf16_f32 v0, v0, v1
	v_cvt_pk_bf16_f32 v1, v2, v3
	flat_store_dwordx2 v[16:17], v[0:1]
	ds_read_b128 v[0:3], v98 offset:4352
	v_and_b32_e32 v5, 0xffff0000, v22
	v_lshlrev_b32_e32 v4, 16, v22
	v_and_b32_e32 v7, 0xffff0000, v23
	v_lshlrev_b32_e32 v6, 16, v23
	s_waitcnt lgkmcnt(0)
	v_pk_mul_f32 v[0:1], v[0:1], v[4:5]
	v_pk_mul_f32 v[2:3], v[2:3], v[6:7]
	v_cvt_pk_bf16_f32 v0, v0, v1
	v_cvt_pk_bf16_f32 v1, v2, v3
	flat_store_dwordx2 v[20:21], v[0:1]
	ds_read_b128 v[0:3], v98 offset:5440
	v_and_b32_e32 v5, 0xffff0000, v26
	v_lshlrev_b32_e32 v4, 16, v26
	v_and_b32_e32 v7, 0xffff0000, v27
	v_lshlrev_b32_e32 v6, 16, v27
	s_waitcnt lgkmcnt(0)
	v_pk_mul_f32 v[0:1], v[0:1], v[4:5]
	v_pk_mul_f32 v[2:3], v[2:3], v[6:7]
	v_cvt_pk_bf16_f32 v0, v0, v1
	v_cvt_pk_bf16_f32 v1, v2, v3
	flat_store_dwordx2 v[24:25], v[0:1]
	ds_read_b128 v[0:3], v98 offset:6528
	v_and_b32_e32 v5, 0xffff0000, v30
	v_lshlrev_b32_e32 v4, 16, v30
	v_and_b32_e32 v7, 0xffff0000, v31
	v_lshlrev_b32_e32 v6, 16, v31
	s_waitcnt lgkmcnt(0)
	v_pk_mul_f32 v[0:1], v[0:1], v[4:5]
	v_pk_mul_f32 v[2:3], v[2:3], v[6:7]
	v_cvt_pk_bf16_f32 v0, v0, v1
	v_cvt_pk_bf16_f32 v1, v2, v3
	flat_store_dwordx2 v[28:29], v[0:1]
	ds_read_b128 v[0:3], v98 offset:7616
	v_and_b32_e32 v5, 0xffff0000, v34
	v_lshlrev_b32_e32 v4, 16, v34
	v_and_b32_e32 v7, 0xffff0000, v35
	v_lshlrev_b32_e32 v6, 16, v35
	s_waitcnt lgkmcnt(0)
	v_pk_mul_f32 v[0:1], v[0:1], v[4:5]
	v_pk_mul_f32 v[2:3], v[2:3], v[6:7]
	v_cvt_pk_bf16_f32 v0, v0, v1
	v_cvt_pk_bf16_f32 v1, v2, v3
	flat_store_dwordx2 v[32:33], v[0:1]
	ds_read_b64 v[128:129], v40
	s_waitcnt lgkmcnt(0)
	v_lshl_add_u64 v[2:3], v[128:129], 0, s[42:43]
	v_lshlrev_b32_e32 v5, 4, v41
	v_and_b32_e32 v0, 32, v41
	v_lshrrev_b32_e32 v1, 1, v41
	v_bitop3_b32 v0, v5, v0, 48 bitop3:0x6c
	v_bfe_u32 v16, v41, 2, 4
	v_ashrrev_i32_e32 v17, 3, v41
	v_and_b32_e32 v9, 0xfffffc00, v5
	v_and_b32_e32 v18, 32, v1
	v_add_u32_e32 v1, 0x2000, v5
	v_lshrrev_b32_e32 v19, 1, v0
	v_add_u32_e32 v8, 0x4000, v5
	v_add_u32_e32 v5, 0x6000, v5
	v_and_or_b32 v4, v17, s44, v16
	v_ashrrev_i32_e32 v20, 7, v1
	v_or_b32_e32 v10, v19, v18
	v_ashrrev_i32_e32 v21, 7, v8
	v_ashrrev_i32_e32 v22, 7, v5
	v_and_or_b32 v6, v20, s44, v16
	v_lshl_add_u64 v[0:1], v[128:129], 0, s[36:37]
	v_lshl_or_b32 v130, v4, 10, v10
	v_and_or_b32 v8, v21, s44, v16
	v_and_or_b32 v5, v22, s44, v16
	v_add_u32_e32 v151, 0, v9
	v_lshl_or_b32 v4, v6, 10, v10
	v_lshl_add_u64 v[6:7], v[0:1], 0, s[4:5]
	v_lshl_or_b32 v8, v8, 10, v10
	v_lshl_or_b32 v10, v5, 10, v10
	v_add_u32_e32 v5, 0x8000, v151
	v_lshlrev_b64 v[12:13], 1, v[130:131]
	v_readfirstlane_b32 s0, v151
	v_add_co_u32_e32 v14, vcc, v6, v12
	v_addc_co_u32_e32 v15, vcc, v7, v13, vcc
	s_mov_b32 m0, s0
	v_readfirstlane_b32 s0, v5
	v_mov_b32_e32 v5, v131
	v_add_u32_e32 v9, 0x2000, v151
	global_load_lds_dwordx4 v[14:15], off
	v_add_co_u32_e32 v12, vcc, v2, v12
	v_addc_co_u32_e32 v13, vcc, v3, v13, vcc
	s_mov_b32 m0, s0
	v_lshlrev_b64 v[4:5], 1, v[4:5]
	v_readfirstlane_b32 s0, v9
	v_add_u32_e32 v9, 0xa000, v151
	global_load_lds_dwordx4 v[12:13], off
	v_add_co_u32_e32 v12, vcc, v6, v4
	v_addc_co_u32_e32 v13, vcc, v7, v5, vcc
	s_mov_b32 m0, s0
	v_readfirstlane_b32 s0, v9
	global_load_lds_dwordx4 v[12:13], off
	v_add_co_u32_e32 v4, vcc, v2, v4
	v_addc_co_u32_e32 v5, vcc, v3, v5, vcc
	s_mov_b32 m0, s0
	v_mov_b32_e32 v9, v131
	v_add_u32_e32 v11, 0x4000, v151
	global_load_lds_dwordx4 v[4:5], off
	v_lshlrev_b64 v[4:5], 1, v[8:9]
	v_readfirstlane_b32 s0, v11
	v_add_co_u32_e32 v8, vcc, v6, v4
	v_addc_co_u32_e32 v9, vcc, v7, v5, vcc
	s_mov_b32 m0, s0
	v_add_co_u32_e32 v4, vcc, v2, v4
	v_addc_co_u32_e32 v5, vcc, v3, v5, vcc
	global_load_lds_dwordx4 v[8:9], off
	v_add_u32_e32 v8, 0xc000, v151
	v_mov_b32_e32 v11, v131
	v_readfirstlane_b32 s0, v8
	s_mov_b32 m0, s0
	v_add_u32_e32 v8, 0x6000, v151
	global_load_lds_dwordx4 v[4:5], off
	v_lshlrev_b64 v[4:5], 1, v[10:11]
	v_readfirstlane_b32 s0, v8
	v_add_co_u32_e32 v6, vcc, v6, v4
	v_addc_co_u32_e32 v7, vcc, v7, v5, vcc
	s_mov_b32 m0, s0
	v_add_co_u32_e32 v4, vcc, v2, v4
	v_addc_co_u32_e32 v5, vcc, v3, v5, vcc
	global_load_lds_dwordx4 v[6:7], off
	v_add_u32_e32 v6, 0xe000, v151
	v_and_b32_e32 v23, 15, v41
	v_readfirstlane_b32 s0, v6
	s_mov_b32 m0, s0
	v_lshlrev_b32_e32 v6, 2, v41
	global_load_lds_dwordx4 v[4:5], off
	v_and_b32_e32 v4, 48, v41
	v_lshlrev_b32_e32 v5, 6, v23
	v_and_b32_e32 v6, 32, v6
	v_bitop3_b32 v152, v5, v6, v4 bitop3:0x36
	v_lshlrev_b32_e32 v5, 7, v41
	v_and_b32_e32 v153, 0x6000, v5
	v_lshlrev_b32_e32 v5, 6, v41
	v_and_b32_e32 v154, 0xffffc000, v5
	v_and_b32_e32 v5, 0x3c0, v5
	v_bitop3_b32 v156, v5, v6, v4 bitop3:0x36
	v_lshlrev_b32_e32 v4, 10, v22
	v_and_or_b32 v4, v4, s45, v19
	v_lshlrev_b32_e32 v10, 10, v16
	v_lshlrev_b32_e32 v6, 10, v21
	v_or3_b32 v130, v4, v10, v18
	v_and_or_b32 v6, v6, s45, v19
	v_lshlrev_b32_e32 v8, 10, v20
	v_lshlrev_b64 v[4:5], 1, v[130:131]
	v_or3_b32 v130, v6, v10, v18
	v_and_or_b32 v8, v8, s45, v19
	v_lshlrev_b32_e32 v11, 10, v17
	v_lshlrev_b64 v[6:7], 1, v[130:131]
	v_or3_b32 v130, v8, v10, v18
	v_and_or_b32 v11, v11, s45, v19
	s_nop 0
	v_lshl_add_u64 v[2:3], v[2:3], 0, s[6:7]
	v_lshlrev_b64 v[8:9], 1, v[130:131]
	v_or3_b32 v130, v11, v10, v18
	v_lshl_add_u64 v[0:1], v[0:1], 0, s[8:9]
	v_add_co_u32_e32 v138, vcc, v2, v8
	v_addc_co_u32_e32 v139, vcc, v3, v9, vcc
	v_lshlrev_b64 v[10:11], 1, v[130:131]
	v_add_co_u32_e32 v146, vcc, v0, v8
	v_addc_co_u32_e32 v147, vcc, v1, v9, vcc
	v_or_b32_e32 v155, 0x800, v154
	v_or_b32_e32 v157, 0x1000, v154
	v_or_b32_e32 v158, 0x1800, v154
	v_or_b32_e32 v159, 0x2000, v154
	v_or_b32_e32 v160, 0x2800, v154
	v_or_b32_e32 v161, 0x3000, v154
	v_or_b32_e32 v162, 0x3800, v154
	v_add_co_u32_e32 v134, vcc, v2, v4
	v_addc_co_u32_e32 v135, vcc, v3, v5, vcc
	v_add_co_u32_e32 v136, vcc, v2, v6
	v_addc_co_u32_e32 v137, vcc, v3, v7, vcc
	v_add_co_u32_e32 v140, vcc, v2, v10
	v_addc_co_u32_e32 v141, vcc, v3, v11, vcc
	v_add_co_u32_e32 v142, vcc, v0, v4
	v_addc_co_u32_e32 v143, vcc, v1, v5, vcc
	v_add_co_u32_e32 v144, vcc, v0, v6
	v_addc_co_u32_e32 v145, vcc, v1, v7, vcc
	v_add_co_u32_e32 v148, vcc, v0, v10
	v_addc_co_u32_e32 v149, vcc, v1, v11, vcc
	s_mov_b64 s[42:43], 0
	s_waitcnt vmcnt(0) lgkmcnt(0)
	s_barrier
	v_readfirstlane_b32 s100, v151
	s_and_b32 s0, s29, 0x10000
	s_xor_b32 s53, s0, 0x10000
	s_add_i32 s0, s0, 0
	v_add3_u32 v130, s0, v152, v153
	v_add3_u32 v163, s0, v152, v154
	v_add3_u32 v196, s0, v156, v155
	v_add3_u32 v197, s0, v156, v157
	v_add3_u32 v198, s0, v156, v158
	v_add3_u32 v199, s0, v156, v159
	v_add3_u32 v200, s0, v156, v160
	v_add3_u32 v201, s0, v156, v161
	v_add3_u32 v202, s0, v156, v162
	ds_read_b128 v[180:183], v130 offset:32768
	ds_read_b128 v[164:167], v163
	ds_read_b128 v[168:171], v196
	ds_read_b128 v[172:175], v197
	ds_read_b128 v[176:179], v198
	ds_read_b128 v[184:187], v130 offset:34816
	ds_read_b128 v[188:191], v130 offset:36864
	ds_read_b128 v[192:195], v130 offset:38912
	s_add_i32 s101, s100, s53
	v_readfirstlane_b32 s98, v148
	v_readfirstlane_b32 s99, v149
	v_readfirstlane_b32 vcc_lo, v140
	v_readfirstlane_b32 vcc_hi, v141
	s_sub_u32 s98, s98, 0x1000000
	s_subb_u32 s99, s99, 0
	s_sub_u32 vcc_lo, vcc_lo, 0x1000000
	s_subb_u32 vcc_hi, vcc_hi, 0
	v_subrev_u32_e32 v148, s98, v148
	v_subrev_u32_e32 v140, vcc_lo, v140
	v_subrev_u32_e32 v146, s98, v146
	v_subrev_u32_e32 v138, vcc_lo, v138
	v_subrev_u32_e32 v144, s98, v144
	v_subrev_u32_e32 v136, vcc_lo, v136
	v_subrev_u32_e32 v142, s98, v142
	v_subrev_u32_e32 v134, vcc_lo, v134
	s_mov_b32 m0, s101
	s_nop 0
	global_load_lds_dwordx4 v148, s[98:99]
	s_add_i32 m0, s101, 0x8000
	s_nop 0
	global_load_lds_dwordx4 v140, vcc
	s_add_i32 m0, s101, 0x2000
	s_nop 0
	global_load_lds_dwordx4 v146, s[98:99]
	s_add_i32 m0, s101, 0xa000
	s_nop 0
	global_load_lds_dwordx4 v138, vcc
	s_add_i32 m0, s101, 0x4000
	s_nop 0
	global_load_lds_dwordx4 v144, s[98:99]
	s_add_i32 m0, s101, 0xc000
	s_nop 0
	global_load_lds_dwordx4 v136, vcc
	s_add_i32 m0, s101, 0x6000
	s_nop 0
	global_load_lds_dwordx4 v142, s[98:99]
	s_add_i32 m0, s101, 0xe000
	s_nop 0
	global_load_lds_dwordx4 v134, vcc

.Lex_795:
	s_waitcnt lgkmcnt(0)
	v_add3_u32 v130, s46, v156, v162
	v_add3_u32 v151, s46, v156, v161
	v_add3_u32 v206, s46, v156, v160
	v_add3_u32 v198, s46, v156, v159
	v_add3_u32 v186, s46, v156, v158
	v_add3_u32 v187, s46, v156, v157
	v_add3_u32 v188, s46, v156, v155
	v_add3_u32 v189, s46, v152, v154
	v_add3_u32 v190, s47, v152, v153
	ds_read_b128 v[134:137], v130
	ds_read_b128 v[138:141], v151
	ds_read_b128 v[142:145], v206
	ds_read_b128 v[146:149], v198
	ds_read_b128 v[158:161], v186
	ds_read_b128 v[162:165], v187
	ds_read_b128 v[166:169], v188
	ds_read_b128 v[154:157], v189
	ds_read_b128 v[170:173], v190
	s_waitcnt lgkmcnt(0)
	v_mfma_f32_16x16x32_bf16 v[16:19], v[170:173], v[138:141], v[16:19]
	v_mfma_f32_16x16x32_bf16 v[174:177], v[170:173], v[134:137], v[36:39]
	s_nop 2
	ds_read_b128 v[36:39], v190 offset:2048
	s_waitcnt lgkmcnt(0)
	v_mfma_f32_16x16x32_bf16 v[12:15], v[36:39], v[138:141], v[12:15]
	v_mfma_f32_16x16x32_bf16 v[60:63], v[170:173], v[146:149], v[60:63]
	v_mfma_f32_16x16x32_bf16 v[28:31], v[36:39], v[134:137], v[28:31]
	v_mfma_f32_16x16x32_bf16 v[56:59], v[36:39], v[146:149], v[56:59]
	ds_read_b128 v[178:181], v190 offset:4096
	s_waitcnt lgkmcnt(0)
	v_mfma_f32_16x16x32_bf16 v[182:185], v[178:181], v[134:137], v[20:23]
	v_mfma_f32_16x16x32_bf16 v[52:55], v[178:181], v[146:149], v[52:55]
	s_nop 1
	ds_read_b128 v[20:23], v190 offset:6144
	s_waitcnt lgkmcnt(0)
	v_mfma_f32_16x16x32_bf16 v[134:137], v[20:23], v[134:137], v[8:11]
	v_mfma_f32_16x16x32_bf16 v[8:11], v[20:23], v[154:157], v[112:115]
	v_mfma_f32_16x16x32_bf16 v[112:115], v[20:23], v[158:161], v[64:67]
	v_mfma_f32_16x16x32_bf16 v[64:67], v[178:181], v[154:157], v[116:119]
	v_mfma_f32_16x16x32_bf16 v[116:119], v[178:181], v[158:161], v[68:71]
	v_mfma_f32_16x16x32_bf16 v[68:71], v[36:39], v[154:157], v[120:123]
	v_mfma_f32_16x16x32_bf16 v[120:123], v[36:39], v[158:161], v[72:75]
	v_mfma_f32_16x16x32_bf16 v[72:75], v[170:173], v[154:157], v[124:127]
	v_mfma_f32_16x16x32_bf16 v[124:127], v[170:173], v[158:161], v[76:79]
	v_mfma_f32_16x16x32_bf16 v[48:51], v[20:23], v[146:149], v[48:51]
	v_mfma_f32_16x16x32_bf16 v[146:149], v[170:173], v[142:145], v[44:47]
	v_mfma_f32_16x16x32_bf16 v[152:155], v[36:39], v[142:145], v[40:43]
	v_mfma_f32_16x16x32_bf16 v[156:159], v[178:181], v[142:145], v[32:35]
	v_mfma_f32_16x16x32_bf16 v[24:27], v[20:23], v[142:145], v[24:27]
	v_mfma_f32_16x16x32_bf16 v[142:145], v[178:181], v[138:141], v[4:7]
	v_mfma_f32_16x16x32_bf16 v[108:111], v[170:173], v[166:169], v[108:111]
	v_mfma_f32_16x16x32_bf16 v[92:95], v[170:173], v[162:165], v[92:95]
	v_mfma_f32_16x16x32_bf16 v[104:107], v[36:39], v[166:169], v[104:107]
	v_mfma_f32_16x16x32_bf16 v[88:91], v[36:39], v[162:165], v[88:91]
	v_mfma_f32_16x16x32_bf16 v[100:103], v[178:181], v[166:169], v[100:103]
	v_mfma_f32_16x16x32_bf16 v[84:87], v[178:181], v[162:165], v[84:87]
	v_mfma_f32_16x16x32_bf16 v[96:99], v[20:23], v[166:169], v[96:99]
	v_mfma_f32_16x16x32_bf16 v[80:83], v[20:23], v[162:165], v[80:83]
	v_mfma_f32_16x16x32_bf16 v[20:23], v[20:23], v[138:141], v[0:3]
	ds_read_b128 v[138:141], v190 offset:1024
	ds_read_b128 v[160:163], v190 offset:3072
	ds_read_b128 v[164:167], v190 offset:5120
	ds_read_b128 v[168:171], v190 offset:7168
	ds_read_b128 v[0:3], v189 offset:1024
	ds_read_b128 v[4:7], v188 offset:1024
	ds_read_b128 v[32:35], v187 offset:1024
	ds_read_b128 v[36:39], v186 offset:1024
	s_waitcnt lgkmcnt(3)
	v_mfma_f32_16x16x32_bf16 v[178:181], v[138:141], v[0:3], v[72:75]
	v_mfma_f32_16x16x32_bf16 v[186:189], v[160:163], v[0:3], v[68:71]
	v_mfma_f32_16x16x32_bf16 v[190:193], v[164:167], v[0:3], v[64:67]
	v_mfma_f32_16x16x32_bf16 v[194:197], v[168:171], v[0:3], v[8:11]
	ds_read_b128 v[0:3], v198 offset:1024
	s_waitcnt lgkmcnt(3)
	v_mfma_f32_16x16x32_bf16 v[108:111], v[138:141], v[4:7], v[108:111]
	v_mfma_f32_16x16x32_bf16 v[104:107], v[160:163], v[4:7], v[104:107]
	v_mfma_f32_16x16x32_bf16 v[198:201], v[164:167], v[4:7], v[100:103]
	v_mfma_f32_16x16x32_bf16 v[202:205], v[168:171], v[4:7], v[96:99]
	ds_read_b128 v[4:7], v206 offset:1024
	s_waitcnt lgkmcnt(3)
	v_mfma_f32_16x16x32_bf16 v[64:67], v[138:141], v[32:35], v[92:95]
	v_mfma_f32_16x16x32_bf16 v[68:71], v[160:163], v[32:35], v[88:91]
	v_mfma_f32_16x16x32_bf16 v[72:75], v[164:167], v[32:35], v[84:87]
	v_mfma_f32_16x16x32_bf16 v[76:79], v[168:171], v[32:35], v[80:83]
	ds_read_b128 v[96:99], v151 offset:1024
	s_waitcnt lgkmcnt(3)
	v_mfma_f32_16x16x32_bf16 v[80:83], v[138:141], v[36:39], v[124:127]
	v_mfma_f32_16x16x32_bf16 v[84:87], v[160:163], v[36:39], v[120:123]
	v_mfma_f32_16x16x32_bf16 v[88:91], v[164:167], v[36:39], v[116:119]
	v_mfma_f32_16x16x32_bf16 v[92:95], v[168:171], v[36:39], v[112:115]
	ds_read_b128 v[100:103], v130 offset:1024
	s_waitcnt lgkmcnt(3)
	v_mfma_f32_16x16x32_bf16 v[32:35], v[138:141], v[0:3], v[60:63]
	v_mfma_f32_16x16x32_bf16 v[36:39], v[160:163], v[0:3], v[56:59]
	v_mfma_f32_16x16x32_bf16 v[40:43], v[164:167], v[0:3], v[52:55]
	v_mfma_f32_16x16x32_bf16 v[44:47], v[168:171], v[0:3], v[48:51]
	s_waitcnt lgkmcnt(2)
	v_mfma_f32_16x16x32_bf16 v[48:51], v[138:141], v[4:7], v[146:149]
	v_mfma_f32_16x16x32_bf16 v[52:55], v[160:163], v[4:7], v[152:155]
	v_mfma_f32_16x16x32_bf16 v[56:59], v[164:167], v[4:7], v[156:159]
	v_mfma_f32_16x16x32_bf16 v[60:63], v[168:171], v[4:7], v[24:27]
	s_waitcnt lgkmcnt(1)
	v_mfma_f32_16x16x32_bf16 v[0:3], v[138:141], v[96:99], v[16:19]
	v_mfma_f32_16x16x32_bf16 v[4:7], v[160:163], v[96:99], v[12:15]
	v_mfma_f32_16x16x32_bf16 v[8:11], v[164:167], v[96:99], v[142:145]
	v_mfma_f32_16x16x32_bf16 v[12:15], v[168:171], v[96:99], v[20:23]
	s_waitcnt lgkmcnt(0)
	v_mfma_f32_16x16x32_bf16 v[16:19], v[138:141], v[100:103], v[174:177]
	v_mfma_f32_16x16x32_bf16 v[20:23], v[160:163], v[100:103], v[28:31]
	v_mfma_f32_16x16x32_bf16 v[24:27], v[164:167], v[100:103], v[182:185]
	v_mfma_f32_16x16x32_bf16 v[28:31], v[168:171], v[100:103], v[134:137]
	v_lshrrev_b32_e32 v96, 6, v150
	v_lshlrev_b32_e32 v98, 2, v150
	v_and_b32_e32 v97, 15, v150
	v_mul_lo_u32 v96, v96, s48
	v_and_b32_e32 v112, 60, v98
	v_bfe_u32 v99, v150, 4, 2
	v_add_u32_e32 v96, s46, v96
	v_and_b32_e32 v100, 48, v150
	v_lshlrev_b32_e32 v98, 2, v112
	v_mul_u32_u24_e32 v101, 0x110, v99
	v_mul_u32_u24_e32 v97, 0x110, v97
	v_add3_u32 v98, v96, v98, v101
	v_add3_u32 v101, v96, v100, v97
	s_waitcnt vmcnt(0)
	s_barrier
	ds_write_b128 v101, v[178:181]
	ds_write_b128 v101, v[186:189] offset:64
	ds_write_b128 v101, v[190:193] offset:128
	ds_write_b128 v101, v[194:197] offset:192
	ds_write_b128 v101, v[108:111] offset:4352
	ds_write_b128 v101, v[104:107] offset:4416
	ds_write_b128 v101, v[198:201] offset:4480
	ds_write_b128 v101, v[202:205] offset:4544
	ds_read_b128 v[102:105], v98
	v_ashrrev_i32_e32 v113, 1, v150
	v_and_b32_e32 v96, 0xffffff80, v113
	v_and_or_b32 v106, v150, s49, v112
	v_add_u32_e32 v100, s28, v96
	s_waitcnt lgkmcnt(0)
	v_mul_f32_e32 v102, 0xbfb8aa3b, v102
	v_mul_f32_e32 v103, 0xbfb8aa3b, v103
	v_mul_f32_e32 v104, 0xbfb8aa3b, v104
	v_mul_f32_e32 v105, 0xbfb8aa3b, v105
	v_exp_f32_e32 v102, v102
	v_exp_f32_e32 v103, v103
	v_exp_f32_e32 v104, v104
	v_exp_f32_e32 v105, v105
	v_add_f32_e32 v102, 1.0, v102
	v_add_f32_e32 v103, 1.0, v103
	v_add_f32_e32 v104, 1.0, v104
	v_add_f32_e32 v105, 1.0, v105
	v_rcp_f32_e32 v102, v102
	v_rcp_f32_e32 v103, v103
	v_rcp_f32_e32 v104, v104
	v_rcp_f32_e32 v105, v105
	v_lshl_add_u64 v[96:97], v[128:129], 0, s[38:39]
	v_lshlrev_b32_e32 v130, 1, v106
	v_cvt_pk_bf16_f32 v102, v102, v103
	v_cvt_pk_bf16_f32 v103, v104, v105
	v_or_b32_e32 v104, v100, v99
	v_lshl_add_u64 v[96:97], v[96:97], 0, v[130:131]
	v_ashrrev_i32_e32 v105, 31, v104
	v_lshl_add_u64 v[96:97], v[96:97], 0, s[26:27]
	v_lshlrev_b64 v[104:105], 11, v[104:105]
	v_lshl_add_u64 v[104:105], v[96:97], 0, v[104:105]
	flat_store_dwordx2 v[104:105], v[102:103]
	ds_read_b128 v[102:105], v98 offset:1088
	v_mov_b32_e32 v150, v132
	s_waitcnt lgkmcnt(0)
	v_mul_f32_e32 v102, 0xbfb8aa3b, v102
	v_exp_f32_e32 v102, v102
	v_mul_f32_e32 v103, 0xbfb8aa3b, v103
	v_exp_f32_e32 v103, v103
	v_add_f32_e32 v102, 1.0, v102
	v_rcp_f32_e32 v106, v102
	v_add_f32_e32 v102, 1.0, v103
	v_mul_f32_e32 v103, 0xbfb8aa3b, v104
	v_exp_f32_e32 v103, v103
	v_mul_f32_e32 v104, 0xbfb8aa3b, v105
	v_exp_f32_e32 v104, v104
	v_rcp_f32_e32 v105, v102
	v_add_f32_e32 v102, 1.0, v103
	v_rcp_f32_e32 v103, v102
	v_add_f32_e32 v102, 1.0, v104
	v_rcp_f32_e32 v107, v102
	v_or_b32_e32 v102, 4, v99
	v_cvt_pk_bf16_f32 v104, v106, v105
	v_or_b32_e32 v106, v100, v102
	v_cvt_pk_bf16_f32 v105, v103, v107
	v_ashrrev_i32_e32 v107, 31, v106
	v_lshlrev_b64 v[106:107], 11, v[106:107]
	v_lshl_add_u64 v[106:107], v[96:97], 0, v[106:107]
	flat_store_dwordx2 v[106:107], v[104:105]
	ds_read_b128 v[104:107], v98 offset:2176
	s_waitcnt lgkmcnt(0)
	v_mul_f32_e32 v103, 0xbfb8aa3b, v104
	v_exp_f32_e32 v103, v103
	v_mul_f32_e32 v104, 0xbfb8aa3b, v105
	v_exp_f32_e32 v104, v104
	v_add_f32_e32 v103, 1.0, v103
	v_rcp_f32_e32 v105, v103
	v_add_f32_e32 v103, 1.0, v104
	v_mul_f32_e32 v104, 0xbfb8aa3b, v106
	v_exp_f32_e32 v104, v104
	v_mul_f32_e32 v106, 0xbfb8aa3b, v107
	v_exp_f32_e32 v106, v106
	v_rcp_f32_e32 v107, v103
	v_add_f32_e32 v103, 1.0, v104
	v_rcp_f32_e32 v108, v103
	v_add_f32_e32 v103, 1.0, v106
	v_rcp_f32_e32 v106, v103
	v_or_b32_e32 v103, 8, v99
	v_cvt_pk_bf16_f32 v104, v105, v107
	v_cvt_pk_bf16_f32 v105, v108, v106
	v_or_b32_e32 v106, v100, v103
	v_ashrrev_i32_e32 v107, 31, v106
	v_lshlrev_b64 v[106:107], 11, v[106:107]
	v_lshl_add_u64 v[106:107], v[96:97], 0, v[106:107]
	flat_store_dwordx2 v[106:107], v[104:105]
	ds_read_b128 v[104:107], v98 offset:3264
	s_waitcnt lgkmcnt(0)
	v_mul_f32_e32 v104, 0xbfb8aa3b, v104
	v_exp_f32_e32 v104, v104
	v_mul_f32_e32 v105, 0xbfb8aa3b, v105
	v_exp_f32_e32 v105, v105
	v_add_f32_e32 v104, 1.0, v104
	v_rcp_f32_e32 v108, v104
	v_add_f32_e32 v104, 1.0, v105
	v_mul_f32_e32 v105, 0xbfb8aa3b, v106
	v_exp_f32_e32 v105, v105
	v_mul_f32_e32 v106, 0xbfb8aa3b, v107
	v_exp_f32_e32 v106, v106
	v_rcp_f32_e32 v107, v104
	v_add_f32_e32 v104, 1.0, v105
	v_rcp_f32_e32 v105, v104
	v_add_f32_e32 v104, 1.0, v106
	v_rcp_f32_e32 v109, v104
	v_or_b32_e32 v104, 12, v99
	v_cvt_pk_bf16_f32 v106, v108, v107
	v_or_b32_e32 v108, v100, v104
	v_cvt_pk_bf16_f32 v107, v105, v109
	v_ashrrev_i32_e32 v109, 31, v108
	v_lshlrev_b64 v[108:109], 11, v[108:109]
	v_lshl_add_u64 v[108:109], v[96:97], 0, v[108:109]
	flat_store_dwordx2 v[108:109], v[106:107]
	ds_read_b128 v[106:109], v98 offset:4352
	s_waitcnt lgkmcnt(0)
	v_mul_f32_e32 v105, 0xbfb8aa3b, v106
	v_exp_f32_e32 v105, v105
	v_mul_f32_e32 v106, 0xbfb8aa3b, v107
	v_exp_f32_e32 v106, v106
	v_add_f32_e32 v105, 1.0, v105
	v_rcp_f32_e32 v107, v105
	v_add_f32_e32 v105, 1.0, v106
	v_mul_f32_e32 v106, 0xbfb8aa3b, v108
	v_exp_f32_e32 v106, v106
	v_mul_f32_e32 v108, 0xbfb8aa3b, v109
	v_exp_f32_e32 v108, v108
	v_rcp_f32_e32 v109, v105
	v_add_f32_e32 v105, 1.0, v106
	v_rcp_f32_e32 v110, v105
	v_add_f32_e32 v105, 1.0, v108
	v_rcp_f32_e32 v108, v105
	v_or_b32_e32 v105, 16, v99
	v_cvt_pk_bf16_f32 v106, v107, v109
	v_cvt_pk_bf16_f32 v107, v110, v108
	v_or_b32_e32 v108, v100, v105
	v_ashrrev_i32_e32 v109, 31, v108
	v_lshlrev_b64 v[108:109], 11, v[108:109]
	v_lshl_add_u64 v[108:109], v[96:97], 0, v[108:109]
	flat_store_dwordx2 v[108:109], v[106:107]
	ds_read_b128 v[106:109], v98 offset:5440
	s_waitcnt lgkmcnt(0)
	v_mul_f32_e32 v106, 0xbfb8aa3b, v106
	v_exp_f32_e32 v106, v106
	v_mul_f32_e32 v107, 0xbfb8aa3b, v107
	v_exp_f32_e32 v107, v107
	v_add_f32_e32 v106, 1.0, v106
	v_rcp_f32_e32 v110, v106
	v_add_f32_e32 v106, 1.0, v107
	v_mul_f32_e32 v107, 0xbfb8aa3b, v108
	v_exp_f32_e32 v107, v107
	v_mul_f32_e32 v108, 0xbfb8aa3b, v109
	v_exp_f32_e32 v108, v108
	v_rcp_f32_e32 v109, v106
	v_add_f32_e32 v106, 1.0, v107
	v_rcp_f32_e32 v107, v106
	v_add_f32_e32 v106, 1.0, v108
	v_rcp_f32_e32 v111, v106
	v_or_b32_e32 v106, 20, v99
	v_cvt_pk_bf16_f32 v108, v110, v109
	v_or_b32_e32 v110, v100, v106
	v_cvt_pk_bf16_f32 v109, v107, v111
	v_ashrrev_i32_e32 v111, 31, v110
	v_lshlrev_b64 v[110:111], 11, v[110:111]
	v_lshl_add_u64 v[110:111], v[96:97], 0, v[110:111]
	flat_store_dwordx2 v[110:111], v[108:109]
	ds_read_b128 v[108:111], v98 offset:6528
	s_waitcnt lgkmcnt(0)
	v_mul_f32_e32 v107, 0xbfb8aa3b, v108
	v_exp_f32_e32 v107, v107
	v_mul_f32_e32 v108, 0xbfb8aa3b, v109
	v_exp_f32_e32 v108, v108
	v_add_f32_e32 v107, 1.0, v107
	v_rcp_f32_e32 v109, v107
	v_add_f32_e32 v107, 1.0, v108
	v_mul_f32_e32 v108, 0xbfb8aa3b, v110
	v_exp_f32_e32 v108, v108
	v_mul_f32_e32 v110, 0xbfb8aa3b, v111
	v_exp_f32_e32 v110, v110
	v_rcp_f32_e32 v111, v107
	v_add_f32_e32 v107, 1.0, v108
	v_rcp_f32_e32 v112, v107
	v_add_f32_e32 v107, 1.0, v110
	v_rcp_f32_e32 v110, v107
	v_or_b32_e32 v107, 24, v99
	v_cvt_pk_bf16_f32 v108, v109, v111
	v_cvt_pk_bf16_f32 v109, v112, v110
	v_or_b32_e32 v110, v100, v107
	v_ashrrev_i32_e32 v111, 31, v110
	v_lshlrev_b64 v[110:111], 11, v[110:111]
	v_lshl_add_u64 v[110:111], v[96:97], 0, v[110:111]
	flat_store_dwordx2 v[110:111], v[108:109]
	ds_read_b128 v[108:111], v98 offset:7616
	s_waitcnt lgkmcnt(0)
	v_mul_f32_e32 v108, 0xbfb8aa3b, v108
	v_exp_f32_e32 v108, v108
	v_mul_f32_e32 v109, 0xbfb8aa3b, v109
	v_exp_f32_e32 v109, v109
	v_add_f32_e32 v108, 1.0, v108
	v_rcp_f32_e32 v112, v108
	v_add_f32_e32 v108, 1.0, v109
	v_mul_f32_e32 v109, 0xbfb8aa3b, v110
	v_exp_f32_e32 v109, v109
	v_mul_f32_e32 v110, 0xbfb8aa3b, v111
	v_exp_f32_e32 v110, v110
	v_rcp_f32_e32 v111, v108
	v_add_f32_e32 v108, 1.0, v109
	v_rcp_f32_e32 v109, v108
	v_add_f32_e32 v108, 1.0, v110
	v_rcp_f32_e32 v113, v108
	v_or_b32_e32 v108, 28, v99
	v_cvt_pk_bf16_f32 v110, v112, v111
	v_or_b32_e32 v112, v100, v108
	v_cvt_pk_bf16_f32 v111, v109, v113
	v_ashrrev_i32_e32 v113, 31, v112
	v_lshlrev_b64 v[112:113], 11, v[112:113]
	v_lshl_add_u64 v[112:113], v[96:97], 0, v[112:113]
	flat_store_dwordx2 v[112:113], v[110:111]
	ds_write_b128 v101, v[64:67]
	ds_write_b128 v101, v[68:71] offset:64
	ds_write_b128 v101, v[72:75] offset:128
	ds_write_b128 v101, v[76:79] offset:192
	ds_write_b128 v101, v[80:83] offset:4352
	ds_write_b128 v101, v[84:87] offset:4416
	ds_write_b128 v101, v[88:91] offset:4480
	ds_write_b128 v101, v[92:95] offset:4544
	ds_read_b128 v[64:67], v98
	v_or_b32_e32 v68, 32, v100
	s_waitcnt lgkmcnt(0)
	v_mul_f32_e32 v64, 0xbfb8aa3b, v64
	v_mul_f32_e32 v65, 0xbfb8aa3b, v65
	v_mul_f32_e32 v66, 0xbfb8aa3b, v66
	v_mul_f32_e32 v67, 0xbfb8aa3b, v67
	v_exp_f32_e32 v64, v64
	v_exp_f32_e32 v65, v65
	v_exp_f32_e32 v66, v66
	v_exp_f32_e32 v67, v67
	v_add_f32_e32 v64, 1.0, v64
	v_add_f32_e32 v65, 1.0, v65
	v_add_f32_e32 v66, 1.0, v66
	v_add_f32_e32 v67, 1.0, v67
	v_rcp_f32_e32 v64, v64
	v_rcp_f32_e32 v65, v65
	v_rcp_f32_e32 v66, v66
	v_rcp_f32_e32 v67, v67
	v_cvt_pk_bf16_f32 v64, v64, v65
	v_cvt_pk_bf16_f32 v65, v66, v67
	v_or_b32_e32 v66, v68, v99
	v_ashrrev_i32_e32 v67, 31, v66
	v_lshlrev_b64 v[66:67], 11, v[66:67]
	v_lshl_add_u64 v[66:67], v[96:97], 0, v[66:67]
	flat_store_dwordx2 v[66:67], v[64:65]
	ds_read_b128 v[64:67], v98 offset:1088
	s_waitcnt lgkmcnt(0)
	v_mul_f32_e32 v64, 0xbfb8aa3b, v64
	v_mul_f32_e32 v65, 0xbfb8aa3b, v65
	v_mul_f32_e32 v66, 0xbfb8aa3b, v66
	v_mul_f32_e32 v67, 0xbfb8aa3b, v67
	v_exp_f32_e32 v64, v64
	v_exp_f32_e32 v65, v65
	v_exp_f32_e32 v66, v66
	v_exp_f32_e32 v67, v67
	v_add_f32_e32 v64, 1.0, v64
	v_add_f32_e32 v65, 1.0, v65
	v_add_f32_e32 v66, 1.0, v66
	v_add_f32_e32 v67, 1.0, v67
	v_rcp_f32_e32 v64, v64
	v_rcp_f32_e32 v65, v65
	v_rcp_f32_e32 v66, v66
	v_rcp_f32_e32 v67, v67
	v_cvt_pk_bf16_f32 v64, v64, v65
	v_cvt_pk_bf16_f32 v65, v66, v67
	v_or_b32_e32 v66, v68, v102
	v_ashrrev_i32_e32 v67, 31, v66
	v_lshlrev_b64 v[66:67], 11, v[66:67]
	v_lshl_add_u64 v[66:67], v[96:97], 0, v[66:67]
	flat_store_dwordx2 v[66:67], v[64:65]
	ds_read_b128 v[64:67], v98 offset:2176
	s_waitcnt lgkmcnt(0)
	v_mul_f32_e32 v64, 0xbfb8aa3b, v64
	v_mul_f32_e32 v65, 0xbfb8aa3b, v65
	v_mul_f32_e32 v66, 0xbfb8aa3b, v66
	v_mul_f32_e32 v67, 0xbfb8aa3b, v67
	v_exp_f32_e32 v64, v64
	v_exp_f32_e32 v65, v65
	v_exp_f32_e32 v66, v66
	v_exp_f32_e32 v67, v67
	v_add_f32_e32 v64, 1.0, v64
	v_add_f32_e32 v65, 1.0, v65
	v_add_f32_e32 v66, 1.0, v66
	v_add_f32_e32 v67, 1.0, v67
	v_rcp_f32_e32 v64, v64
	v_rcp_f32_e32 v65, v65
	v_rcp_f32_e32 v66, v66
	v_rcp_f32_e32 v67, v67
	v_cvt_pk_bf16_f32 v64, v64, v65
	v_cvt_pk_bf16_f32 v65, v66, v67
	v_or_b32_e32 v66, v68, v103
	v_ashrrev_i32_e32 v67, 31, v66
	v_lshlrev_b64 v[66:67], 11, v[66:67]
	v_lshl_add_u64 v[66:67], v[96:97], 0, v[66:67]
	flat_store_dwordx2 v[66:67], v[64:65]
	ds_read_b128 v[64:67], v98 offset:3264
	s_waitcnt lgkmcnt(0)
	v_mul_f32_e32 v64, 0xbfb8aa3b, v64
	v_mul_f32_e32 v65, 0xbfb8aa3b, v65
	v_mul_f32_e32 v66, 0xbfb8aa3b, v66
	v_mul_f32_e32 v67, 0xbfb8aa3b, v67
	v_exp_f32_e32 v64, v64
	v_exp_f32_e32 v65, v65
	v_exp_f32_e32 v66, v66
	v_exp_f32_e32 v67, v67
	v_add_f32_e32 v64, 1.0, v64
	v_add_f32_e32 v65, 1.0, v65
	v_add_f32_e32 v66, 1.0, v66
	v_add_f32_e32 v67, 1.0, v67
	v_rcp_f32_e32 v64, v64
	v_rcp_f32_e32 v65, v65
	v_rcp_f32_e32 v66, v66
	v_rcp_f32_e32 v67, v67
	v_cvt_pk_bf16_f32 v64, v64, v65
	v_cvt_pk_bf16_f32 v65, v66, v67
	v_or_b32_e32 v66, v68, v104
	v_ashrrev_i32_e32 v67, 31, v66
	v_lshlrev_b64 v[66:67], 11, v[66:67]
	v_lshl_add_u64 v[66:67], v[96:97], 0, v[66:67]
	flat_store_dwordx2 v[66:67], v[64:65]
	ds_read_b128 v[64:67], v98 offset:4352
	s_waitcnt lgkmcnt(0)
	v_mul_f32_e32 v64, 0xbfb8aa3b, v64
	v_mul_f32_e32 v65, 0xbfb8aa3b, v65
	v_mul_f32_e32 v66, 0xbfb8aa3b, v66
	v_mul_f32_e32 v67, 0xbfb8aa3b, v67
	v_exp_f32_e32 v64, v64
	v_exp_f32_e32 v65, v65
	v_exp_f32_e32 v66, v66
	v_exp_f32_e32 v67, v67
	v_add_f32_e32 v64, 1.0, v64
	v_add_f32_e32 v65, 1.0, v65
	v_add_f32_e32 v66, 1.0, v66
	v_add_f32_e32 v67, 1.0, v67
	v_rcp_f32_e32 v64, v64
	v_rcp_f32_e32 v65, v65
	v_rcp_f32_e32 v66, v66
	v_rcp_f32_e32 v67, v67
	v_cvt_pk_bf16_f32 v64, v64, v65
	v_cvt_pk_bf16_f32 v65, v66, v67
	v_or_b32_e32 v66, v68, v105
	v_ashrrev_i32_e32 v67, 31, v66
	v_lshlrev_b64 v[66:67], 11, v[66:67]
	v_lshl_add_u64 v[66:67], v[96:97], 0, v[66:67]
	flat_store_dwordx2 v[66:67], v[64:65]
	ds_read_b128 v[64:67], v98 offset:5440
	s_waitcnt lgkmcnt(0)
	v_mul_f32_e32 v64, 0xbfb8aa3b, v64
	v_mul_f32_e32 v65, 0xbfb8aa3b, v65
	v_mul_f32_e32 v66, 0xbfb8aa3b, v66
	v_mul_f32_e32 v67, 0xbfb8aa3b, v67
	v_exp_f32_e32 v64, v64
	v_exp_f32_e32 v65, v65
	v_exp_f32_e32 v66, v66
	v_exp_f32_e32 v67, v67
	v_add_f32_e32 v64, 1.0, v64
	v_add_f32_e32 v65, 1.0, v65
	v_add_f32_e32 v66, 1.0, v66
	v_add_f32_e32 v67, 1.0, v67
	v_rcp_f32_e32 v64, v64
	v_rcp_f32_e32 v65, v65
	v_rcp_f32_e32 v66, v66
	v_rcp_f32_e32 v67, v67
	v_cvt_pk_bf16_f32 v64, v64, v65
	v_cvt_pk_bf16_f32 v65, v66, v67
	v_or_b32_e32 v66, v68, v106
	v_ashrrev_i32_e32 v67, 31, v66
	v_lshlrev_b64 v[66:67], 11, v[66:67]
	v_lshl_add_u64 v[66:67], v[96:97], 0, v[66:67]
	flat_store_dwordx2 v[66:67], v[64:65]
	ds_read_b128 v[64:67], v98 offset:6528
	s_waitcnt lgkmcnt(0)
	v_mul_f32_e32 v64, 0xbfb8aa3b, v64
	v_mul_f32_e32 v65, 0xbfb8aa3b, v65
	v_mul_f32_e32 v66, 0xbfb8aa3b, v66
	v_mul_f32_e32 v67, 0xbfb8aa3b, v67
	v_exp_f32_e32 v64, v64
	v_exp_f32_e32 v65, v65
	v_exp_f32_e32 v66, v66
	v_exp_f32_e32 v67, v67
	v_add_f32_e32 v64, 1.0, v64
	v_add_f32_e32 v65, 1.0, v65
	v_add_f32_e32 v66, 1.0, v66
	v_add_f32_e32 v67, 1.0, v67
	v_rcp_f32_e32 v64, v64
	v_rcp_f32_e32 v65, v65
	v_rcp_f32_e32 v66, v66
	v_rcp_f32_e32 v67, v67
	v_cvt_pk_bf16_f32 v64, v64, v65
	v_cvt_pk_bf16_f32 v65, v66, v67
	v_or_b32_e32 v66, v68, v107
	v_ashrrev_i32_e32 v67, 31, v66
	v_lshlrev_b64 v[66:67], 11, v[66:67]
	v_lshl_add_u64 v[66:67], v[96:97], 0, v[66:67]
	flat_store_dwordx2 v[66:67], v[64:65]
	ds_read_b128 v[64:67], v98 offset:7616
	s_waitcnt lgkmcnt(0)
	v_mul_f32_e32 v64, 0xbfb8aa3b, v64
	v_mul_f32_e32 v65, 0xbfb8aa3b, v65
	v_mul_f32_e32 v66, 0xbfb8aa3b, v66
	v_mul_f32_e32 v67, 0xbfb8aa3b, v67
	v_exp_f32_e32 v64, v64
	v_exp_f32_e32 v65, v65
	v_exp_f32_e32 v66, v66
	v_exp_f32_e32 v67, v67
	v_add_f32_e32 v64, 1.0, v64
	v_add_f32_e32 v65, 1.0, v65
	v_add_f32_e32 v66, 1.0, v66
	v_add_f32_e32 v67, 1.0, v67
	v_rcp_f32_e32 v64, v64
	v_rcp_f32_e32 v65, v65
	v_rcp_f32_e32 v66, v66
	v_rcp_f32_e32 v67, v67
	v_cvt_pk_bf16_f32 v64, v64, v65
	v_cvt_pk_bf16_f32 v65, v66, v67
	v_or_b32_e32 v66, v68, v108
	v_ashrrev_i32_e32 v67, 31, v66
	v_lshlrev_b64 v[66:67], 11, v[66:67]
	v_lshl_add_u64 v[66:67], v[96:97], 0, v[66:67]
	flat_store_dwordx2 v[66:67], v[64:65]
	ds_write_b128 v101, v[32:35]
	ds_write_b128 v101, v[36:39] offset:64
	ds_write_b128 v101, v[40:43] offset:128
	ds_write_b128 v101, v[44:47] offset:192
	ds_write_b128 v101, v[48:51] offset:4352
	ds_write_b128 v101, v[52:55] offset:4416
	ds_write_b128 v101, v[56:59] offset:4480
	ds_write_b128 v101, v[60:63] offset:4544
	ds_read_b128 v[32:35], v98
	v_or_b32_e32 v36, 64, v100
	s_waitcnt lgkmcnt(0)
	v_mul_f32_e32 v32, 0xbfb8aa3b, v32
	v_mul_f32_e32 v33, 0xbfb8aa3b, v33
	v_mul_f32_e32 v34, 0xbfb8aa3b, v34
	v_mul_f32_e32 v35, 0xbfb8aa3b, v35
	v_exp_f32_e32 v32, v32
	v_exp_f32_e32 v33, v33
	v_exp_f32_e32 v34, v34
	v_exp_f32_e32 v35, v35
	v_add_f32_e32 v32, 1.0, v32
	v_add_f32_e32 v33, 1.0, v33
	v_add_f32_e32 v34, 1.0, v34
	v_add_f32_e32 v35, 1.0, v35
	v_rcp_f32_e32 v32, v32
	v_rcp_f32_e32 v33, v33
	v_rcp_f32_e32 v34, v34
	v_rcp_f32_e32 v35, v35
	v_cvt_pk_bf16_f32 v32, v32, v33
	v_cvt_pk_bf16_f32 v33, v34, v35
	v_or_b32_e32 v34, v36, v99
	v_ashrrev_i32_e32 v35, 31, v34
	v_lshlrev_b64 v[34:35], 11, v[34:35]
	v_lshl_add_u64 v[34:35], v[96:97], 0, v[34:35]
	flat_store_dwordx2 v[34:35], v[32:33]
	ds_read_b128 v[32:35], v98 offset:1088
	s_waitcnt lgkmcnt(0)
	v_mul_f32_e32 v32, 0xbfb8aa3b, v32
	v_mul_f32_e32 v33, 0xbfb8aa3b, v33
	v_mul_f32_e32 v34, 0xbfb8aa3b, v34
	v_mul_f32_e32 v35, 0xbfb8aa3b, v35
	v_exp_f32_e32 v32, v32
	v_exp_f32_e32 v33, v33
	v_exp_f32_e32 v34, v34
	v_exp_f32_e32 v35, v35
	v_add_f32_e32 v32, 1.0, v32
	v_add_f32_e32 v33, 1.0, v33
	v_add_f32_e32 v34, 1.0, v34
	v_add_f32_e32 v35, 1.0, v35
	v_rcp_f32_e32 v32, v32
	v_rcp_f32_e32 v33, v33
	v_rcp_f32_e32 v34, v34
	v_rcp_f32_e32 v35, v35
	v_cvt_pk_bf16_f32 v32, v32, v33
	v_cvt_pk_bf16_f32 v33, v34, v35
	v_or_b32_e32 v34, v36, v102
	v_ashrrev_i32_e32 v35, 31, v34
	v_lshlrev_b64 v[34:35], 11, v[34:35]
	v_lshl_add_u64 v[34:35], v[96:97], 0, v[34:35]
	flat_store_dwordx2 v[34:35], v[32:33]
	ds_read_b128 v[32:35], v98 offset:2176
	s_waitcnt lgkmcnt(0)
	v_mul_f32_e32 v32, 0xbfb8aa3b, v32
	v_mul_f32_e32 v33, 0xbfb8aa3b, v33
	v_mul_f32_e32 v34, 0xbfb8aa3b, v34
	v_mul_f32_e32 v35, 0xbfb8aa3b, v35
	v_exp_f32_e32 v32, v32
	v_exp_f32_e32 v33, v33
	v_exp_f32_e32 v34, v34
	v_exp_f32_e32 v35, v35
	v_add_f32_e32 v32, 1.0, v32
	v_add_f32_e32 v33, 1.0, v33
	v_add_f32_e32 v34, 1.0, v34
	v_add_f32_e32 v35, 1.0, v35
	v_rcp_f32_e32 v32, v32
	v_rcp_f32_e32 v33, v33
	v_rcp_f32_e32 v34, v34
	v_rcp_f32_e32 v35, v35
	v_cvt_pk_bf16_f32 v32, v32, v33
	v_cvt_pk_bf16_f32 v33, v34, v35
	v_or_b32_e32 v34, v36, v103
	v_ashrrev_i32_e32 v35, 31, v34
	v_lshlrev_b64 v[34:35], 11, v[34:35]
	v_lshl_add_u64 v[34:35], v[96:97], 0, v[34:35]
	flat_store_dwordx2 v[34:35], v[32:33]
	ds_read_b128 v[32:35], v98 offset:3264
	s_waitcnt lgkmcnt(0)
	v_mul_f32_e32 v32, 0xbfb8aa3b, v32
	v_mul_f32_e32 v33, 0xbfb8aa3b, v33
	v_mul_f32_e32 v34, 0xbfb8aa3b, v34
	v_mul_f32_e32 v35, 0xbfb8aa3b, v35
	v_exp_f32_e32 v32, v32
	v_exp_f32_e32 v33, v33
	v_exp_f32_e32 v34, v34
	v_exp_f32_e32 v35, v35
	v_add_f32_e32 v32, 1.0, v32
	v_add_f32_e32 v33, 1.0, v33
	v_add_f32_e32 v34, 1.0, v34
	v_add_f32_e32 v35, 1.0, v35
	v_rcp_f32_e32 v32, v32
	v_rcp_f32_e32 v33, v33
	v_rcp_f32_e32 v34, v34
	v_rcp_f32_e32 v35, v35
	v_cvt_pk_bf16_f32 v32, v32, v33
	v_cvt_pk_bf16_f32 v33, v34, v35
	v_or_b32_e32 v34, v36, v104
	v_ashrrev_i32_e32 v35, 31, v34
	v_lshlrev_b64 v[34:35], 11, v[34:35]
	v_lshl_add_u64 v[34:35], v[96:97], 0, v[34:35]
	flat_store_dwordx2 v[34:35], v[32:33]
	ds_read_b128 v[32:35], v98 offset:4352
	s_waitcnt lgkmcnt(0)
	v_mul_f32_e32 v32, 0xbfb8aa3b, v32
	v_mul_f32_e32 v33, 0xbfb8aa3b, v33
	v_mul_f32_e32 v34, 0xbfb8aa3b, v34
	v_mul_f32_e32 v35, 0xbfb8aa3b, v35
	v_exp_f32_e32 v32, v32
	v_exp_f32_e32 v33, v33
	v_exp_f32_e32 v34, v34
	v_exp_f32_e32 v35, v35
	v_add_f32_e32 v32, 1.0, v32
	v_add_f32_e32 v33, 1.0, v33
	v_add_f32_e32 v34, 1.0, v34
	v_add_f32_e32 v35, 1.0, v35
	v_rcp_f32_e32 v32, v32
	v_rcp_f32_e32 v33, v33
	v_rcp_f32_e32 v34, v34
	v_rcp_f32_e32 v35, v35
	v_cvt_pk_bf16_f32 v32, v32, v33
	v_cvt_pk_bf16_f32 v33, v34, v35
	v_or_b32_e32 v34, v36, v105
	v_ashrrev_i32_e32 v35, 31, v34
	v_lshlrev_b64 v[34:35], 11, v[34:35]
	v_lshl_add_u64 v[34:35], v[96:97], 0, v[34:35]
	flat_store_dwordx2 v[34:35], v[32:33]
	ds_read_b128 v[32:35], v98 offset:5440
	s_waitcnt lgkmcnt(0)
	v_mul_f32_e32 v32, 0xbfb8aa3b, v32
	v_mul_f32_e32 v33, 0xbfb8aa3b, v33
	v_mul_f32_e32 v34, 0xbfb8aa3b, v34
	v_mul_f32_e32 v35, 0xbfb8aa3b, v35
	v_exp_f32_e32 v32, v32
	v_exp_f32_e32 v33, v33
	v_exp_f32_e32 v34, v34
	v_exp_f32_e32 v35, v35
	v_add_f32_e32 v32, 1.0, v32
	v_add_f32_e32 v33, 1.0, v33
	v_add_f32_e32 v34, 1.0, v34
	v_add_f32_e32 v35, 1.0, v35
	v_rcp_f32_e32 v32, v32
	v_rcp_f32_e32 v33, v33
	v_rcp_f32_e32 v34, v34
	v_rcp_f32_e32 v35, v35
	v_cvt_pk_bf16_f32 v32, v32, v33
	v_cvt_pk_bf16_f32 v33, v34, v35
	v_or_b32_e32 v34, v36, v106
	v_ashrrev_i32_e32 v35, 31, v34
	v_lshlrev_b64 v[34:35], 11, v[34:35]
	v_lshl_add_u64 v[34:35], v[96:97], 0, v[34:35]
	flat_store_dwordx2 v[34:35], v[32:33]
	ds_read_b128 v[32:35], v98 offset:6528
	s_waitcnt lgkmcnt(0)
	v_mul_f32_e32 v32, 0xbfb8aa3b, v32
	v_mul_f32_e32 v33, 0xbfb8aa3b, v33
	v_mul_f32_e32 v34, 0xbfb8aa3b, v34
	v_mul_f32_e32 v35, 0xbfb8aa3b, v35
	v_exp_f32_e32 v32, v32
	v_exp_f32_e32 v33, v33
	v_exp_f32_e32 v34, v34
	v_exp_f32_e32 v35, v35
	v_add_f32_e32 v32, 1.0, v32
	v_add_f32_e32 v33, 1.0, v33
	v_add_f32_e32 v34, 1.0, v34
	v_add_f32_e32 v35, 1.0, v35
	v_rcp_f32_e32 v32, v32
	v_rcp_f32_e32 v33, v33
	v_rcp_f32_e32 v34, v34
	v_rcp_f32_e32 v35, v35
	v_cvt_pk_bf16_f32 v32, v32, v33
	v_cvt_pk_bf16_f32 v33, v34, v35
	v_or_b32_e32 v34, v36, v107
	v_ashrrev_i32_e32 v35, 31, v34
	v_lshlrev_b64 v[34:35], 11, v[34:35]
	v_lshl_add_u64 v[34:35], v[96:97], 0, v[34:35]
	flat_store_dwordx2 v[34:35], v[32:33]
	ds_read_b128 v[32:35], v98 offset:7616
	s_waitcnt lgkmcnt(0)
	v_mul_f32_e32 v32, 0xbfb8aa3b, v32
	v_mul_f32_e32 v33, 0xbfb8aa3b, v33
	v_mul_f32_e32 v34, 0xbfb8aa3b, v34
	v_mul_f32_e32 v35, 0xbfb8aa3b, v35
	v_exp_f32_e32 v32, v32
	v_exp_f32_e32 v33, v33
	v_exp_f32_e32 v34, v34
	v_exp_f32_e32 v35, v35
	v_add_f32_e32 v32, 1.0, v32
	v_add_f32_e32 v33, 1.0, v33
	v_add_f32_e32 v34, 1.0, v34
	v_add_f32_e32 v35, 1.0, v35
	v_rcp_f32_e32 v32, v32
	v_rcp_f32_e32 v33, v33
	v_rcp_f32_e32 v34, v34
	v_rcp_f32_e32 v35, v35
	v_cvt_pk_bf16_f32 v32, v32, v33
	v_cvt_pk_bf16_f32 v33, v34, v35
	v_or_b32_e32 v34, v36, v108
	v_ashrrev_i32_e32 v35, 31, v34
	v_lshlrev_b64 v[34:35], 11, v[34:35]
	v_lshl_add_u64 v[34:35], v[96:97], 0, v[34:35]
	flat_store_dwordx2 v[34:35], v[32:33]
	ds_write_b128 v101, v[0:3]
	ds_write_b128 v101, v[4:7] offset:64
	ds_write_b128 v101, v[8:11] offset:128
	ds_write_b128 v101, v[12:15] offset:192
	ds_write_b128 v101, v[16:19] offset:4352
	ds_write_b128 v101, v[20:23] offset:4416
	ds_write_b128 v101, v[24:27] offset:4480
	ds_write_b128 v101, v[28:31] offset:4544
	ds_read_b128 v[0:3], v98
	v_or_b32_e32 v4, 0x60, v100
	v_mov_b32_e32 v12, v132
	s_waitcnt lgkmcnt(0)
	v_mul_f32_e32 v0, 0xbfb8aa3b, v0
	v_mul_f32_e32 v1, 0xbfb8aa3b, v1
	v_mul_f32_e32 v2, 0xbfb8aa3b, v2
	v_mul_f32_e32 v3, 0xbfb8aa3b, v3
	v_exp_f32_e32 v0, v0
	v_exp_f32_e32 v1, v1
	v_exp_f32_e32 v2, v2
	v_exp_f32_e32 v3, v3
	v_add_f32_e32 v0, 1.0, v0
	v_add_f32_e32 v1, 1.0, v1
	v_add_f32_e32 v2, 1.0, v2
	v_add_f32_e32 v3, 1.0, v3
	v_rcp_f32_e32 v0, v0
	v_rcp_f32_e32 v1, v1
	v_rcp_f32_e32 v2, v2
	v_rcp_f32_e32 v3, v3
	v_cvt_pk_bf16_f32 v0, v0, v1
	v_cvt_pk_bf16_f32 v1, v2, v3
	v_or_b32_e32 v2, v4, v99
	v_ashrrev_i32_e32 v3, 31, v2
	v_lshlrev_b64 v[2:3], 11, v[2:3]
	v_lshl_add_u64 v[2:3], v[96:97], 0, v[2:3]
	flat_store_dwordx2 v[2:3], v[0:1]
	ds_read_b128 v[0:3], v98 offset:1088
	s_waitcnt lgkmcnt(0)
	v_mul_f32_e32 v0, 0xbfb8aa3b, v0
	v_mul_f32_e32 v1, 0xbfb8aa3b, v1
	v_mul_f32_e32 v2, 0xbfb8aa3b, v2
	v_mul_f32_e32 v3, 0xbfb8aa3b, v3
	v_exp_f32_e32 v0, v0
	v_exp_f32_e32 v1, v1
	v_exp_f32_e32 v2, v2
	v_exp_f32_e32 v3, v3
	v_add_f32_e32 v0, 1.0, v0
	v_add_f32_e32 v1, 1.0, v1
	v_add_f32_e32 v2, 1.0, v2
	v_add_f32_e32 v3, 1.0, v3
	v_rcp_f32_e32 v0, v0
	v_rcp_f32_e32 v1, v1
	v_rcp_f32_e32 v2, v2
	v_rcp_f32_e32 v3, v3
	v_cvt_pk_bf16_f32 v0, v0, v1
	v_cvt_pk_bf16_f32 v1, v2, v3
	v_or_b32_e32 v2, v4, v102
	v_ashrrev_i32_e32 v3, 31, v2
	v_lshlrev_b64 v[2:3], 11, v[2:3]
	v_lshl_add_u64 v[2:3], v[96:97], 0, v[2:3]
	flat_store_dwordx2 v[2:3], v[0:1]
	ds_read_b128 v[0:3], v98 offset:2176
	s_waitcnt lgkmcnt(0)
	v_mul_f32_e32 v0, 0xbfb8aa3b, v0
	v_mul_f32_e32 v1, 0xbfb8aa3b, v1
	v_mul_f32_e32 v2, 0xbfb8aa3b, v2
	v_mul_f32_e32 v3, 0xbfb8aa3b, v3
	v_exp_f32_e32 v0, v0
	v_exp_f32_e32 v1, v1
	v_exp_f32_e32 v2, v2
	v_exp_f32_e32 v3, v3
	v_add_f32_e32 v0, 1.0, v0
	v_add_f32_e32 v1, 1.0, v1
	v_add_f32_e32 v2, 1.0, v2
	v_add_f32_e32 v3, 1.0, v3
	v_rcp_f32_e32 v0, v0
	v_rcp_f32_e32 v1, v1
	v_rcp_f32_e32 v2, v2
	v_rcp_f32_e32 v3, v3
	v_cvt_pk_bf16_f32 v0, v0, v1
	v_cvt_pk_bf16_f32 v1, v2, v3
	v_or_b32_e32 v2, v4, v103
	v_ashrrev_i32_e32 v3, 31, v2
	v_lshlrev_b64 v[2:3], 11, v[2:3]
	v_lshl_add_u64 v[2:3], v[96:97], 0, v[2:3]
	flat_store_dwordx2 v[2:3], v[0:1]
	ds_read_b128 v[0:3], v98 offset:3264
	s_waitcnt lgkmcnt(0)
	v_mul_f32_e32 v0, 0xbfb8aa3b, v0
	v_mul_f32_e32 v1, 0xbfb8aa3b, v1
	v_mul_f32_e32 v2, 0xbfb8aa3b, v2
	v_mul_f32_e32 v3, 0xbfb8aa3b, v3
	v_exp_f32_e32 v0, v0
	v_exp_f32_e32 v1, v1
	v_exp_f32_e32 v2, v2
	v_exp_f32_e32 v3, v3
	v_add_f32_e32 v0, 1.0, v0
	v_add_f32_e32 v1, 1.0, v1
	v_add_f32_e32 v2, 1.0, v2
	v_add_f32_e32 v3, 1.0, v3
	v_rcp_f32_e32 v0, v0
	v_rcp_f32_e32 v1, v1
	v_rcp_f32_e32 v2, v2
	v_rcp_f32_e32 v3, v3
	v_cvt_pk_bf16_f32 v0, v0, v1
	v_cvt_pk_bf16_f32 v1, v2, v3
	v_or_b32_e32 v2, v4, v104
	v_ashrrev_i32_e32 v3, 31, v2
	v_lshlrev_b64 v[2:3], 11, v[2:3]
	v_lshl_add_u64 v[2:3], v[96:97], 0, v[2:3]
	flat_store_dwordx2 v[2:3], v[0:1]
	ds_read_b128 v[0:3], v98 offset:4352
	s_waitcnt lgkmcnt(0)
	v_mul_f32_e32 v0, 0xbfb8aa3b, v0
	v_mul_f32_e32 v1, 0xbfb8aa3b, v1
	v_mul_f32_e32 v2, 0xbfb8aa3b, v2
	v_mul_f32_e32 v3, 0xbfb8aa3b, v3
	v_exp_f32_e32 v0, v0
	v_exp_f32_e32 v1, v1
	v_exp_f32_e32 v2, v2
	v_exp_f32_e32 v3, v3
	v_add_f32_e32 v0, 1.0, v0
	v_add_f32_e32 v1, 1.0, v1
	v_add_f32_e32 v2, 1.0, v2
	v_add_f32_e32 v3, 1.0, v3
	v_rcp_f32_e32 v0, v0
	v_rcp_f32_e32 v1, v1
	v_rcp_f32_e32 v2, v2
	v_rcp_f32_e32 v3, v3
	v_cvt_pk_bf16_f32 v0, v0, v1
	v_cvt_pk_bf16_f32 v1, v2, v3
	v_or_b32_e32 v2, v4, v105
	v_ashrrev_i32_e32 v3, 31, v2
	v_lshlrev_b64 v[2:3], 11, v[2:3]
	v_lshl_add_u64 v[2:3], v[96:97], 0, v[2:3]
	flat_store_dwordx2 v[2:3], v[0:1]
	ds_read_b128 v[0:3], v98 offset:5440
	s_waitcnt lgkmcnt(0)
	v_mul_f32_e32 v0, 0xbfb8aa3b, v0
	v_mul_f32_e32 v1, 0xbfb8aa3b, v1
	v_mul_f32_e32 v2, 0xbfb8aa3b, v2
	v_mul_f32_e32 v3, 0xbfb8aa3b, v3
	v_exp_f32_e32 v0, v0
	v_exp_f32_e32 v1, v1
	v_exp_f32_e32 v2, v2
	v_exp_f32_e32 v3, v3
	v_add_f32_e32 v0, 1.0, v0
	v_add_f32_e32 v1, 1.0, v1
	v_add_f32_e32 v2, 1.0, v2
	v_add_f32_e32 v3, 1.0, v3
	v_rcp_f32_e32 v0, v0
	v_rcp_f32_e32 v1, v1
	v_rcp_f32_e32 v2, v2
	v_rcp_f32_e32 v3, v3
	v_cvt_pk_bf16_f32 v0, v0, v1
	v_cvt_pk_bf16_f32 v1, v2, v3
	v_or_b32_e32 v2, v4, v106
	v_ashrrev_i32_e32 v3, 31, v2
	v_lshlrev_b64 v[2:3], 11, v[2:3]
	v_lshl_add_u64 v[2:3], v[96:97], 0, v[2:3]
	flat_store_dwordx2 v[2:3], v[0:1]
	ds_read_b128 v[0:3], v98 offset:6528
	s_waitcnt lgkmcnt(0)
	v_mul_f32_e32 v0, 0xbfb8aa3b, v0
	v_mul_f32_e32 v1, 0xbfb8aa3b, v1
	v_mul_f32_e32 v2, 0xbfb8aa3b, v2
	v_mul_f32_e32 v3, 0xbfb8aa3b, v3
	v_exp_f32_e32 v0, v0
	v_exp_f32_e32 v1, v1
	v_exp_f32_e32 v2, v2
	v_exp_f32_e32 v3, v3
	v_add_f32_e32 v0, 1.0, v0
	v_add_f32_e32 v1, 1.0, v1
	v_add_f32_e32 v2, 1.0, v2
	v_add_f32_e32 v3, 1.0, v3
	v_rcp_f32_e32 v0, v0
	v_rcp_f32_e32 v1, v1
	v_rcp_f32_e32 v2, v2
	v_rcp_f32_e32 v3, v3
	v_cvt_pk_bf16_f32 v0, v0, v1
	v_cvt_pk_bf16_f32 v1, v2, v3
	v_or_b32_e32 v2, v4, v107
	v_ashrrev_i32_e32 v3, 31, v2
	v_lshlrev_b64 v[2:3], 11, v[2:3]
	v_add_co_u32_e32 v2, vcc, v96, v2
	v_addc_co_u32_e32 v3, vcc, v97, v3, vcc
	flat_store_dwordx2 v[2:3], v[0:1]
	ds_read_b128 v[0:3], v98 offset:7616
	s_waitcnt lgkmcnt(0)
	v_mul_f32_e32 v0, 0xbfb8aa3b, v0
	v_mul_f32_e32 v1, 0xbfb8aa3b, v1
	v_mul_f32_e32 v2, 0xbfb8aa3b, v2
	v_mul_f32_e32 v3, 0xbfb8aa3b, v3
	v_exp_f32_e32 v0, v0
	v_exp_f32_e32 v1, v1
	v_exp_f32_e32 v2, v2
	v_exp_f32_e32 v3, v3
	v_add_f32_e32 v0, 1.0, v0
	v_add_f32_e32 v1, 1.0, v1
	v_add_f32_e32 v2, 1.0, v2
	v_add_f32_e32 v3, 1.0, v3
	v_rcp_f32_e32 v0, v0
	v_rcp_f32_e32 v1, v1
	v_rcp_f32_e32 v2, v2
	v_rcp_f32_e32 v3, v3
	v_cvt_pk_bf16_f32 v0, v0, v1
	v_cvt_pk_bf16_f32 v1, v2, v3
	v_or_b32_e32 v2, v4, v108
	v_ashrrev_i32_e32 v3, 31, v2
	v_lshlrev_b64 v[2:3], 11, v[2:3]
	v_add_co_u32_e32 v2, vcc, v96, v2
	v_addc_co_u32_e32 v3, vcc, v97, v3, vcc
	flat_store_dwordx2 v[2:3], v[0:1]
	v_mov_b32_e32 v0, s3
	ds_read_b128 v[0:3], v0
	s_waitcnt lgkmcnt(0)
	v_readfirstlane_b32 s0, v3
	v_readfirstlane_b32 s29, v2
	v_lshlrev_b32_e32 v3, 4, v12
	v_and_b32_e32 v2, 32, v12
	s_add_u32 s42, s29, s36
	v_lshrrev_b32_e32 v4, 1, v12
	v_bitop3_b32 v2, v3, v2, 48 bitop3:0x6c
	s_addc_u32 s43, s0, s37
	v_bfe_u32 v13, v12, 2, 4
	v_and_b32_e32 v14, 32, v4
	v_lshrrev_b32_e32 v15, 1, v2
	v_ashrrev_i32_e32 v16, 3, v12
	s_add_u32 s36, s42, 0x18800000
	v_or_b32_e32 v6, v15, v14
	v_and_or_b32 v2, v16, s44, v13
	s_addc_u32 s37, s43, 0
	s_lshl_b64 s[38:39], s[30:31], 11
	v_and_b32_e32 v5, 0xfffffc00, v3
	v_lshl_or_b32 v130, v2, 10, v6
	v_add_u32_e32 v2, 0x2000, v3
	v_add_u32_e32 v4, 0x4000, v3
	v_add_u32_e32 v3, 0x6000, v3
	s_add_u32 s53, s29, s38
	v_ashrrev_i32_e32 v17, 7, v2
	v_ashrrev_i32_e32 v18, 7, v4
	v_ashrrev_i32_e32 v19, 7, v3
	s_addc_u32 s54, s0, s39
	v_and_or_b32 v2, v17, s44, v13
	v_and_or_b32 v4, v18, s44, v13
	v_and_or_b32 v3, v19, s44, v13
	v_add_u32_e32 v151, 0, v5
	s_add_u32 s38, s53, 0xe00000
	v_lshl_or_b32 v2, v2, 10, v6
	v_lshl_or_b32 v4, v4, 10, v6
	v_lshl_or_b32 v6, v3, 10, v6
	v_add_u32_e32 v3, 0x8000, v151
	v_lshlrev_b64 v[8:9], 1, v[130:131]
	v_readfirstlane_b32 s55, v151
	s_addc_u32 s39, s54, 0
	v_lshl_add_u64 v[10:11], s[36:37], 0, v[8:9]
	s_mov_b32 m0, s55
	v_readfirstlane_b32 s55, v3
	v_mov_b32_e32 v3, v131
	v_add_u32_e32 v5, 0x2000, v151
	global_load_lds_dwordx4 v[10:11], off
	v_lshl_add_u64 v[8:9], s[38:39], 0, v[8:9]
	s_mov_b32 m0, s55
	v_lshlrev_b64 v[2:3], 1, v[2:3]
	v_readfirstlane_b32 s55, v5
	v_add_u32_e32 v5, 0xa000, v151
	global_load_lds_dwordx4 v[8:9], off
	v_lshl_add_u64 v[8:9], s[36:37], 0, v[2:3]
	s_mov_b32 m0, s55
	v_readfirstlane_b32 s55, v5
	global_load_lds_dwordx4 v[8:9], off
	v_lshl_add_u64 v[2:3], s[38:39], 0, v[2:3]
	s_mov_b32 m0, s55
	v_mov_b32_e32 v5, v131
	v_add_u32_e32 v7, 0x4000, v151
	global_load_lds_dwordx4 v[2:3], off
	v_lshlrev_b64 v[2:3], 1, v[4:5]
	v_readfirstlane_b32 s55, v7
	v_lshl_add_u64 v[4:5], s[36:37], 0, v[2:3]
	s_mov_b32 m0, s55
	v_lshl_add_u64 v[2:3], s[38:39], 0, v[2:3]
	global_load_lds_dwordx4 v[4:5], off
	v_add_u32_e32 v4, 0xc000, v151
	v_mov_b32_e32 v7, v131
	v_readfirstlane_b32 s55, v4
	s_mov_b32 m0, s55
	v_and_b32_e32 v20, 15, v12
	global_load_lds_dwordx4 v[2:3], off
	v_lshlrev_b64 v[2:3], 1, v[6:7]
	v_add_u32_e32 v6, 0x6000, v151
	v_lshl_add_u64 v[4:5], s[36:37], 0, v[2:3]
	v_readfirstlane_b32 s36, v6
	s_mov_b32 m0, s36
	v_lshl_add_u64 v[2:3], s[38:39], 0, v[2:3]
	global_load_lds_dwordx4 v[4:5], off
	v_add_u32_e32 v4, 0xe000, v151
	v_lshlrev_b32_e32 v8, 10, v13
	v_readfirstlane_b32 s36, v4
	s_mov_b32 m0, s36
	v_lshlrev_b32_e32 v4, 2, v12
	global_load_lds_dwordx4 v[2:3], off
	v_and_b32_e32 v2, 48, v12
	v_lshlrev_b32_e32 v3, 6, v20
	v_and_b32_e32 v4, 32, v4
	v_bitop3_b32 v152, v3, v4, v2 bitop3:0x36
	v_lshlrev_b32_e32 v3, 7, v12
	v_and_b32_e32 v153, 0x6000, v3
	v_lshlrev_b32_e32 v3, 6, v12
	v_and_b32_e32 v154, 0xffffc000, v3
	v_and_b32_e32 v3, 0x3c0, v3
	v_bitop3_b32 v156, v3, v4, v2 bitop3:0x36
	v_lshlrev_b32_e32 v2, 10, v19
	v_and_or_b32 v2, v2, s45, v15
	v_lshlrev_b32_e32 v4, 10, v18
	v_or3_b32 v130, v2, v8, v14
	v_and_or_b32 v4, v4, s45, v15
	v_lshlrev_b32_e32 v6, 10, v17
	v_lshlrev_b64 v[2:3], 1, v[130:131]
	v_or3_b32 v130, v4, v8, v14
	v_and_or_b32 v6, v6, s45, v15
	v_lshlrev_b32_e32 v9, 10, v16
	v_lshlrev_b64 v[4:5], 1, v[130:131]
	v_or3_b32 v130, v6, v8, v14
	v_and_or_b32 v9, v9, s45, v15
	s_add_u32 s36, s53, 0xe00080
	v_lshlrev_b64 v[6:7], 1, v[130:131]
	v_or3_b32 v130, v9, v8, v14
	s_addc_u32 s37, s54, 0
	v_lshlrev_b64 v[8:9], 1, v[130:131]
	s_nop 0
	v_lshl_add_u64 v[134:135], s[36:37], 0, v[2:3]
	v_lshl_add_u64 v[136:137], s[36:37], 0, v[4:5]
	v_lshl_add_u64 v[138:139], s[36:37], 0, v[6:7]
	v_lshl_add_u64 v[140:141], s[36:37], 0, v[8:9]
	s_add_u32 s36, s42, 0x18800080
	s_addc_u32 s37, s43, 0
	v_or_b32_e32 v155, 0x800, v154
	v_or_b32_e32 v157, 0x1000, v154
	v_or_b32_e32 v158, 0x1800, v154
	v_or_b32_e32 v159, 0x2000, v154
	v_or_b32_e32 v160, 0x2800, v154
	v_or_b32_e32 v161, 0x3000, v154
	v_or_b32_e32 v162, 0x3800, v154
	v_lshl_add_u64 v[142:143], s[36:37], 0, v[2:3]
	v_lshl_add_u64 v[144:145], s[36:37], 0, v[4:5]
	v_lshl_add_u64 v[146:147], s[36:37], 0, v[6:7]
	v_lshl_add_u64 v[148:149], s[36:37], 0, v[8:9]
	s_mov_b32 s38, 0
	s_mov_b64 s[36:37], 0
	s_waitcnt vmcnt(0) lgkmcnt(0)
	s_barrier
	v_readfirstlane_b32 s100, v151
	s_and_b32 s39, s38, 0x10000
	s_xor_b32 s42, s39, 0x10000
	s_add_i32 s39, s39, 0
	v_add3_u32 v130, s39, v152, v153
	v_add3_u32 v163, s39, v152, v154
	v_add3_u32 v196, s39, v156, v155
	v_add3_u32 v197, s39, v156, v157
	v_add3_u32 v198, s39, v156, v158
	v_add3_u32 v199, s39, v156, v159
	v_add3_u32 v200, s39, v156, v160
	v_add3_u32 v201, s39, v156, v161
	v_add3_u32 v202, s39, v156, v162
	ds_read_b128 v[180:183], v130 offset:32768
	ds_read_b128 v[164:167], v163
	ds_read_b128 v[168:171], v196
	ds_read_b128 v[172:175], v197
	ds_read_b128 v[176:179], v198
	ds_read_b128 v[184:187], v130 offset:34816
	ds_read_b128 v[188:191], v130 offset:36864
	ds_read_b128 v[192:195], v130 offset:38912
	s_add_i32 s101, s100, s42
	v_readfirstlane_b32 s98, v148
	v_readfirstlane_b32 s99, v149
	v_readfirstlane_b32 vcc_lo, v140
	v_readfirstlane_b32 vcc_hi, v141
	s_sub_u32 s98, s98, 0x1000000
	s_subb_u32 s99, s99, 0
	s_sub_u32 vcc_lo, vcc_lo, 0x1000000
	s_subb_u32 vcc_hi, vcc_hi, 0
	v_subrev_u32_e32 v148, s98, v148
	v_subrev_u32_e32 v140, vcc_lo, v140
	v_subrev_u32_e32 v146, s98, v146
	v_subrev_u32_e32 v138, vcc_lo, v138
	v_subrev_u32_e32 v144, s98, v144
	v_subrev_u32_e32 v136, vcc_lo, v136
	v_subrev_u32_e32 v142, s98, v142
	v_subrev_u32_e32 v134, vcc_lo, v134
	s_mov_b32 m0, s101
	s_nop 0
	global_load_lds_dwordx4 v148, s[98:99]
	s_add_i32 m0, s101, 0x8000
	s_nop 0
	global_load_lds_dwordx4 v140, vcc
	s_add_i32 m0, s101, 0x2000
	s_nop 0
	global_load_lds_dwordx4 v146, s[98:99]
	s_add_i32 m0, s101, 0xa000
	s_nop 0
	global_load_lds_dwordx4 v138, vcc
	s_add_i32 m0, s101, 0x4000
	s_nop 0
	global_load_lds_dwordx4 v144, s[98:99]
	s_add_i32 m0, s101, 0xc000
	s_nop 0
	global_load_lds_dwordx4 v136, vcc
	s_add_i32 m0, s101, 0x6000
	s_nop 0
	global_load_lds_dwordx4 v142, s[98:99]
	s_add_i32 m0, s101, 0xe000
	s_nop 0
	global_load_lds_dwordx4 v134, vcc

.LBB0_845:
	s_ashr_i32 s12, s27, 31
	s_lshr_b32 s12, s12, 26
	s_add_i32 s12, s27, s12
	s_ashr_i32 s13, s12, 6
	s_and_b32 s12, s12, 0xffc0
	s_sub_i32 s12, s27, s12
	s_bfe_i32 s14, s12, 0x80000
	s_bfe_u32 s14, s14, 0x4000b
	s_add_i32 s14, s12, s14
	s_lshl_b32 s28, s13, 4
	s_and_b32 s13, s14, 0xf0
	v_mov_b32_e32 v148, v132
	v_mov_b32_e32 v18, v132
	s_sub_i32 s12, s12, s13
	ds_read_b64 v[0:1], v133
	s_bfe_i32 s15, s14, 0x80000
	v_lshlrev_b32_e32 v9, 4, v18
	v_and_b32_e32 v8, 32, v18
	s_sext_i32_i8 s12, s12
	v_lshrrev_b32_e32 v10, 1, v18
	v_bitop3_b32 v8, v9, v8, 48 bitop3:0x6c
	s_sext_i32_i16 s15, s15
	s_add_i32 s28, s28, s12
	v_bfe_u32 v19, v18, 2, 4
	v_and_b32_e32 v20, 32, v10
	v_lshrrev_b32_e32 v21, 1, v8
	v_ashrrev_i32_e32 v22, 3, v18
	s_lshl_b32 s14, s28, 8
	s_lshl_b32 s12, s15, 4
	v_or_b32_e32 v12, v21, v20
	v_and_or_b32 v8, v22, s18, v19
	s_and_b32 s12, s12, 0xffffff00
	s_ashr_i32 s15, s14, 31
	v_and_b32_e32 v11, 0xfffffc00, v9
	v_lshl_or_b32 v128, v8, 10, v12
	v_add_u32_e32 v8, 0x2000, v9
	v_add_u32_e32 v10, 0x4000, v9
	v_add_u32_e32 v9, 0x6000, v9
	s_lshl_b64 s[16:17], s[14:15], 11
	s_ashr_i32 s13, s12, 31
	v_ashrrev_i32_e32 v23, 7, v8
	v_ashrrev_i32_e32 v24, 7, v10
	v_ashrrev_i32_e32 v25, 7, v9
	s_waitcnt lgkmcnt(0)
	v_lshl_add_u64 v[2:3], v[0:1], 0, s[16:17]
	s_lshl_b64 s[16:17], s[12:13], 11
	v_and_or_b32 v8, v23, s18, v19
	v_and_or_b32 v10, v24, s18, v19
	v_and_or_b32 v9, v25, s18, v19
	v_add_u32_e32 v149, 0, v11
	v_lshl_add_u64 v[4:5], v[2:3], 0, s[4:5]
	v_lshl_add_u64 v[0:1], v[0:1], 0, s[16:17]
	v_lshl_or_b32 v8, v8, 10, v12
	v_lshl_or_b32 v10, v10, 10, v12
	v_lshl_or_b32 v12, v9, 10, v12
	v_add_u32_e32 v9, 0x8000, v149
	v_lshlrev_b64 v[14:15], 1, v[128:129]
	v_readfirstlane_b32 s15, v149
	v_lshl_add_u64 v[6:7], v[0:1], 0, s[6:7]
	v_add_co_u32_e32 v16, vcc, v4, v14
	v_addc_co_u32_e32 v17, vcc, v5, v15, vcc
	s_mov_b32 m0, s15
	v_readfirstlane_b32 s15, v9
	v_mov_b32_e32 v9, v129
	v_add_u32_e32 v11, 0x2000, v149
	global_load_lds_dwordx4 v[16:17], off
	v_add_co_u32_e32 v14, vcc, v6, v14
	v_addc_co_u32_e32 v15, vcc, v7, v15, vcc
	s_mov_b32 m0, s15
	v_lshlrev_b64 v[8:9], 1, v[8:9]
	v_readfirstlane_b32 s15, v11
	v_add_u32_e32 v11, 0xa000, v149
	global_load_lds_dwordx4 v[14:15], off
	v_add_co_u32_e32 v14, vcc, v4, v8
	v_addc_co_u32_e32 v15, vcc, v5, v9, vcc
	s_mov_b32 m0, s15
	v_readfirstlane_b32 s15, v11
	global_load_lds_dwordx4 v[14:15], off
	v_add_co_u32_e32 v8, vcc, v6, v8
	v_addc_co_u32_e32 v9, vcc, v7, v9, vcc
	s_mov_b32 m0, s15
	v_mov_b32_e32 v11, v129
	v_add_u32_e32 v13, 0x4000, v149
	global_load_lds_dwordx4 v[8:9], off
	v_lshlrev_b64 v[8:9], 1, v[10:11]
	v_readfirstlane_b32 s15, v13
	v_add_co_u32_e32 v10, vcc, v4, v8
	v_addc_co_u32_e32 v11, vcc, v5, v9, vcc
	s_mov_b32 m0, s15
	v_add_co_u32_e32 v8, vcc, v6, v8
	v_addc_co_u32_e32 v9, vcc, v7, v9, vcc
	global_load_lds_dwordx4 v[10:11], off
	v_add_u32_e32 v10, 0xc000, v149
	v_mov_b32_e32 v13, v129
	v_readfirstlane_b32 s15, v10
	s_mov_b32 m0, s15
	v_add_u32_e32 v10, 0x6000, v149
	global_load_lds_dwordx4 v[8:9], off
	v_lshlrev_b64 v[8:9], 1, v[12:13]
	v_readfirstlane_b32 s15, v10
	v_add_co_u32_e32 v4, vcc, v4, v8
	v_addc_co_u32_e32 v5, vcc, v5, v9, vcc
	s_mov_b32 m0, s15
	v_and_b32_e32 v26, 15, v18
	global_load_lds_dwordx4 v[4:5], off
	v_add_co_u32_e32 v4, vcc, v6, v8
	v_addc_co_u32_e32 v5, vcc, v7, v9, vcc
	v_add_u32_e32 v6, 0xe000, v149
	v_lshlrev_b32_e32 v10, 10, v19
	v_readfirstlane_b32 s15, v6
	s_mov_b32 m0, s15
	v_lshlrev_b32_e32 v6, 2, v18
	global_load_lds_dwordx4 v[4:5], off
	v_and_b32_e32 v4, 48, v18
	v_lshlrev_b32_e32 v5, 6, v26
	v_and_b32_e32 v6, 32, v6
	v_bitop3_b32 v150, v5, v6, v4 bitop3:0x36
	v_lshlrev_b32_e32 v5, 7, v18
	v_and_b32_e32 v151, 0x6000, v5
	v_lshlrev_b32_e32 v5, 6, v18
	v_and_b32_e32 v152, 0xffffc000, v5
	v_and_b32_e32 v5, 0x3c0, v5
	v_bitop3_b32 v154, v5, v6, v4 bitop3:0x36
	v_lshlrev_b32_e32 v4, 10, v25
	v_and_or_b32 v4, v4, s19, v21
	v_lshlrev_b32_e32 v6, 10, v24
	v_or3_b32 v128, v4, v10, v20
	v_and_or_b32 v6, v6, s19, v21
	v_lshlrev_b32_e32 v8, 10, v23
	v_lshlrev_b64 v[4:5], 1, v[128:129]
	v_or3_b32 v128, v6, v10, v20
	v_and_or_b32 v8, v8, s19, v21
	v_lshlrev_b32_e32 v11, 10, v22
	v_lshlrev_b64 v[6:7], 1, v[128:129]
	v_or3_b32 v128, v8, v10, v20
	v_and_or_b32 v11, v11, s19, v21
	v_lshlrev_b64 v[8:9], 1, v[128:129]
	v_or3_b32 v128, v11, v10, v20
	s_nop 0
	v_lshl_add_u64 v[0:1], v[0:1], 0, s[8:9]
	v_lshlrev_b64 v[10:11], 1, v[128:129]
	v_add_co_u32_e32 v130, vcc, v0, v4
	v_addc_co_u32_e32 v131, vcc, v1, v5, vcc
	v_add_co_u32_e32 v134, vcc, v0, v6
	v_addc_co_u32_e32 v135, vcc, v1, v7, vcc
	v_add_co_u32_e32 v136, vcc, v0, v8
	v_addc_co_u32_e32 v137, vcc, v1, v9, vcc
	v_add_co_u32_e32 v138, vcc, v0, v10
	v_addc_co_u32_e32 v139, vcc, v1, v11, vcc
	v_lshl_add_u64 v[0:1], v[2:3], 0, s[10:11]
	v_or_b32_e32 v153, 0x800, v152
	v_or_b32_e32 v155, 0x1000, v152
	v_or_b32_e32 v156, 0x1800, v152
	v_or_b32_e32 v157, 0x2000, v152
	v_or_b32_e32 v158, 0x2800, v152
	v_or_b32_e32 v159, 0x3000, v152
	v_or_b32_e32 v160, 0x3800, v152
	v_add_co_u32_e32 v140, vcc, v0, v4
	v_addc_co_u32_e32 v141, vcc, v1, v5, vcc
	v_add_co_u32_e32 v142, vcc, v0, v6
	v_addc_co_u32_e32 v143, vcc, v1, v7, vcc
	v_add_co_u32_e32 v144, vcc, v0, v8
	v_addc_co_u32_e32 v145, vcc, v1, v9, vcc
	v_add_co_u32_e32 v146, vcc, v0, v10
	v_addc_co_u32_e32 v147, vcc, v1, v11, vcc
	s_mov_b64 s[16:17], 0
	s_mov_b32 s15, 0
	s_waitcnt vmcnt(0) lgkmcnt(0)
	s_barrier
	v_readfirstlane_b32 s100, v149
	s_and_b32 s29, s15, 0x10000
	s_xor_b32 s30, s29, 0x10000
	s_add_i32 s29, s29, 0
	v_add3_u32 v128, s29, v150, v151
	v_add3_u32 v161, s29, v150, v152
	v_add3_u32 v194, s29, v154, v153
	v_add3_u32 v195, s29, v154, v155
	v_add3_u32 v196, s29, v154, v156
	v_add3_u32 v197, s29, v154, v157
	v_add3_u32 v198, s29, v154, v158
	v_add3_u32 v199, s29, v154, v159
	v_add3_u32 v200, s29, v154, v160
	ds_read_b128 v[178:181], v128 offset:32768
	ds_read_b128 v[162:165], v161
	ds_read_b128 v[166:169], v194
	ds_read_b128 v[170:173], v195
	ds_read_b128 v[174:177], v196
	ds_read_b128 v[182:185], v128 offset:34816
	ds_read_b128 v[186:189], v128 offset:36864
	ds_read_b128 v[190:193], v128 offset:38912
	s_add_i32 s101, s100, s30
	v_readfirstlane_b32 s98, v146
	v_readfirstlane_b32 s99, v147
	v_readfirstlane_b32 vcc_lo, v138
	v_readfirstlane_b32 vcc_hi, v139
	s_sub_u32 s98, s98, 0x1000000
	s_subb_u32 s99, s99, 0
	s_sub_u32 vcc_lo, vcc_lo, 0x1000000
	s_subb_u32 vcc_hi, vcc_hi, 0
	v_subrev_u32_e32 v146, s98, v146
	v_subrev_u32_e32 v138, vcc_lo, v138
	v_subrev_u32_e32 v144, s98, v144
	v_subrev_u32_e32 v136, vcc_lo, v136
	v_subrev_u32_e32 v142, s98, v142
	v_subrev_u32_e32 v134, vcc_lo, v134
	v_subrev_u32_e32 v140, s98, v140
	v_subrev_u32_e32 v130, vcc_lo, v130
	s_mov_b32 m0, s101
	s_nop 0
	global_load_lds_dwordx4 v146, s[98:99]
	s_add_i32 m0, s101, 0x8000
	s_nop 0
	global_load_lds_dwordx4 v138, vcc
	s_add_i32 m0, s101, 0x2000
	s_nop 0
	global_load_lds_dwordx4 v144, s[98:99]
	s_add_i32 m0, s101, 0xa000
	s_nop 0
	global_load_lds_dwordx4 v136, vcc
	s_add_i32 m0, s101, 0x4000
	s_nop 0
	global_load_lds_dwordx4 v142, s[98:99]
	s_add_i32 m0, s101, 0xc000
	s_nop 0
	global_load_lds_dwordx4 v134, vcc
	s_add_i32 m0, s101, 0x6000
	s_nop 0
	global_load_lds_dwordx4 v140, s[98:99]
	s_add_i32 m0, s101, 0xe000
	s_nop 0
	global_load_lds_dwordx4 v130, vcc

.LBB0_941:
	s_mul_hi_i32 s14, s39, 0x2aaaaaab
	s_lshr_b32 s15, s14, 31
	s_ashr_i32 s14, s14, 5
	s_add_i32 s15, s14, s15
	s_mul_i32 s14, s15, 0xc0
	s_sub_i32 s16, s39, s14
	s_sext_i32_i16 s14, s16
	s_bfe_u32 s14, s14, 0x4001b
	s_add_i32 s14, s16, s14
	s_sext_i32_i16 s17, s14
	s_and_b32 s14, s14, 0xfff0
	s_sub_i32 s14, s16, s14
	s_sext_i32_i16 s19, s14
	s_lshl_b32 s14, s17, 4
	s_and_b32 s14, s14, 0xffffff00
	v_mov_b32_e32 v148, v132
	v_mov_b32_e32 v18, v132
	s_add_i32 s17, s14, 0x500
	ds_read_b64 v[0:1], v133
	s_cmpk_lt_i32 s16, 0x60
	v_lshlrev_b32_e32 v9, 4, v18
	v_and_b32_e32 v8, 32, v18
	v_lshrrev_b32_e32 v10, 1, v18
	v_bitop3_b32 v8, v9, v8, 48 bitop3:0x6c
	s_cselect_b32 s18, s14, s17
	s_lshl_b32 s15, s15, 12
	s_lshl_b32 s16, s19, 8
	v_bfe_u32 v19, v18, 2, 4
	v_and_b32_e32 v20, 32, v10
	v_lshrrev_b32_e32 v21, 1, v8
	v_ashrrev_i32_e32 v22, 3, v18
	s_add_i32 s16, s16, s15
	v_or_b32_e32 v12, v21, v20
	v_and_or_b32 v8, v22, s20, v19
	s_ashr_i32 s17, s16, 31
	v_and_b32_e32 v11, 0xfffffc00, v9
	v_lshl_or_b32 v128, v8, 10, v12
	v_add_u32_e32 v8, 0x2000, v9
	v_add_u32_e32 v10, 0x4000, v9
	v_add_u32_e32 v9, 0x6000, v9
	s_lshl_b64 s[42:43], s[16:17], 11
	s_ashr_i32 s19, s18, 31
	v_ashrrev_i32_e32 v23, 7, v8
	v_ashrrev_i32_e32 v24, 7, v10
	v_ashrrev_i32_e32 v25, 7, v9
	s_waitcnt lgkmcnt(0)
	v_lshl_add_u64 v[2:3], v[0:1], 0, s[42:43]
	s_lshl_b64 s[18:19], s[18:19], 11
	v_and_or_b32 v8, v23, s20, v19
	v_and_or_b32 v10, v24, s20, v19
	v_and_or_b32 v9, v25, s20, v19
	v_add_u32_e32 v149, 0, v11
	v_lshl_add_u64 v[4:5], v[2:3], 0, s[4:5]
	v_lshl_add_u64 v[0:1], v[0:1], 0, s[18:19]
	v_lshl_or_b32 v8, v8, 10, v12
	v_lshl_or_b32 v10, v10, 10, v12
	v_lshl_or_b32 v12, v9, 10, v12
	v_add_u32_e32 v9, 0x8000, v149
	v_lshlrev_b64 v[14:15], 1, v[128:129]
	v_readfirstlane_b32 s15, v149
	v_lshl_add_u64 v[6:7], v[0:1], 0, s[6:7]
	v_add_co_u32_e32 v16, vcc, v4, v14
	v_addc_co_u32_e32 v17, vcc, v5, v15, vcc
	s_mov_b32 m0, s15
	v_readfirstlane_b32 s15, v9
	v_mov_b32_e32 v9, v129
	v_add_u32_e32 v11, 0x2000, v149
	s_cmp_lg_u32 s101, 0
	s_cbranch_scc1 .Lnxh_942_7
	global_load_lds_dwordx4 v[16:17], off
.Lnxh_942_7:
	v_add_co_u32_e32 v14, vcc, v6, v14
	v_addc_co_u32_e32 v15, vcc, v7, v15, vcc
	s_mov_b32 m0, s15
	v_lshlrev_b64 v[8:9], 1, v[8:9]
	v_readfirstlane_b32 s15, v11
	v_add_u32_e32 v11, 0xa000, v149
	s_cmp_lg_u32 s101, 0
	s_cbranch_scc1 .Lnxh_942_6
	global_load_lds_dwordx4 v[14:15], off
.Lnxh_942_6:
	v_add_co_u32_e32 v14, vcc, v4, v8
	v_addc_co_u32_e32 v15, vcc, v5, v9, vcc
	s_mov_b32 m0, s15
	v_readfirstlane_b32 s15, v11
	s_cmp_lg_u32 s101, 0
	s_cbranch_scc1 .Lnxh_942_5
	global_load_lds_dwordx4 v[14:15], off
.Lnxh_942_5:
	v_add_co_u32_e32 v8, vcc, v6, v8
	v_addc_co_u32_e32 v9, vcc, v7, v9, vcc
	s_mov_b32 m0, s15
	v_mov_b32_e32 v11, v129
	v_add_u32_e32 v13, 0x4000, v149
	s_cmp_lg_u32 s101, 0
	s_cbranch_scc1 .Lnxh_942_4
	global_load_lds_dwordx4 v[8:9], off
.Lnxh_942_4:
	v_lshlrev_b64 v[8:9], 1, v[10:11]
	v_readfirstlane_b32 s15, v13
	v_add_co_u32_e32 v10, vcc, v4, v8
	v_addc_co_u32_e32 v11, vcc, v5, v9, vcc
	s_mov_b32 m0, s15
	v_add_co_u32_e32 v8, vcc, v6, v8
	v_addc_co_u32_e32 v9, vcc, v7, v9, vcc
	s_cmp_lg_u32 s101, 0
	s_cbranch_scc1 .Lnxh_942_3
	global_load_lds_dwordx4 v[10:11], off

.Lnxh_942_2:
	v_lshlrev_b64 v[8:9], 1, v[12:13]
	v_readfirstlane_b32 s15, v10
	v_add_co_u32_e32 v4, vcc, v4, v8
	v_addc_co_u32_e32 v5, vcc, v5, v9, vcc
	s_mov_b32 m0, s15
	v_and_b32_e32 v26, 15, v18
	s_cmp_lg_u32 s101, 0
	s_cbranch_scc1 .Lnxh_942_1
	global_load_lds_dwordx4 v[4:5], off
.Lnxh_942_1:
	v_add_co_u32_e32 v4, vcc, v6, v8
	v_addc_co_u32_e32 v5, vcc, v7, v9, vcc
	v_add_u32_e32 v6, 0xe000, v149
	v_lshlrev_b32_e32 v10, 10, v19
	v_readfirstlane_b32 s15, v6
	s_mov_b32 m0, s15
	v_lshlrev_b32_e32 v6, 2, v18
	s_cmp_lg_u32 s101, 0
	s_cbranch_scc1 .Lnxh_942_0
	global_load_lds_dwordx4 v[4:5], off
.Lnxh_942_0:
	v_and_b32_e32 v4, 48, v18
	v_lshlrev_b32_e32 v5, 6, v26
	v_and_b32_e32 v6, 32, v6
	v_bitop3_b32 v150, v5, v6, v4 bitop3:0x36
	v_lshlrev_b32_e32 v5, 7, v18
	v_and_b32_e32 v151, 0x6000, v5
	v_lshlrev_b32_e32 v5, 6, v18
	v_and_b32_e32 v152, 0xffffc000, v5
	v_and_b32_e32 v5, 0x3c0, v5
	v_bitop3_b32 v154, v5, v6, v4 bitop3:0x36
	v_lshlrev_b32_e32 v4, 10, v25
	v_and_or_b32 v4, v4, s22, v21
	v_lshlrev_b32_e32 v6, 10, v24
	v_or3_b32 v128, v4, v10, v20
	v_and_or_b32 v6, v6, s22, v21
	v_lshlrev_b32_e32 v8, 10, v23
	v_lshlrev_b64 v[4:5], 1, v[128:129]
	v_or3_b32 v128, v6, v10, v20
	v_and_or_b32 v8, v8, s22, v21
	v_lshlrev_b32_e32 v11, 10, v22
	v_lshlrev_b64 v[6:7], 1, v[128:129]
	v_or3_b32 v128, v8, v10, v20
	v_and_or_b32 v11, v11, s22, v21
	v_lshlrev_b64 v[8:9], 1, v[128:129]
	v_or3_b32 v128, v11, v10, v20
	s_nop 0
	v_lshl_add_u64 v[0:1], v[0:1], 0, s[8:9]
	v_lshlrev_b64 v[10:11], 1, v[128:129]
	v_add_co_u32_e32 v130, vcc, v0, v4
	v_addc_co_u32_e32 v131, vcc, v1, v5, vcc
	v_add_co_u32_e32 v134, vcc, v0, v6
	v_addc_co_u32_e32 v135, vcc, v1, v7, vcc
	v_add_co_u32_e32 v136, vcc, v0, v8
	v_addc_co_u32_e32 v137, vcc, v1, v9, vcc
	v_add_co_u32_e32 v138, vcc, v0, v10
	v_addc_co_u32_e32 v139, vcc, v1, v11, vcc
	v_lshl_add_u64 v[0:1], v[2:3], 0, s[10:11]
	v_or_b32_e32 v153, 0x800, v152
	v_or_b32_e32 v155, 0x1000, v152
	v_or_b32_e32 v156, 0x1800, v152
	v_or_b32_e32 v157, 0x2000, v152
	v_or_b32_e32 v158, 0x2800, v152
	v_or_b32_e32 v159, 0x3000, v152
	v_or_b32_e32 v160, 0x3800, v152
	v_add_co_u32_e32 v140, vcc, v0, v4
	v_addc_co_u32_e32 v141, vcc, v1, v5, vcc
	v_add_co_u32_e32 v142, vcc, v0, v6
	v_addc_co_u32_e32 v143, vcc, v1, v7, vcc
	v_add_co_u32_e32 v144, vcc, v0, v8
	v_addc_co_u32_e32 v145, vcc, v1, v9, vcc
	v_add_co_u32_e32 v146, vcc, v0, v10
	v_addc_co_u32_e32 v147, vcc, v1, v11, vcc
	s_mov_b64 s[18:19], 0
	s_mov_b32 s15, 0
	s_cmp_lg_u32 s101, 0
	s_cbranch_scc1 .Lnxw_942
	s_waitcnt vmcnt(0)

.LBB0_1039:
	s_mul_hi_i32 s14, s42, 0x66666667
	s_lshr_b32 s15, s14, 31
	s_ashr_i32 s14, s14, 6
	s_add_i32 s15, s14, s15
	s_mul_i32 s14, s15, 0xa0
	s_sub_i32 s16, s42, s14
	s_sext_i32_i16 s14, s16
	s_bfe_u32 s14, s14, 0x4001b
	s_add_i32 s14, s16, s14
	s_sext_i32_i16 s17, s14
	s_and_b32 s14, s14, 0xfff0
	s_sub_i32 s14, s16, s14
	s_sext_i32_i16 s19, s14
	s_lshl_b32 s14, s17, 4
	s_and_b32 s14, s14, 0xffffff00
	v_mov_b32_e32 v148, v132
	v_mov_b32_e32 v18, v132
	s_cmpk_lt_i32 s16, 0x50
	ds_read_b64 v[0:1], v133
	s_cselect_b32 s16, s3, 0xc00
	v_lshlrev_b32_e32 v9, 4, v18
	v_and_b32_e32 v8, 32, v18
	v_lshrrev_b32_e32 v10, 1, v18
	v_bitop3_b32 v8, v9, v8, 48 bitop3:0x6c
	s_add_i32 s18, s14, s16
	s_lshl_b32 s15, s15, 12
	s_lshl_b32 s16, s19, 8
	v_bfe_u32 v19, v18, 2, 4
	v_and_b32_e32 v20, 32, v10
	v_lshrrev_b32_e32 v21, 1, v8
	v_ashrrev_i32_e32 v22, 3, v18
	s_add_i32 s16, s16, s15
	v_or_b32_e32 v12, v21, v20
	v_and_or_b32 v8, v22, s21, v19
	s_ashr_i32 s17, s16, 31
	v_and_b32_e32 v11, 0xfffffc00, v9
	v_lshl_or_b32 v128, v8, 10, v12
	v_add_u32_e32 v8, 0x2000, v9
	v_add_u32_e32 v10, 0x4000, v9
	v_add_u32_e32 v9, 0x6000, v9
	s_lshl_b64 s[44:45], s[16:17], 11
	s_ashr_i32 s19, s18, 31
	v_ashrrev_i32_e32 v23, 7, v8
	v_ashrrev_i32_e32 v24, 7, v10
	v_ashrrev_i32_e32 v25, 7, v9
	s_waitcnt lgkmcnt(0)
	v_lshl_add_u64 v[2:3], v[0:1], 0, s[44:45]
	s_lshl_b64 s[18:19], s[18:19], 11
	v_and_or_b32 v8, v23, s21, v19
	v_and_or_b32 v10, v24, s21, v19
	v_and_or_b32 v9, v25, s21, v19
	v_add_u32_e32 v149, 0, v11
	v_lshl_add_u64 v[4:5], v[2:3], 0, s[4:5]
	v_lshl_add_u64 v[0:1], v[0:1], 0, s[18:19]
	v_lshl_or_b32 v8, v8, 10, v12
	v_lshl_or_b32 v10, v10, 10, v12
	v_lshl_or_b32 v12, v9, 10, v12
	v_add_u32_e32 v9, 0x8000, v149
	v_lshlrev_b64 v[14:15], 1, v[128:129]
	v_readfirstlane_b32 s15, v149
	v_lshl_add_u64 v[6:7], v[0:1], 0, s[6:7]
	v_add_co_u32_e32 v16, vcc, v4, v14
	v_addc_co_u32_e32 v17, vcc, v5, v15, vcc
	s_mov_b32 m0, s15
	v_readfirstlane_b32 s15, v9
	v_mov_b32_e32 v9, v129
	v_add_u32_e32 v11, 0x2000, v149
	s_cmp_lg_u32 s101, 0
	s_cbranch_scc1 .Lnxh_1040_7
	global_load_lds_dwordx4 v[16:17], off

.Lnxh_1040_0:
	v_and_b32_e32 v4, 48, v18
	v_lshlrev_b32_e32 v5, 6, v26
	v_and_b32_e32 v6, 32, v6
	v_bitop3_b32 v150, v5, v6, v4 bitop3:0x36
	v_lshlrev_b32_e32 v5, 7, v18
	v_and_b32_e32 v151, 0x6000, v5
	v_lshlrev_b32_e32 v5, 6, v18
	v_and_b32_e32 v152, 0xffffc000, v5
	v_and_b32_e32 v5, 0x3c0, v5
	v_bitop3_b32 v154, v5, v6, v4 bitop3:0x36
	v_lshlrev_b32_e32 v4, 10, v25
	v_and_or_b32 v4, v4, s23, v21
	v_lshlrev_b32_e32 v6, 10, v24
	v_or3_b32 v128, v4, v10, v20
	v_and_or_b32 v6, v6, s23, v21
	v_lshlrev_b32_e32 v8, 10, v23
	v_lshlrev_b64 v[4:5], 1, v[128:129]
	v_or3_b32 v128, v6, v10, v20
	v_and_or_b32 v8, v8, s23, v21
	v_lshlrev_b32_e32 v11, 10, v22
	v_lshlrev_b64 v[6:7], 1, v[128:129]
	v_or3_b32 v128, v8, v10, v20
	v_and_or_b32 v11, v11, s23, v21
	v_lshlrev_b64 v[8:9], 1, v[128:129]
	v_or3_b32 v128, v11, v10, v20
	s_nop 0
	v_lshl_add_u64 v[0:1], v[0:1], 0, s[8:9]
	v_lshlrev_b64 v[10:11], 1, v[128:129]
	v_add_co_u32_e32 v130, vcc, v0, v4
	v_addc_co_u32_e32 v131, vcc, v1, v5, vcc
	v_add_co_u32_e32 v134, vcc, v0, v6
	v_addc_co_u32_e32 v135, vcc, v1, v7, vcc
	v_add_co_u32_e32 v136, vcc, v0, v8
	v_addc_co_u32_e32 v137, vcc, v1, v9, vcc
	v_add_co_u32_e32 v138, vcc, v0, v10
	v_addc_co_u32_e32 v139, vcc, v1, v11, vcc
	v_lshl_add_u64 v[0:1], v[2:3], 0, s[10:11]
	v_or_b32_e32 v153, 0x800, v152
	v_or_b32_e32 v155, 0x1000, v152
	v_or_b32_e32 v156, 0x1800, v152
	v_or_b32_e32 v157, 0x2000, v152
	v_or_b32_e32 v158, 0x2800, v152
	v_or_b32_e32 v159, 0x3000, v152
	v_or_b32_e32 v160, 0x3800, v152
	v_add_co_u32_e32 v140, vcc, v0, v4
	v_addc_co_u32_e32 v141, vcc, v1, v5, vcc
	v_add_co_u32_e32 v142, vcc, v0, v6
	v_addc_co_u32_e32 v143, vcc, v1, v7, vcc
	v_add_co_u32_e32 v144, vcc, v0, v8
	v_addc_co_u32_e32 v145, vcc, v1, v9, vcc
	v_add_co_u32_e32 v146, vcc, v0, v10
	v_addc_co_u32_e32 v147, vcc, v1, v11, vcc
	s_mov_b64 s[18:19], 0
	s_mov_b32 s15, 0
	s_cmp_lg_u32 s101, 0
	s_cbranch_scc1 .Lnxw_1040
	s_waitcnt vmcnt(0)

.LBB0_1137:
	s_ashr_i32 s10, s23, 31
	s_lshr_b32 s10, s10, 26
	s_add_i32 s10, s23, s10
	s_ashr_i32 s11, s10, 6
	s_and_b32 s10, s10, 0xffc0
	s_sub_i32 s10, s23, s10
	s_bfe_i32 s12, s10, 0x80000
	s_bfe_u32 s12, s12, 0x4000b
	v_mov_b32_e32 v148, v132
	v_mov_b32_e32 v18, v132
	s_add_i32 s12, s10, s12
	ds_read_b64 v[0:1], v133
	s_lshl_b32 s25, s11, 4
	v_lshlrev_b32_e32 v9, 4, v18
	v_and_b32_e32 v8, 32, v18
	s_and_b32 s11, s12, 0xf0
	v_bfe_u32 v19, v18, 2, 4
	v_lshrrev_b32_e32 v10, 1, v18
	v_bitop3_b32 v8, v9, v8, 48 bitop3:0x6c
	v_ashrrev_i32_e32 v22, 3, v18
	s_sub_i32 s10, s10, s11
	v_and_b32_e32 v20, 32, v10
	v_lshrrev_b32_e32 v21, 1, v8
	v_and_or_b32 v8, v22, s14, v19
	s_bfe_i32 s13, s12, 0x80000
	s_sext_i32_i8 s10, s10
	v_or_b32_e32 v12, v21, v20
	v_mul_u32_u24_e32 v8, 0xb00, v8
	s_sext_i32_i16 s13, s13
	s_add_i32 s25, s25, s10
	v_and_b32_e32 v11, 0xfffffc00, v9
	v_or_b32_e32 v128, v12, v8
	v_add_u32_e32 v8, 0x2000, v9
	v_add_u32_e32 v10, 0x4000, v9
	v_add_u32_e32 v9, 0x6000, v9
	s_ashr_i32 s26, s13, 4
	s_lshl_b32 s24, s25, 8
	v_ashrrev_i32_e32 v23, 7, v8
	v_ashrrev_i32_e32 v24, 7, v10
	v_ashrrev_i32_e32 v25, 7, v9
	s_lshl_b32 s10, s26, 8
	s_mul_i32 s12, s25, 0x160000
	s_mul_hi_i32 s13, s24, 0x1600
	v_and_or_b32 v8, v23, s14, v19
	v_and_or_b32 v10, v24, s14, v19
	v_and_or_b32 v9, v25, s14, v19
	s_waitcnt lgkmcnt(0)
	v_lshl_add_u64 v[2:3], v[0:1], 0, s[12:13]
	s_mul_i32 s12, s26, 0x160000
	s_mul_hi_i32 s13, s10, 0x1600
	v_mul_u32_u24_e32 v8, 0xb00, v8
	v_mul_u32_u24_e32 v10, 0xb00, v10
	v_mul_u32_u24_e32 v9, 0xb00, v9
	v_add_u32_e32 v149, 0, v11
	v_lshl_add_u64 v[4:5], v[2:3], 0, s[0:1]
	v_lshl_add_u64 v[0:1], v[0:1], 0, s[12:13]
	v_or_b32_e32 v8, v8, v12
	v_or_b32_e32 v10, v10, v12
	v_or_b32_e32 v12, v9, v12
	v_add_u32_e32 v9, 0x8000, v149
	v_lshlrev_b64 v[14:15], 1, v[128:129]
	v_readfirstlane_b32 s12, v149
	v_lshl_add_u64 v[6:7], v[0:1], 0, s[4:5]
	v_add_co_u32_e32 v16, vcc, v4, v14
	v_addc_co_u32_e32 v17, vcc, v5, v15, vcc
	s_mov_b32 m0, s12
	v_readfirstlane_b32 s12, v9
	v_mov_b32_e32 v9, v129
	v_add_u32_e32 v11, 0x2000, v149
	global_load_lds_dwordx4 v[16:17], off
	v_add_co_u32_e32 v14, vcc, v6, v14
	v_addc_co_u32_e32 v15, vcc, v7, v15, vcc
	s_mov_b32 m0, s12
	v_lshlrev_b64 v[8:9], 1, v[8:9]
	v_readfirstlane_b32 s12, v11
	v_add_u32_e32 v11, 0xa000, v149
	global_load_lds_dwordx4 v[14:15], off
	v_add_co_u32_e32 v14, vcc, v4, v8
	v_addc_co_u32_e32 v15, vcc, v5, v9, vcc
	s_mov_b32 m0, s12
	v_readfirstlane_b32 s12, v11
	global_load_lds_dwordx4 v[14:15], off
	v_add_co_u32_e32 v8, vcc, v6, v8
	v_addc_co_u32_e32 v9, vcc, v7, v9, vcc
	s_mov_b32 m0, s12
	v_mov_b32_e32 v11, v129
	v_add_u32_e32 v13, 0x4000, v149
	global_load_lds_dwordx4 v[8:9], off
	v_lshlrev_b64 v[8:9], 1, v[10:11]
	v_readfirstlane_b32 s12, v13
	v_add_co_u32_e32 v10, vcc, v4, v8
	v_addc_co_u32_e32 v11, vcc, v5, v9, vcc
	s_mov_b32 m0, s12
	v_add_co_u32_e32 v8, vcc, v6, v8
	v_addc_co_u32_e32 v9, vcc, v7, v9, vcc
	global_load_lds_dwordx4 v[10:11], off
	v_add_u32_e32 v10, 0xc000, v149
	v_mov_b32_e32 v13, v129
	v_readfirstlane_b32 s12, v10
	s_mov_b32 m0, s12
	v_add_u32_e32 v10, 0x6000, v149
	global_load_lds_dwordx4 v[8:9], off
	v_lshlrev_b64 v[8:9], 1, v[12:13]
	v_readfirstlane_b32 s12, v10
	v_add_co_u32_e32 v4, vcc, v4, v8
	v_addc_co_u32_e32 v5, vcc, v5, v9, vcc
	s_mov_b32 m0, s12
	v_and_b32_e32 v26, 15, v18
	global_load_lds_dwordx4 v[4:5], off
	v_add_co_u32_e32 v4, vcc, v6, v8
	v_addc_co_u32_e32 v5, vcc, v7, v9, vcc
	v_add_u32_e32 v6, 0xe000, v149
	v_lshrrev_b32_e32 v8, 4, v23
	v_readfirstlane_b32 s12, v6
	s_mov_b32 m0, s12
	v_lshlrev_b32_e32 v6, 2, v18
	global_load_lds_dwordx4 v[4:5], off
	v_and_b32_e32 v4, 48, v18
	v_lshlrev_b32_e32 v5, 6, v26
	v_and_b32_e32 v6, 32, v6
	v_bitop3_b32 v150, v5, v6, v4 bitop3:0x36
	v_lshlrev_b32_e32 v5, 7, v18
	v_and_b32_e32 v151, 0x6000, v5
	v_lshlrev_b32_e32 v5, 6, v18
	v_and_b32_e32 v152, 0xffffc000, v5
	v_and_b32_e32 v5, 0x3c0, v5
	v_bitop3_b32 v154, v5, v6, v4 bitop3:0x36
	v_lshrrev_b32_e32 v4, 4, v25
	v_mul_lo_u32 v4, v4, s16
	v_lshrrev_b32_e32 v6, 4, v24
	v_or_b32_e32 v4, v21, v4
	v_mul_lo_u32 v6, v6, s16
	v_mad_u32_u24 v4, v19, s15, v4
	v_or_b32_e32 v6, v21, v6
	v_mul_lo_u32 v8, v8, s16
	v_lshrrev_b32_e32 v10, 4, v22
	v_or_b32_e32 v128, v4, v20
	v_mad_u32_u24 v6, v19, s15, v6
	v_or_b32_e32 v8, v21, v8
	v_mul_lo_u32 v10, v10, s16
	v_lshlrev_b64 v[4:5], 1, v[128:129]
	v_or_b32_e32 v128, v6, v20
	v_mad_u32_u24 v8, v19, s15, v8
	v_or_b32_e32 v10, v21, v10
	v_lshlrev_b64 v[6:7], 1, v[128:129]
	v_or_b32_e32 v128, v8, v20
	v_mad_u32_u24 v10, v19, s15, v10
	v_lshlrev_b64 v[8:9], 1, v[128:129]
	v_or_b32_e32 v128, v10, v20
	s_nop 0
	v_lshl_add_u64 v[0:1], v[0:1], 0, s[6:7]
	v_lshlrev_b64 v[10:11], 1, v[128:129]
	v_add_co_u32_e32 v130, vcc, v0, v4
	v_addc_co_u32_e32 v131, vcc, v1, v5, vcc
	v_add_co_u32_e32 v134, vcc, v0, v6
	v_addc_co_u32_e32 v135, vcc, v1, v7, vcc
	v_add_co_u32_e32 v136, vcc, v0, v8
	v_addc_co_u32_e32 v137, vcc, v1, v9, vcc
	v_add_co_u32_e32 v138, vcc, v0, v10
	v_addc_co_u32_e32 v139, vcc, v1, v11, vcc
	v_lshl_add_u64 v[0:1], v[2:3], 0, s[8:9]
	s_ashr_i32 s11, s10, 31
	v_or_b32_e32 v153, 0x800, v152
	v_or_b32_e32 v155, 0x1000, v152
	v_or_b32_e32 v156, 0x1800, v152
	v_or_b32_e32 v157, 0x2000, v152
	v_or_b32_e32 v158, 0x2800, v152
	v_or_b32_e32 v159, 0x3000, v152
	v_or_b32_e32 v160, 0x3800, v152
	v_add_co_u32_e32 v140, vcc, v0, v4
	v_addc_co_u32_e32 v141, vcc, v1, v5, vcc
	v_add_co_u32_e32 v142, vcc, v0, v6
	v_addc_co_u32_e32 v143, vcc, v1, v7, vcc
	v_add_co_u32_e32 v144, vcc, v0, v8
	v_addc_co_u32_e32 v145, vcc, v1, v9, vcc
	v_add_co_u32_e32 v146, vcc, v0, v10
	v_addc_co_u32_e32 v147, vcc, v1, v11, vcc
	s_mov_b64 s[12:13], 0
	s_mov_b32 s26, 0
	s_waitcnt vmcnt(0) lgkmcnt(0)
	s_barrier
	v_readfirstlane_b32 s100, v149
	s_and_b32 s27, s26, 0x10000
	s_xor_b32 s28, s27, 0x10000
	s_add_i32 s27, s27, 0
	v_add3_u32 v128, s27, v150, v151
	v_add3_u32 v161, s27, v150, v152
	v_add3_u32 v194, s27, v154, v153
	v_add3_u32 v195, s27, v154, v155
	v_add3_u32 v196, s27, v154, v156
	v_add3_u32 v197, s27, v154, v157
	v_add3_u32 v198, s27, v154, v158
	v_add3_u32 v199, s27, v154, v159
	v_add3_u32 v200, s27, v154, v160
	ds_read_b128 v[178:181], v128 offset:32768
	ds_read_b128 v[162:165], v161
	ds_read_b128 v[166:169], v194
	ds_read_b128 v[170:173], v195
	ds_read_b128 v[174:177], v196
	ds_read_b128 v[182:185], v128 offset:34816
	ds_read_b128 v[186:189], v128 offset:36864
	ds_read_b128 v[190:193], v128 offset:38912
	s_add_i32 s101, s100, s28
	v_readfirstlane_b32 s98, v146
	v_readfirstlane_b32 s99, v147
	v_readfirstlane_b32 vcc_lo, v138
	v_readfirstlane_b32 vcc_hi, v139
	s_sub_u32 s98, s98, 0x1000000
	s_subb_u32 s99, s99, 0
	s_sub_u32 vcc_lo, vcc_lo, 0x1000000
	s_subb_u32 vcc_hi, vcc_hi, 0
	v_subrev_u32_e32 v146, s98, v146
	v_subrev_u32_e32 v138, vcc_lo, v138
	v_subrev_u32_e32 v144, s98, v144
	v_subrev_u32_e32 v136, vcc_lo, v136
	v_subrev_u32_e32 v142, s98, v142
	v_subrev_u32_e32 v134, vcc_lo, v134
	v_subrev_u32_e32 v140, s98, v140
	v_subrev_u32_e32 v130, vcc_lo, v130
	s_mov_b32 m0, s101
	s_nop 0
	global_load_lds_dwordx4 v146, s[98:99]
	s_add_i32 m0, s101, 0x8000
	s_nop 0
	global_load_lds_dwordx4 v138, vcc
	s_add_i32 m0, s101, 0x2000
	s_nop 0
	global_load_lds_dwordx4 v144, s[98:99]
	s_add_i32 m0, s101, 0xa000
	s_nop 0
	global_load_lds_dwordx4 v136, vcc
	s_add_i32 m0, s101, 0x4000
	s_nop 0
	global_load_lds_dwordx4 v142, s[98:99]
	s_add_i32 m0, s101, 0xc000
	s_nop 0
	global_load_lds_dwordx4 v134, vcc
	s_add_i32 m0, s101, 0x6000
	s_nop 0
	global_load_lds_dwordx4 v140, s[98:99]
	s_add_i32 m0, s101, 0xe000
	s_nop 0
	global_load_lds_dwordx4 v130, vcc
